# v17 + stride-4 and unit-stride forward levels fully unrolled with strength-reduced addressing (immediate LDS offsets, no per-iteration address or loop-control code)
# speedup vs baseline: 1.0068x; 1.0013x over previous
; DI float2 twid(float r) { return float2{__builtin_amdgcn_cosf(r), -__builtin_amdgcn_sinf(r)}; }
; DI void bfly_fwd(float2 a0, float2 a1, float2 a2, float2 a3, float r, float2& o0, float2& o1, float2& o2, float2& o3) {
;   float2 t0 = {a0.x + a2.x, a0.y + a2.y}, t1 = {a0.x - a2.x, a0.y - a2.y}, t2 = {a1.x + a3.x, a1.y + a3.y}, t3 = {a1.x - a3.x, a1.y - a3.y};
;   float2 b0 = {t0.x + t2.x, t0.y + t2.y}, b2 = {t0.x - t2.x, t0.y - t2.y}, b1 = {t1.x + t3.y, t1.y - t3.x}, b3 = {t1.x - t3.y, t1.y + t3.x};
;   float2 w1 = twid(r), w2 = cmul(w1, w1), w3 = cmul(w2, w1);
;   o0 = b0; o1 = cmul(b1, w1); o2 = cmul(b2, w2); o3 = cmul(b3, w3);
; }
;   const int Q = 1 << lq; const float invM = 1.f / (float)(4 << lq);
;   for (int bb = tid; bb < NBT * (N / 4); bb += NTHR) { const int b = bb & (N / 4 - 1); float2* z = z0 + (bb / (N / 4)) * N; int j = b & (Q - 1), base = ((b >> lq) << (lq + 2)) + j; float2 o0, o1, o2, o3;
;     bfly_fwd(z[base], z[base + Q], z[base + 2 * Q], z[base + 3 * Q], (float)j * invM, o0, o1, o2, o3);
;     z[base] = o0; z[base + Q] = o1; z[base + 2 * Q] = o2; z[base + 3 * Q] = o3; }
;   __syncthreads();
; }
.LBB0_1496:
	v_ashrrev_i32_e32 v27, 31, v26
	v_lshrrev_b32_e32 v27, 21, v27
	v_add_lshl_u32 v27, v26, v27, 5
	v_and_b32_e32 v27, 0xffff0000, v27
	v_and_b32_e32 v28, 0x1ff0, v25
	v_add_u32_e32 v27, 16, v27
	v_lshlrev_b32_e32 v28, 3, v28
	v_lshlrev_b32_e32 v29, 3, v24
	v_add3_u32 v27, v27, v28, v29
	v_add_u32_e32 v241, v27, v236
	v_add_u32_e32 v242, v27, v237
	v_add_u32_e32 v243, v27, v238
	v_add_u32_e32 v244, v27, v239
	ds_read_b64 v[28:29], v241
	ds_read_b64 v[30:31], v242
	ds_read_b64 v[32:33], v243
	ds_read_b64 v[34:35], v244
	s_waitcnt lgkmcnt(0)
	v_pk_mul_f32 v[218:219], v[30:31], v[222:223] op_sel:[1,1] op_sel_hi:[1,0]
	v_pk_mul_f32 v[220:221], v[32:33], v[224:225] op_sel:[1,1] op_sel_hi:[1,0]
	v_pk_mul_f32 v[36:37], v[34:35], v[226:227] op_sel:[1,1] op_sel_hi:[1,0]
	v_pk_fma_f32 v[30:31], v[30:31], v[222:223], v[218:219] op_sel_hi:[0,1,1] neg_lo:[0,0,1]
	v_pk_fma_f32 v[32:33], v[32:33], v[224:225], v[220:221] op_sel_hi:[0,1,1] neg_lo:[0,0,1]
	v_pk_fma_f32 v[34:35], v[34:35], v[226:227], v[36:37] op_sel_hi:[0,1,1] neg_lo:[0,0,1]
	v_pk_add_f32 v[36:37], v[28:29], v[32:33]
	v_pk_add_f32 v[38:39], v[28:29], v[32:33] neg_lo:[0,1] neg_hi:[0,1]
	v_pk_add_f32 v[40:41], v[30:31], v[34:35]
	v_pk_add_f32 v[42:43], v[30:31], v[34:35] neg_lo:[0,1] neg_hi:[0,1]
	v_pk_add_f32 v[28:29], v[36:37], v[40:41]
	v_pk_add_f32 v[32:33], v[36:37], v[40:41] neg_lo:[0,1] neg_hi:[0,1]
	v_pk_add_f32 v[30:31], v[38:39], v[42:43] op_sel:[0,1] op_sel_hi:[1,0] neg_hi:[0,1]
	v_pk_add_f32 v[34:35], v[38:39], v[42:43] op_sel:[0,1] op_sel_hi:[1,0] neg_lo:[0,1]
	v_pk_mul_f32 v[218:219], v[28:29], v[228:229] op_sel:[1,1] op_sel_hi:[1,0]
	v_pk_mul_f32 v[220:221], v[32:33], v[232:233] op_sel:[1,1] op_sel_hi:[1,0]
	v_pk_mul_f32 v[36:37], v[30:31], v[230:231] op_sel:[1,1] op_sel_hi:[1,0]
	v_pk_mul_f32 v[40:41], v[34:35], v[234:235] op_sel:[1,1] op_sel_hi:[1,0]
	v_pk_fma_f32 v[28:29], v[28:29], v[228:229], v[218:219] op_sel_hi:[0,1,1] neg_lo:[0,0,1]
	v_pk_fma_f32 v[32:33], v[32:33], v[232:233], v[220:221] op_sel_hi:[0,1,1] neg_lo:[0,0,1]
	v_pk_fma_f32 v[30:31], v[30:31], v[230:231], v[36:37] op_sel_hi:[0,1,1] neg_lo:[0,0,1]
	v_pk_fma_f32 v[34:35], v[34:35], v[234:235], v[40:41] op_sel_hi:[0,1,1] neg_lo:[0,0,1]
	s_nop 0
	ds_write_b64 v241, v[28:29]
	ds_write_b64 v243, v[32:33]
	ds_write_b64 v242, v[30:31]
	ds_write_b64 v244, v[34:35]
	ds_read_b64 v[28:29], v241 offset:16384
	ds_read_b64 v[30:31], v242 offset:16384
	ds_read_b64 v[32:33], v243 offset:16384
	ds_read_b64 v[34:35], v244 offset:16384
	s_waitcnt lgkmcnt(0)
	v_pk_mul_f32 v[218:219], v[30:31], v[222:223] op_sel:[1,1] op_sel_hi:[1,0]
	v_pk_mul_f32 v[220:221], v[32:33], v[224:225] op_sel:[1,1] op_sel_hi:[1,0]
	v_pk_mul_f32 v[36:37], v[34:35], v[226:227] op_sel:[1,1] op_sel_hi:[1,0]
	v_pk_fma_f32 v[30:31], v[30:31], v[222:223], v[218:219] op_sel_hi:[0,1,1] neg_lo:[0,0,1]
	v_pk_fma_f32 v[32:33], v[32:33], v[224:225], v[220:221] op_sel_hi:[0,1,1] neg_lo:[0,0,1]
	v_pk_fma_f32 v[34:35], v[34:35], v[226:227], v[36:37] op_sel_hi:[0,1,1] neg_lo:[0,0,1]
	v_pk_add_f32 v[36:37], v[28:29], v[32:33]
	v_pk_add_f32 v[38:39], v[28:29], v[32:33] neg_lo:[0,1] neg_hi:[0,1]
	v_pk_add_f32 v[40:41], v[30:31], v[34:35]
	v_pk_add_f32 v[42:43], v[30:31], v[34:35] neg_lo:[0,1] neg_hi:[0,1]
	v_pk_add_f32 v[28:29], v[36:37], v[40:41]
	v_pk_add_f32 v[32:33], v[36:37], v[40:41] neg_lo:[0,1] neg_hi:[0,1]
	v_pk_add_f32 v[30:31], v[38:39], v[42:43] op_sel:[0,1] op_sel_hi:[1,0] neg_hi:[0,1]
	v_pk_add_f32 v[34:35], v[38:39], v[42:43] op_sel:[0,1] op_sel_hi:[1,0] neg_lo:[0,1]
	v_pk_mul_f32 v[218:219], v[28:29], v[228:229] op_sel:[1,1] op_sel_hi:[1,0]
	v_pk_mul_f32 v[220:221], v[32:33], v[232:233] op_sel:[1,1] op_sel_hi:[1,0]
	v_pk_mul_f32 v[36:37], v[30:31], v[230:231] op_sel:[1,1] op_sel_hi:[1,0]
	v_pk_mul_f32 v[40:41], v[34:35], v[234:235] op_sel:[1,1] op_sel_hi:[1,0]
	v_pk_fma_f32 v[28:29], v[28:29], v[228:229], v[218:219] op_sel_hi:[0,1,1] neg_lo:[0,0,1]
	v_pk_fma_f32 v[32:33], v[32:33], v[232:233], v[220:221] op_sel_hi:[0,1,1] neg_lo:[0,0,1]
	v_pk_fma_f32 v[30:31], v[30:31], v[230:231], v[36:37] op_sel_hi:[0,1,1] neg_lo:[0,0,1]
	v_pk_fma_f32 v[34:35], v[34:35], v[234:235], v[40:41] op_sel_hi:[0,1,1] neg_lo:[0,0,1]
	s_nop 0
	ds_write_b64 v241, v[28:29] offset:16384
	ds_write_b64 v243, v[32:33] offset:16384
	ds_write_b64 v242, v[30:31] offset:16384
	ds_write_b64 v244, v[34:35] offset:16384
	ds_read_b64 v[28:29], v241 offset:32768
	ds_read_b64 v[30:31], v242 offset:32768
	ds_read_b64 v[32:33], v243 offset:32768
	ds_read_b64 v[34:35], v244 offset:32768
	s_waitcnt lgkmcnt(0)
; DI float2 twid(float r) { return float2{__builtin_amdgcn_cosf(r), -__builtin_amdgcn_sinf(r)}; }
; DI void bfly_fwd(float2 a0, float2 a1, float2 a2, float2 a3, float r, float2& o0, float2& o1, float2& o2, float2& o3) {
;   float2 t0 = {a0.x + a2.x, a0.y + a2.y}, t1 = {a0.x - a2.x, a0.y - a2.y}, t2 = {a1.x + a3.x, a1.y + a3.y}, t3 = {a1.x - a3.x, a1.y - a3.y};
;   float2 b0 = {t0.x + t2.x, t0.y + t2.y}, b2 = {t0.x - t2.x, t0.y - t2.y}, b1 = {t1.x + t3.y, t1.y - t3.x}, b3 = {t1.x - t3.y, t1.y + t3.x};
;   float2 w1 = twid(r), w2 = cmul(w1, w1), w3 = cmul(w2, w1);
;   o0 = b0; o1 = cmul(b1, w1); o2 = cmul(b2, w2); o3 = cmul(b3, w3);
; }
;   const int Q = 1 << lq; const float invM = 1.f / (float)(4 << lq);
;   for (int bb = tid; bb < NBT * (N / 4); bb += NTHR) { const int b = bb & (N / 4 - 1); float2* z = z0 + (bb / (N / 4)) * N; int j = b & (Q - 1), base = ((b >> lq) << (lq + 2)) + j; float2 o0, o1, o2, o3;
;     bfly_fwd(z[base], z[base + Q], z[base + 2 * Q], z[base + 3 * Q], (float)j * invM, o0, o1, o2, o3);
;     z[base] = o0; z[base + Q] = o1; z[base + 2 * Q] = o2; z[base + 3 * Q] = o3; }
;   __syncthreads();
; }
	v_pk_mul_f32 v[218:219], v[30:31], v[222:223] op_sel:[1,1] op_sel_hi:[1,0]
	v_pk_mul_f32 v[220:221], v[32:33], v[224:225] op_sel:[1,1] op_sel_hi:[1,0]
	v_pk_mul_f32 v[36:37], v[34:35], v[226:227] op_sel:[1,1] op_sel_hi:[1,0]
	v_pk_fma_f32 v[30:31], v[30:31], v[222:223], v[218:219] op_sel_hi:[0,1,1] neg_lo:[0,0,1]
	v_pk_fma_f32 v[32:33], v[32:33], v[224:225], v[220:221] op_sel_hi:[0,1,1] neg_lo:[0,0,1]
	v_pk_fma_f32 v[34:35], v[34:35], v[226:227], v[36:37] op_sel_hi:[0,1,1] neg_lo:[0,0,1]
	v_pk_add_f32 v[36:37], v[28:29], v[32:33]
	v_pk_add_f32 v[38:39], v[28:29], v[32:33] neg_lo:[0,1] neg_hi:[0,1]
	v_pk_add_f32 v[40:41], v[30:31], v[34:35]
	v_pk_add_f32 v[42:43], v[30:31], v[34:35] neg_lo:[0,1] neg_hi:[0,1]
	v_pk_add_f32 v[28:29], v[36:37], v[40:41]
	v_pk_add_f32 v[32:33], v[36:37], v[40:41] neg_lo:[0,1] neg_hi:[0,1]
	v_pk_add_f32 v[30:31], v[38:39], v[42:43] op_sel:[0,1] op_sel_hi:[1,0] neg_hi:[0,1]
	v_pk_add_f32 v[34:35], v[38:39], v[42:43] op_sel:[0,1] op_sel_hi:[1,0] neg_lo:[0,1]
	v_pk_mul_f32 v[218:219], v[28:29], v[228:229] op_sel:[1,1] op_sel_hi:[1,0]
	v_pk_mul_f32 v[220:221], v[32:33], v[232:233] op_sel:[1,1] op_sel_hi:[1,0]
	v_pk_mul_f32 v[36:37], v[30:31], v[230:231] op_sel:[1,1] op_sel_hi:[1,0]
	v_pk_mul_f32 v[40:41], v[34:35], v[234:235] op_sel:[1,1] op_sel_hi:[1,0]
	v_pk_fma_f32 v[28:29], v[28:29], v[228:229], v[218:219] op_sel_hi:[0,1,1] neg_lo:[0,0,1]
	v_pk_fma_f32 v[32:33], v[32:33], v[232:233], v[220:221] op_sel_hi:[0,1,1] neg_lo:[0,0,1]
	v_pk_fma_f32 v[30:31], v[30:31], v[230:231], v[36:37] op_sel_hi:[0,1,1] neg_lo:[0,0,1]
	v_pk_fma_f32 v[34:35], v[34:35], v[234:235], v[40:41] op_sel_hi:[0,1,1] neg_lo:[0,0,1]
	s_nop 0
	ds_write_b64 v241, v[28:29] offset:32768
	ds_write_b64 v243, v[32:33] offset:32768
	ds_write_b64 v242, v[30:31] offset:32768
	ds_write_b64 v244, v[34:35] offset:32768
	ds_read_b64 v[28:29], v241 offset:49152
	ds_read_b64 v[30:31], v242 offset:49152
	ds_read_b64 v[32:33], v243 offset:49152
	ds_read_b64 v[34:35], v244 offset:49152
	s_waitcnt lgkmcnt(0)
	v_pk_mul_f32 v[218:219], v[30:31], v[222:223] op_sel:[1,1] op_sel_hi:[1,0]
	v_pk_mul_f32 v[220:221], v[32:33], v[224:225] op_sel:[1,1] op_sel_hi:[1,0]
	v_pk_mul_f32 v[36:37], v[34:35], v[226:227] op_sel:[1,1] op_sel_hi:[1,0]
	v_pk_fma_f32 v[30:31], v[30:31], v[222:223], v[218:219] op_sel_hi:[0,1,1] neg_lo:[0,0,1]
	v_pk_fma_f32 v[32:33], v[32:33], v[224:225], v[220:221] op_sel_hi:[0,1,1] neg_lo:[0,0,1]
	v_pk_fma_f32 v[34:35], v[34:35], v[226:227], v[36:37] op_sel_hi:[0,1,1] neg_lo:[0,0,1]
	v_pk_add_f32 v[36:37], v[28:29], v[32:33]
	v_pk_add_f32 v[38:39], v[28:29], v[32:33] neg_lo:[0,1] neg_hi:[0,1]
	v_pk_add_f32 v[40:41], v[30:31], v[34:35]
	v_pk_add_f32 v[42:43], v[30:31], v[34:35] neg_lo:[0,1] neg_hi:[0,1]
	v_pk_add_f32 v[28:29], v[36:37], v[40:41]
	v_pk_add_f32 v[32:33], v[36:37], v[40:41] neg_lo:[0,1] neg_hi:[0,1]
	v_pk_add_f32 v[30:31], v[38:39], v[42:43] op_sel:[0,1] op_sel_hi:[1,0] neg_hi:[0,1]
	v_pk_add_f32 v[34:35], v[38:39], v[42:43] op_sel:[0,1] op_sel_hi:[1,0] neg_lo:[0,1]
	v_pk_mul_f32 v[218:219], v[28:29], v[228:229] op_sel:[1,1] op_sel_hi:[1,0]
	v_pk_mul_f32 v[220:221], v[32:33], v[232:233] op_sel:[1,1] op_sel_hi:[1,0]
	v_pk_mul_f32 v[36:37], v[30:31], v[230:231] op_sel:[1,1] op_sel_hi:[1,0]
	v_pk_mul_f32 v[40:41], v[34:35], v[234:235] op_sel:[1,1] op_sel_hi:[1,0]
	v_pk_fma_f32 v[28:29], v[28:29], v[228:229], v[218:219] op_sel_hi:[0,1,1] neg_lo:[0,0,1]
	v_pk_fma_f32 v[32:33], v[32:33], v[232:233], v[220:221] op_sel_hi:[0,1,1] neg_lo:[0,0,1]
	v_pk_fma_f32 v[30:31], v[30:31], v[230:231], v[36:37] op_sel_hi:[0,1,1] neg_lo:[0,0,1]
	v_pk_fma_f32 v[34:35], v[34:35], v[234:235], v[40:41] op_sel_hi:[0,1,1] neg_lo:[0,0,1]
	s_nop 0
	ds_write_b64 v241, v[28:29] offset:49152
	ds_write_b64 v243, v[32:33] offset:49152
	ds_write_b64 v242, v[30:31] offset:49152
	ds_write_b64 v244, v[34:35] offset:49152
	v_add_u32_e32 v25, 0x2000, v25
	v_add_u32_e32 v27, 0x800, v26
	v_mov_b32_e32 v26, v27
	s_mov_b64 s[10:11], exec

; DI float2 twid(float r) { return float2{__builtin_amdgcn_cosf(r), -__builtin_amdgcn_sinf(r)}; }
; DI void bfly_fwd(float2 a0, float2 a1, float2 a2, float2 a3, float r, float2& o0, float2& o1, float2& o2, float2& o3) {
;   float2 t0 = {a0.x + a2.x, a0.y + a2.y}, t1 = {a0.x - a2.x, a0.y - a2.y}, t2 = {a1.x + a3.x, a1.y + a3.y}, t3 = {a1.x - a3.x, a1.y - a3.y};
;   float2 b0 = {t0.x + t2.x, t0.y + t2.y}, b2 = {t0.x - t2.x, t0.y - t2.y}, b1 = {t1.x + t3.y, t1.y - t3.x}, b3 = {t1.x - t3.y, t1.y + t3.x};
;   float2 w1 = twid(r), w2 = cmul(w1, w1), w3 = cmul(w2, w1);
;   o0 = b0; o1 = cmul(b1, w1); o2 = cmul(b2, w2); o3 = cmul(b3, w3);
; }
;   const int Q = 1 << lq; const float invM = 1.f / (float)(4 << lq);
;   for (int bb = tid; bb < NBT * (N / 4); bb += NTHR) { const int b = bb & (N / 4 - 1); float2* z = z0 + (bb / (N / 4)) * N; int j = b & (Q - 1), base = ((b >> lq) << (lq + 2)) + j; float2 o0, o1, o2, o3;
;     bfly_fwd(z[base], z[base + Q], z[base + 2 * Q], z[base + 3 * Q], (float)j * invM, o0, o1, o2, o3);
;     z[base] = o0; z[base + Q] = o1; z[base + 2 * Q] = o2; z[base + 3 * Q] = o3; }
;   __syncthreads();
; }
.LBB0_1499:
	v_ashrrev_i32_e32 v13, 31, v12
	v_lshrrev_b32_e32 v13, 21, v13
	v_add_lshl_u32 v13, v12, v13, 5
	v_and_b32_e32 v14, 0x1ffc, v11
	v_and_b32_e32 v13, 0xffff0000, v13
	v_lshlrev_b32_e32 v14, 3, v14
	v_add3_u32 v13, 16, v13, v14
	ds_read_b128 v[14:17], v13
	ds_read_b128 v[18:21], v13 offset:16
	s_waitcnt lgkmcnt(0)
	v_pk_add_f32 v[22:23], v[14:15], v[18:19]
	v_pk_add_f32 v[26:27], v[16:17], v[20:21]
	v_pk_add_f32 v[24:25], v[14:15], v[18:19] neg_lo:[0,1] neg_hi:[0,1]
	v_pk_add_f32 v[28:29], v[16:17], v[20:21] neg_lo:[0,1] neg_hi:[0,1]
	v_pk_add_f32 v[14:15], v[22:23], v[26:27]
	v_pk_add_f32 v[18:19], v[22:23], v[26:27] neg_lo:[0,1] neg_hi:[0,1]
	v_pk_add_f32 v[16:17], v[24:25], v[28:29] op_sel:[0,1] op_sel_hi:[1,0] neg_hi:[0,1]
	v_pk_add_f32 v[20:21], v[24:25], v[28:29] op_sel:[0,1] op_sel_hi:[1,0] neg_lo:[0,1]
	s_nop 0
	ds_write_b128 v13, v[14:17]
	ds_write_b128 v13, v[18:21] offset:16
	ds_read_b128 v[14:17], v13 offset:16384
	ds_read_b128 v[18:21], v13 offset:16400
	s_waitcnt lgkmcnt(0)
	v_pk_add_f32 v[22:23], v[14:15], v[18:19]
	v_pk_add_f32 v[26:27], v[16:17], v[20:21]
	v_pk_add_f32 v[24:25], v[14:15], v[18:19] neg_lo:[0,1] neg_hi:[0,1]
	v_pk_add_f32 v[28:29], v[16:17], v[20:21] neg_lo:[0,1] neg_hi:[0,1]
	v_pk_add_f32 v[14:15], v[22:23], v[26:27]
	v_pk_add_f32 v[18:19], v[22:23], v[26:27] neg_lo:[0,1] neg_hi:[0,1]
	v_pk_add_f32 v[16:17], v[24:25], v[28:29] op_sel:[0,1] op_sel_hi:[1,0] neg_hi:[0,1]
	v_pk_add_f32 v[20:21], v[24:25], v[28:29] op_sel:[0,1] op_sel_hi:[1,0] neg_lo:[0,1]
	s_nop 0
	ds_write_b128 v13, v[14:17] offset:16384
	ds_write_b128 v13, v[18:21] offset:16400
	ds_read_b128 v[14:17], v13 offset:32768
	ds_read_b128 v[18:21], v13 offset:32784
	s_waitcnt lgkmcnt(0)
	v_pk_add_f32 v[22:23], v[14:15], v[18:19]
	v_pk_add_f32 v[26:27], v[16:17], v[20:21]
	v_pk_add_f32 v[24:25], v[14:15], v[18:19] neg_lo:[0,1] neg_hi:[0,1]
	v_pk_add_f32 v[28:29], v[16:17], v[20:21] neg_lo:[0,1] neg_hi:[0,1]
	v_pk_add_f32 v[14:15], v[22:23], v[26:27]
	v_pk_add_f32 v[18:19], v[22:23], v[26:27] neg_lo:[0,1] neg_hi:[0,1]
	v_pk_add_f32 v[16:17], v[24:25], v[28:29] op_sel:[0,1] op_sel_hi:[1,0] neg_hi:[0,1]
	v_pk_add_f32 v[20:21], v[24:25], v[28:29] op_sel:[0,1] op_sel_hi:[1,0] neg_lo:[0,1]
	s_nop 0
	ds_write_b128 v13, v[14:17] offset:32768
	ds_write_b128 v13, v[18:21] offset:32784
	ds_read_b128 v[14:17], v13 offset:49152
	ds_read_b128 v[18:21], v13 offset:49168
	s_waitcnt lgkmcnt(0)
	v_pk_add_f32 v[22:23], v[14:15], v[18:19]
	v_pk_add_f32 v[26:27], v[16:17], v[20:21]
	v_pk_add_f32 v[24:25], v[14:15], v[18:19] neg_lo:[0,1] neg_hi:[0,1]
	v_pk_add_f32 v[28:29], v[16:17], v[20:21] neg_lo:[0,1] neg_hi:[0,1]
	v_pk_add_f32 v[14:15], v[22:23], v[26:27]
	v_pk_add_f32 v[18:19], v[22:23], v[26:27] neg_lo:[0,1] neg_hi:[0,1]
	v_pk_add_f32 v[16:17], v[24:25], v[28:29] op_sel:[0,1] op_sel_hi:[1,0] neg_hi:[0,1]
	v_pk_add_f32 v[20:21], v[24:25], v[28:29] op_sel:[0,1] op_sel_hi:[1,0] neg_lo:[0,1]
	s_nop 0
	ds_write_b128 v13, v[14:17] offset:49152
	ds_write_b128 v13, v[18:21] offset:49168
	v_add_u32_e32 v11, 0x2000, v11
	v_add_u32_e32 v13, 0x800, v12
	v_mov_b32_e32 v12, v13
	s_mov_b64 s[8:9], exec

; DI float2 twid(float r) { return float2{__builtin_amdgcn_cosf(r), -__builtin_amdgcn_sinf(r)}; }
; DI void bfly_fwd(float2 a0, float2 a1, float2 a2, float2 a3, float r, float2& o0, float2& o1, float2& o2, float2& o3) {
;   float2 t0 = {a0.x + a2.x, a0.y + a2.y}, t1 = {a0.x - a2.x, a0.y - a2.y}, t2 = {a1.x + a3.x, a1.y + a3.y}, t3 = {a1.x - a3.x, a1.y - a3.y};
;   float2 b0 = {t0.x + t2.x, t0.y + t2.y}, b2 = {t0.x - t2.x, t0.y - t2.y}, b1 = {t1.x + t3.y, t1.y - t3.x}, b3 = {t1.x - t3.y, t1.y + t3.x};
;   float2 w1 = twid(r), w2 = cmul(w1, w1), w3 = cmul(w2, w1);
;   o0 = b0; o1 = cmul(b1, w1); o2 = cmul(b2, w2); o3 = cmul(b3, w3);
; }
;   const int Q = 1 << lq; const float invM = 1.f / (float)(4 << lq);
;   for (int bb = tid; bb < NBT * (N / 4); bb += NTHR) { const int b = bb & (N / 4 - 1); float2* z = z0 + (bb / (N / 4)) * N; int j = b & (Q - 1), base = ((b >> lq) << (lq + 2)) + j; float2 o0, o1, o2, o3;
;     bfly_fwd(z[base], z[base + Q], z[base + 2 * Q], z[base + 3 * Q], (float)j * invM, o0, o1, o2, o3);
;     z[base] = o0; z[base + Q] = o1; z[base + 2 * Q] = o2; z[base + 3 * Q] = o3; }
;   __syncthreads();
; }
.LBB0_1524:
	v_ashrrev_i32_e32 v27, 31, v26
	v_lshrrev_b32_e32 v27, 20, v27
	v_add_lshl_u32 v27, v26, v27, 5
	v_and_b32_e32 v27, 0xfffe0000, v27
	v_and_b32_e32 v28, 0x3ff0, v25
	v_add_u32_e32 v27, 16, v27
	v_lshlrev_b32_e32 v28, 3, v28
	v_lshlrev_b32_e32 v29, 3, v24
	v_add3_u32 v27, v27, v28, v29
	v_add_u32_e32 v241, v27, v236
	v_add_u32_e32 v242, v27, v237
	v_add_u32_e32 v243, v27, v238
	v_add_u32_e32 v244, v27, v239
	ds_read_b64 v[28:29], v241
	ds_read_b64 v[30:31], v242
	ds_read_b64 v[32:33], v243
	ds_read_b64 v[34:35], v244
	s_waitcnt lgkmcnt(0)
	v_pk_mul_f32 v[218:219], v[30:31], v[222:223] op_sel:[1,1] op_sel_hi:[1,0]
	v_pk_mul_f32 v[220:221], v[32:33], v[224:225] op_sel:[1,1] op_sel_hi:[1,0]
	v_pk_mul_f32 v[36:37], v[34:35], v[226:227] op_sel:[1,1] op_sel_hi:[1,0]
	v_pk_fma_f32 v[30:31], v[30:31], v[222:223], v[218:219] op_sel_hi:[0,1,1] neg_lo:[0,0,1]
	v_pk_fma_f32 v[32:33], v[32:33], v[224:225], v[220:221] op_sel_hi:[0,1,1] neg_lo:[0,0,1]
	v_pk_fma_f32 v[34:35], v[34:35], v[226:227], v[36:37] op_sel_hi:[0,1,1] neg_lo:[0,0,1]
	v_pk_add_f32 v[36:37], v[28:29], v[32:33]
	v_pk_add_f32 v[38:39], v[28:29], v[32:33] neg_lo:[0,1] neg_hi:[0,1]
	v_pk_add_f32 v[40:41], v[30:31], v[34:35]
	v_pk_add_f32 v[42:43], v[30:31], v[34:35] neg_lo:[0,1] neg_hi:[0,1]
	v_pk_add_f32 v[28:29], v[36:37], v[40:41]
	v_pk_add_f32 v[32:33], v[36:37], v[40:41] neg_lo:[0,1] neg_hi:[0,1]
	v_pk_add_f32 v[30:31], v[38:39], v[42:43] op_sel:[0,1] op_sel_hi:[1,0] neg_hi:[0,1]
	v_pk_add_f32 v[34:35], v[38:39], v[42:43] op_sel:[0,1] op_sel_hi:[1,0] neg_lo:[0,1]
	v_pk_mul_f32 v[218:219], v[28:29], v[228:229] op_sel:[1,1] op_sel_hi:[1,0]
	v_pk_mul_f32 v[220:221], v[32:33], v[232:233] op_sel:[1,1] op_sel_hi:[1,0]
	v_pk_mul_f32 v[36:37], v[30:31], v[230:231] op_sel:[1,1] op_sel_hi:[1,0]
	v_pk_mul_f32 v[40:41], v[34:35], v[234:235] op_sel:[1,1] op_sel_hi:[1,0]
	v_pk_fma_f32 v[28:29], v[28:29], v[228:229], v[218:219] op_sel_hi:[0,1,1] neg_lo:[0,0,1]
	v_pk_fma_f32 v[32:33], v[32:33], v[232:233], v[220:221] op_sel_hi:[0,1,1] neg_lo:[0,0,1]
	v_pk_fma_f32 v[30:31], v[30:31], v[230:231], v[36:37] op_sel_hi:[0,1,1] neg_lo:[0,0,1]
	v_pk_fma_f32 v[34:35], v[34:35], v[234:235], v[40:41] op_sel_hi:[0,1,1] neg_lo:[0,0,1]
	s_nop 0
	ds_write_b64 v241, v[28:29]
	ds_write_b64 v243, v[32:33]
	ds_write_b64 v242, v[30:31]
	ds_write_b64 v244, v[34:35]
	ds_read_b64 v[28:29], v241 offset:16384
	ds_read_b64 v[30:31], v242 offset:16384
	ds_read_b64 v[32:33], v243 offset:16384
	ds_read_b64 v[34:35], v244 offset:16384
	s_waitcnt lgkmcnt(0)
	v_pk_mul_f32 v[218:219], v[30:31], v[222:223] op_sel:[1,1] op_sel_hi:[1,0]
	v_pk_mul_f32 v[220:221], v[32:33], v[224:225] op_sel:[1,1] op_sel_hi:[1,0]
	v_pk_mul_f32 v[36:37], v[34:35], v[226:227] op_sel:[1,1] op_sel_hi:[1,0]
	v_pk_fma_f32 v[30:31], v[30:31], v[222:223], v[218:219] op_sel_hi:[0,1,1] neg_lo:[0,0,1]
	v_pk_fma_f32 v[32:33], v[32:33], v[224:225], v[220:221] op_sel_hi:[0,1,1] neg_lo:[0,0,1]
	v_pk_fma_f32 v[34:35], v[34:35], v[226:227], v[36:37] op_sel_hi:[0,1,1] neg_lo:[0,0,1]
	v_pk_add_f32 v[36:37], v[28:29], v[32:33]
	v_pk_add_f32 v[38:39], v[28:29], v[32:33] neg_lo:[0,1] neg_hi:[0,1]
	v_pk_add_f32 v[40:41], v[30:31], v[34:35]
	v_pk_add_f32 v[42:43], v[30:31], v[34:35] neg_lo:[0,1] neg_hi:[0,1]
	v_pk_add_f32 v[28:29], v[36:37], v[40:41]
	v_pk_add_f32 v[32:33], v[36:37], v[40:41] neg_lo:[0,1] neg_hi:[0,1]
	v_pk_add_f32 v[30:31], v[38:39], v[42:43] op_sel:[0,1] op_sel_hi:[1,0] neg_hi:[0,1]
	v_pk_add_f32 v[34:35], v[38:39], v[42:43] op_sel:[0,1] op_sel_hi:[1,0] neg_lo:[0,1]
	v_pk_mul_f32 v[218:219], v[28:29], v[228:229] op_sel:[1,1] op_sel_hi:[1,0]
	v_pk_mul_f32 v[220:221], v[32:33], v[232:233] op_sel:[1,1] op_sel_hi:[1,0]
	v_pk_mul_f32 v[36:37], v[30:31], v[230:231] op_sel:[1,1] op_sel_hi:[1,0]
	v_pk_mul_f32 v[40:41], v[34:35], v[234:235] op_sel:[1,1] op_sel_hi:[1,0]
	v_pk_fma_f32 v[28:29], v[28:29], v[228:229], v[218:219] op_sel_hi:[0,1,1] neg_lo:[0,0,1]
	v_pk_fma_f32 v[32:33], v[32:33], v[232:233], v[220:221] op_sel_hi:[0,1,1] neg_lo:[0,0,1]
	v_pk_fma_f32 v[30:31], v[30:31], v[230:231], v[36:37] op_sel_hi:[0,1,1] neg_lo:[0,0,1]
	v_pk_fma_f32 v[34:35], v[34:35], v[234:235], v[40:41] op_sel_hi:[0,1,1] neg_lo:[0,0,1]
	s_nop 0
	ds_write_b64 v241, v[28:29] offset:16384
	ds_write_b64 v243, v[32:33] offset:16384
	ds_write_b64 v242, v[30:31] offset:16384
	ds_write_b64 v244, v[34:35] offset:16384
	ds_read_b64 v[28:29], v241 offset:32768
	ds_read_b64 v[30:31], v242 offset:32768
	ds_read_b64 v[32:33], v243 offset:32768
	ds_read_b64 v[34:35], v244 offset:32768
	s_waitcnt lgkmcnt(0)
	v_pk_mul_f32 v[218:219], v[30:31], v[222:223] op_sel:[1,1] op_sel_hi:[1,0]
	v_pk_mul_f32 v[220:221], v[32:33], v[224:225] op_sel:[1,1] op_sel_hi:[1,0]
	v_pk_mul_f32 v[36:37], v[34:35], v[226:227] op_sel:[1,1] op_sel_hi:[1,0]
	v_pk_fma_f32 v[30:31], v[30:31], v[222:223], v[218:219] op_sel_hi:[0,1,1] neg_lo:[0,0,1]
	v_pk_fma_f32 v[32:33], v[32:33], v[224:225], v[220:221] op_sel_hi:[0,1,1] neg_lo:[0,0,1]
	v_pk_fma_f32 v[34:35], v[34:35], v[226:227], v[36:37] op_sel_hi:[0,1,1] neg_lo:[0,0,1]
	v_pk_add_f32 v[36:37], v[28:29], v[32:33]
	v_pk_add_f32 v[38:39], v[28:29], v[32:33] neg_lo:[0,1] neg_hi:[0,1]
	v_pk_add_f32 v[40:41], v[30:31], v[34:35]
	v_pk_add_f32 v[42:43], v[30:31], v[34:35] neg_lo:[0,1] neg_hi:[0,1]
	v_pk_add_f32 v[28:29], v[36:37], v[40:41]
	v_pk_add_f32 v[32:33], v[36:37], v[40:41] neg_lo:[0,1] neg_hi:[0,1]
	v_pk_add_f32 v[30:31], v[38:39], v[42:43] op_sel:[0,1] op_sel_hi:[1,0] neg_hi:[0,1]
	v_pk_add_f32 v[34:35], v[38:39], v[42:43] op_sel:[0,1] op_sel_hi:[1,0] neg_lo:[0,1]
	v_pk_mul_f32 v[218:219], v[28:29], v[228:229] op_sel:[1,1] op_sel_hi:[1,0]
	v_pk_mul_f32 v[220:221], v[32:33], v[232:233] op_sel:[1,1] op_sel_hi:[1,0]
	v_pk_mul_f32 v[36:37], v[30:31], v[230:231] op_sel:[1,1] op_sel_hi:[1,0]
	v_pk_mul_f32 v[40:41], v[34:35], v[234:235] op_sel:[1,1] op_sel_hi:[1,0]
	v_pk_fma_f32 v[28:29], v[28:29], v[228:229], v[218:219] op_sel_hi:[0,1,1] neg_lo:[0,0,1]
	v_pk_fma_f32 v[32:33], v[32:33], v[232:233], v[220:221] op_sel_hi:[0,1,1] neg_lo:[0,0,1]
	v_pk_fma_f32 v[30:31], v[30:31], v[230:231], v[36:37] op_sel_hi:[0,1,1] neg_lo:[0,0,1]
	v_pk_fma_f32 v[34:35], v[34:35], v[234:235], v[40:41] op_sel_hi:[0,1,1] neg_lo:[0,0,1]
	s_nop 0
	ds_write_b64 v241, v[28:29] offset:32768
	ds_write_b64 v243, v[32:33] offset:32768
	ds_write_b64 v242, v[30:31] offset:32768
	ds_write_b64 v244, v[34:35] offset:32768
	ds_read_b64 v[28:29], v241 offset:49152
	ds_read_b64 v[30:31], v242 offset:49152
	ds_read_b64 v[32:33], v243 offset:49152
	ds_read_b64 v[34:35], v244 offset:49152
	s_waitcnt lgkmcnt(0)
; DI float2 twid(float r) { return float2{__builtin_amdgcn_cosf(r), -__builtin_amdgcn_sinf(r)}; }
; DI void bfly_fwd(float2 a0, float2 a1, float2 a2, float2 a3, float r, float2& o0, float2& o1, float2& o2, float2& o3) {
;   float2 t0 = {a0.x + a2.x, a0.y + a2.y}, t1 = {a0.x - a2.x, a0.y - a2.y}, t2 = {a1.x + a3.x, a1.y + a3.y}, t3 = {a1.x - a3.x, a1.y - a3.y};
;   float2 b0 = {t0.x + t2.x, t0.y + t2.y}, b2 = {t0.x - t2.x, t0.y - t2.y}, b1 = {t1.x + t3.y, t1.y - t3.x}, b3 = {t1.x - t3.y, t1.y + t3.x};
;   float2 w1 = twid(r), w2 = cmul(w1, w1), w3 = cmul(w2, w1);
;   o0 = b0; o1 = cmul(b1, w1); o2 = cmul(b2, w2); o3 = cmul(b3, w3);
; }
;   const int Q = 1 << lq; const float invM = 1.f / (float)(4 << lq);
;   for (int bb = tid; bb < NBT * (N / 4); bb += NTHR) { const int b = bb & (N / 4 - 1); float2* z = z0 + (bb / (N / 4)) * N; int j = b & (Q - 1), base = ((b >> lq) << (lq + 2)) + j; float2 o0, o1, o2, o3;
;     bfly_fwd(z[base], z[base + Q], z[base + 2 * Q], z[base + 3 * Q], (float)j * invM, o0, o1, o2, o3);
;     z[base] = o0; z[base + Q] = o1; z[base + 2 * Q] = o2; z[base + 3 * Q] = o3; }
;   __syncthreads();
; }
	v_pk_mul_f32 v[218:219], v[30:31], v[222:223] op_sel:[1,1] op_sel_hi:[1,0]
	v_pk_mul_f32 v[220:221], v[32:33], v[224:225] op_sel:[1,1] op_sel_hi:[1,0]
	v_pk_mul_f32 v[36:37], v[34:35], v[226:227] op_sel:[1,1] op_sel_hi:[1,0]
	v_pk_fma_f32 v[30:31], v[30:31], v[222:223], v[218:219] op_sel_hi:[0,1,1] neg_lo:[0,0,1]
	v_pk_fma_f32 v[32:33], v[32:33], v[224:225], v[220:221] op_sel_hi:[0,1,1] neg_lo:[0,0,1]
	v_pk_fma_f32 v[34:35], v[34:35], v[226:227], v[36:37] op_sel_hi:[0,1,1] neg_lo:[0,0,1]
	v_pk_add_f32 v[36:37], v[28:29], v[32:33]
	v_pk_add_f32 v[38:39], v[28:29], v[32:33] neg_lo:[0,1] neg_hi:[0,1]
	v_pk_add_f32 v[40:41], v[30:31], v[34:35]
	v_pk_add_f32 v[42:43], v[30:31], v[34:35] neg_lo:[0,1] neg_hi:[0,1]
	v_pk_add_f32 v[28:29], v[36:37], v[40:41]
	v_pk_add_f32 v[32:33], v[36:37], v[40:41] neg_lo:[0,1] neg_hi:[0,1]
	v_pk_add_f32 v[30:31], v[38:39], v[42:43] op_sel:[0,1] op_sel_hi:[1,0] neg_hi:[0,1]
	v_pk_add_f32 v[34:35], v[38:39], v[42:43] op_sel:[0,1] op_sel_hi:[1,0] neg_lo:[0,1]
	v_pk_mul_f32 v[218:219], v[28:29], v[228:229] op_sel:[1,1] op_sel_hi:[1,0]
	v_pk_mul_f32 v[220:221], v[32:33], v[232:233] op_sel:[1,1] op_sel_hi:[1,0]
	v_pk_mul_f32 v[36:37], v[30:31], v[230:231] op_sel:[1,1] op_sel_hi:[1,0]
	v_pk_mul_f32 v[40:41], v[34:35], v[234:235] op_sel:[1,1] op_sel_hi:[1,0]
	v_pk_fma_f32 v[28:29], v[28:29], v[228:229], v[218:219] op_sel_hi:[0,1,1] neg_lo:[0,0,1]
	v_pk_fma_f32 v[32:33], v[32:33], v[232:233], v[220:221] op_sel_hi:[0,1,1] neg_lo:[0,0,1]
	v_pk_fma_f32 v[30:31], v[30:31], v[230:231], v[36:37] op_sel_hi:[0,1,1] neg_lo:[0,0,1]
	v_pk_fma_f32 v[34:35], v[34:35], v[234:235], v[40:41] op_sel_hi:[0,1,1] neg_lo:[0,0,1]
	s_nop 0
	ds_write_b64 v241, v[28:29] offset:49152
	ds_write_b64 v243, v[32:33] offset:49152
	ds_write_b64 v242, v[30:31] offset:49152
	ds_write_b64 v244, v[34:35] offset:49152
	v_add_u32_e32 v241, 0x10000, v241
	v_add_u32_e32 v242, 0x10000, v242
	v_add_u32_e32 v243, 0x10000, v243
	v_add_u32_e32 v244, 0x10000, v244
	ds_read_b64 v[28:29], v241
	ds_read_b64 v[30:31], v242
	ds_read_b64 v[32:33], v243
	ds_read_b64 v[34:35], v244
	s_waitcnt lgkmcnt(0)
	v_pk_mul_f32 v[218:219], v[30:31], v[222:223] op_sel:[1,1] op_sel_hi:[1,0]
	v_pk_mul_f32 v[220:221], v[32:33], v[224:225] op_sel:[1,1] op_sel_hi:[1,0]
	v_pk_mul_f32 v[36:37], v[34:35], v[226:227] op_sel:[1,1] op_sel_hi:[1,0]
	v_pk_fma_f32 v[30:31], v[30:31], v[222:223], v[218:219] op_sel_hi:[0,1,1] neg_lo:[0,0,1]
	v_pk_fma_f32 v[32:33], v[32:33], v[224:225], v[220:221] op_sel_hi:[0,1,1] neg_lo:[0,0,1]
	v_pk_fma_f32 v[34:35], v[34:35], v[226:227], v[36:37] op_sel_hi:[0,1,1] neg_lo:[0,0,1]
	v_pk_add_f32 v[36:37], v[28:29], v[32:33]
	v_pk_add_f32 v[38:39], v[28:29], v[32:33] neg_lo:[0,1] neg_hi:[0,1]
	v_pk_add_f32 v[40:41], v[30:31], v[34:35]
	v_pk_add_f32 v[42:43], v[30:31], v[34:35] neg_lo:[0,1] neg_hi:[0,1]
	v_pk_add_f32 v[28:29], v[36:37], v[40:41]
	v_pk_add_f32 v[32:33], v[36:37], v[40:41] neg_lo:[0,1] neg_hi:[0,1]
	v_pk_add_f32 v[30:31], v[38:39], v[42:43] op_sel:[0,1] op_sel_hi:[1,0] neg_hi:[0,1]
	v_pk_add_f32 v[34:35], v[38:39], v[42:43] op_sel:[0,1] op_sel_hi:[1,0] neg_lo:[0,1]
	v_pk_mul_f32 v[218:219], v[28:29], v[228:229] op_sel:[1,1] op_sel_hi:[1,0]
	v_pk_mul_f32 v[220:221], v[32:33], v[232:233] op_sel:[1,1] op_sel_hi:[1,0]
	v_pk_mul_f32 v[36:37], v[30:31], v[230:231] op_sel:[1,1] op_sel_hi:[1,0]
	v_pk_mul_f32 v[40:41], v[34:35], v[234:235] op_sel:[1,1] op_sel_hi:[1,0]
	v_pk_fma_f32 v[28:29], v[28:29], v[228:229], v[218:219] op_sel_hi:[0,1,1] neg_lo:[0,0,1]
	v_pk_fma_f32 v[32:33], v[32:33], v[232:233], v[220:221] op_sel_hi:[0,1,1] neg_lo:[0,0,1]
	v_pk_fma_f32 v[30:31], v[30:31], v[230:231], v[36:37] op_sel_hi:[0,1,1] neg_lo:[0,0,1]
	v_pk_fma_f32 v[34:35], v[34:35], v[234:235], v[40:41] op_sel_hi:[0,1,1] neg_lo:[0,0,1]
	s_nop 0
	ds_write_b64 v241, v[28:29]
	ds_write_b64 v243, v[32:33]
	ds_write_b64 v242, v[30:31]
	ds_write_b64 v244, v[34:35]
	ds_read_b64 v[28:29], v241 offset:16384
	ds_read_b64 v[30:31], v242 offset:16384
	ds_read_b64 v[32:33], v243 offset:16384
	ds_read_b64 v[34:35], v244 offset:16384
	s_waitcnt lgkmcnt(0)
; DI float2 twid(float r) { return float2{__builtin_amdgcn_cosf(r), -__builtin_amdgcn_sinf(r)}; }
; DI void bfly_fwd(float2 a0, float2 a1, float2 a2, float2 a3, float r, float2& o0, float2& o1, float2& o2, float2& o3) {
;   float2 t0 = {a0.x + a2.x, a0.y + a2.y}, t1 = {a0.x - a2.x, a0.y - a2.y}, t2 = {a1.x + a3.x, a1.y + a3.y}, t3 = {a1.x - a3.x, a1.y - a3.y};
;   float2 b0 = {t0.x + t2.x, t0.y + t2.y}, b2 = {t0.x - t2.x, t0.y - t2.y}, b1 = {t1.x + t3.y, t1.y - t3.x}, b3 = {t1.x - t3.y, t1.y + t3.x};
;   float2 w1 = twid(r), w2 = cmul(w1, w1), w3 = cmul(w2, w1);
;   o0 = b0; o1 = cmul(b1, w1); o2 = cmul(b2, w2); o3 = cmul(b3, w3);
; }
;   const int Q = 1 << lq; const float invM = 1.f / (float)(4 << lq);
;   for (int bb = tid; bb < NBT * (N / 4); bb += NTHR) { const int b = bb & (N / 4 - 1); float2* z = z0 + (bb / (N / 4)) * N; int j = b & (Q - 1), base = ((b >> lq) << (lq + 2)) + j; float2 o0, o1, o2, o3;
;     bfly_fwd(z[base], z[base + Q], z[base + 2 * Q], z[base + 3 * Q], (float)j * invM, o0, o1, o2, o3);
;     z[base] = o0; z[base + Q] = o1; z[base + 2 * Q] = o2; z[base + 3 * Q] = o3; }
;   __syncthreads();
; }
	v_pk_mul_f32 v[218:219], v[30:31], v[222:223] op_sel:[1,1] op_sel_hi:[1,0]
	v_pk_mul_f32 v[220:221], v[32:33], v[224:225] op_sel:[1,1] op_sel_hi:[1,0]
	v_pk_mul_f32 v[36:37], v[34:35], v[226:227] op_sel:[1,1] op_sel_hi:[1,0]
	v_pk_fma_f32 v[30:31], v[30:31], v[222:223], v[218:219] op_sel_hi:[0,1,1] neg_lo:[0,0,1]
	v_pk_fma_f32 v[32:33], v[32:33], v[224:225], v[220:221] op_sel_hi:[0,1,1] neg_lo:[0,0,1]
	v_pk_fma_f32 v[34:35], v[34:35], v[226:227], v[36:37] op_sel_hi:[0,1,1] neg_lo:[0,0,1]
	v_pk_add_f32 v[36:37], v[28:29], v[32:33]
	v_pk_add_f32 v[38:39], v[28:29], v[32:33] neg_lo:[0,1] neg_hi:[0,1]
	v_pk_add_f32 v[40:41], v[30:31], v[34:35]
	v_pk_add_f32 v[42:43], v[30:31], v[34:35] neg_lo:[0,1] neg_hi:[0,1]
	v_pk_add_f32 v[28:29], v[36:37], v[40:41]
	v_pk_add_f32 v[32:33], v[36:37], v[40:41] neg_lo:[0,1] neg_hi:[0,1]
	v_pk_add_f32 v[30:31], v[38:39], v[42:43] op_sel:[0,1] op_sel_hi:[1,0] neg_hi:[0,1]
	v_pk_add_f32 v[34:35], v[38:39], v[42:43] op_sel:[0,1] op_sel_hi:[1,0] neg_lo:[0,1]
	v_pk_mul_f32 v[218:219], v[28:29], v[228:229] op_sel:[1,1] op_sel_hi:[1,0]
	v_pk_mul_f32 v[220:221], v[32:33], v[232:233] op_sel:[1,1] op_sel_hi:[1,0]
	v_pk_mul_f32 v[36:37], v[30:31], v[230:231] op_sel:[1,1] op_sel_hi:[1,0]
	v_pk_mul_f32 v[40:41], v[34:35], v[234:235] op_sel:[1,1] op_sel_hi:[1,0]
	v_pk_fma_f32 v[28:29], v[28:29], v[228:229], v[218:219] op_sel_hi:[0,1,1] neg_lo:[0,0,1]
	v_pk_fma_f32 v[32:33], v[32:33], v[232:233], v[220:221] op_sel_hi:[0,1,1] neg_lo:[0,0,1]
	v_pk_fma_f32 v[30:31], v[30:31], v[230:231], v[36:37] op_sel_hi:[0,1,1] neg_lo:[0,0,1]
	v_pk_fma_f32 v[34:35], v[34:35], v[234:235], v[40:41] op_sel_hi:[0,1,1] neg_lo:[0,0,1]
	s_nop 0
	ds_write_b64 v241, v[28:29] offset:16384
	ds_write_b64 v243, v[32:33] offset:16384
	ds_write_b64 v242, v[30:31] offset:16384
	ds_write_b64 v244, v[34:35] offset:16384
	ds_read_b64 v[28:29], v241 offset:32768
	ds_read_b64 v[30:31], v242 offset:32768
	ds_read_b64 v[32:33], v243 offset:32768
	ds_read_b64 v[34:35], v244 offset:32768
	s_waitcnt lgkmcnt(0)
	v_pk_mul_f32 v[218:219], v[30:31], v[222:223] op_sel:[1,1] op_sel_hi:[1,0]
	v_pk_mul_f32 v[220:221], v[32:33], v[224:225] op_sel:[1,1] op_sel_hi:[1,0]
	v_pk_mul_f32 v[36:37], v[34:35], v[226:227] op_sel:[1,1] op_sel_hi:[1,0]
	v_pk_fma_f32 v[30:31], v[30:31], v[222:223], v[218:219] op_sel_hi:[0,1,1] neg_lo:[0,0,1]
	v_pk_fma_f32 v[32:33], v[32:33], v[224:225], v[220:221] op_sel_hi:[0,1,1] neg_lo:[0,0,1]
	v_pk_fma_f32 v[34:35], v[34:35], v[226:227], v[36:37] op_sel_hi:[0,1,1] neg_lo:[0,0,1]
	v_pk_add_f32 v[36:37], v[28:29], v[32:33]
	v_pk_add_f32 v[38:39], v[28:29], v[32:33] neg_lo:[0,1] neg_hi:[0,1]
	v_pk_add_f32 v[40:41], v[30:31], v[34:35]
	v_pk_add_f32 v[42:43], v[30:31], v[34:35] neg_lo:[0,1] neg_hi:[0,1]
	v_pk_add_f32 v[28:29], v[36:37], v[40:41]
	v_pk_add_f32 v[32:33], v[36:37], v[40:41] neg_lo:[0,1] neg_hi:[0,1]
	v_pk_add_f32 v[30:31], v[38:39], v[42:43] op_sel:[0,1] op_sel_hi:[1,0] neg_hi:[0,1]
	v_pk_add_f32 v[34:35], v[38:39], v[42:43] op_sel:[0,1] op_sel_hi:[1,0] neg_lo:[0,1]
	v_pk_mul_f32 v[218:219], v[28:29], v[228:229] op_sel:[1,1] op_sel_hi:[1,0]
	v_pk_mul_f32 v[220:221], v[32:33], v[232:233] op_sel:[1,1] op_sel_hi:[1,0]
	v_pk_mul_f32 v[36:37], v[30:31], v[230:231] op_sel:[1,1] op_sel_hi:[1,0]
	v_pk_mul_f32 v[40:41], v[34:35], v[234:235] op_sel:[1,1] op_sel_hi:[1,0]
	v_pk_fma_f32 v[28:29], v[28:29], v[228:229], v[218:219] op_sel_hi:[0,1,1] neg_lo:[0,0,1]
	v_pk_fma_f32 v[32:33], v[32:33], v[232:233], v[220:221] op_sel_hi:[0,1,1] neg_lo:[0,0,1]
	v_pk_fma_f32 v[30:31], v[30:31], v[230:231], v[36:37] op_sel_hi:[0,1,1] neg_lo:[0,0,1]
	v_pk_fma_f32 v[34:35], v[34:35], v[234:235], v[40:41] op_sel_hi:[0,1,1] neg_lo:[0,0,1]
	s_nop 0
	ds_write_b64 v241, v[28:29] offset:32768
	ds_write_b64 v243, v[32:33] offset:32768
	ds_write_b64 v242, v[30:31] offset:32768
	ds_write_b64 v244, v[34:35] offset:32768
	ds_read_b64 v[28:29], v241 offset:49152
	ds_read_b64 v[30:31], v242 offset:49152
	ds_read_b64 v[32:33], v243 offset:49152
	ds_read_b64 v[34:35], v244 offset:49152
	s_waitcnt lgkmcnt(0)
	v_pk_mul_f32 v[218:219], v[30:31], v[222:223] op_sel:[1,1] op_sel_hi:[1,0]
	v_pk_mul_f32 v[220:221], v[32:33], v[224:225] op_sel:[1,1] op_sel_hi:[1,0]
	v_pk_mul_f32 v[36:37], v[34:35], v[226:227] op_sel:[1,1] op_sel_hi:[1,0]
	v_pk_fma_f32 v[30:31], v[30:31], v[222:223], v[218:219] op_sel_hi:[0,1,1] neg_lo:[0,0,1]
	v_pk_fma_f32 v[32:33], v[32:33], v[224:225], v[220:221] op_sel_hi:[0,1,1] neg_lo:[0,0,1]
	v_pk_fma_f32 v[34:35], v[34:35], v[226:227], v[36:37] op_sel_hi:[0,1,1] neg_lo:[0,0,1]
	v_pk_add_f32 v[36:37], v[28:29], v[32:33]
	v_pk_add_f32 v[38:39], v[28:29], v[32:33] neg_lo:[0,1] neg_hi:[0,1]
	v_pk_add_f32 v[40:41], v[30:31], v[34:35]
	v_pk_add_f32 v[42:43], v[30:31], v[34:35] neg_lo:[0,1] neg_hi:[0,1]
	v_pk_add_f32 v[28:29], v[36:37], v[40:41]
	v_pk_add_f32 v[32:33], v[36:37], v[40:41] neg_lo:[0,1] neg_hi:[0,1]
	v_pk_add_f32 v[30:31], v[38:39], v[42:43] op_sel:[0,1] op_sel_hi:[1,0] neg_hi:[0,1]
	v_pk_add_f32 v[34:35], v[38:39], v[42:43] op_sel:[0,1] op_sel_hi:[1,0] neg_lo:[0,1]
	v_pk_mul_f32 v[218:219], v[28:29], v[228:229] op_sel:[1,1] op_sel_hi:[1,0]
	v_pk_mul_f32 v[220:221], v[32:33], v[232:233] op_sel:[1,1] op_sel_hi:[1,0]
	v_pk_mul_f32 v[36:37], v[30:31], v[230:231] op_sel:[1,1] op_sel_hi:[1,0]
	v_pk_mul_f32 v[40:41], v[34:35], v[234:235] op_sel:[1,1] op_sel_hi:[1,0]
	v_pk_fma_f32 v[28:29], v[28:29], v[228:229], v[218:219] op_sel_hi:[0,1,1] neg_lo:[0,0,1]
	v_pk_fma_f32 v[32:33], v[32:33], v[232:233], v[220:221] op_sel_hi:[0,1,1] neg_lo:[0,0,1]
	v_pk_fma_f32 v[30:31], v[30:31], v[230:231], v[36:37] op_sel_hi:[0,1,1] neg_lo:[0,0,1]
	v_pk_fma_f32 v[34:35], v[34:35], v[234:235], v[40:41] op_sel_hi:[0,1,1] neg_lo:[0,0,1]
	s_nop 0
	ds_write_b64 v241, v[28:29] offset:49152
	ds_write_b64 v243, v[32:33] offset:49152
	ds_write_b64 v242, v[30:31] offset:49152
	ds_write_b64 v244, v[34:35] offset:49152
	v_add_u32_e32 v25, 0x4000, v25
	v_add_u32_e32 v27, 0x1000, v26
	v_mov_b32_e32 v26, v27
	s_mov_b64 s[10:11], exec

; DI float2 twid(float r) { return float2{__builtin_amdgcn_cosf(r), -__builtin_amdgcn_sinf(r)}; }
; DI void bfly_fwd(float2 a0, float2 a1, float2 a2, float2 a3, float r, float2& o0, float2& o1, float2& o2, float2& o3) {
;   float2 t0 = {a0.x + a2.x, a0.y + a2.y}, t1 = {a0.x - a2.x, a0.y - a2.y}, t2 = {a1.x + a3.x, a1.y + a3.y}, t3 = {a1.x - a3.x, a1.y - a3.y};
;   float2 b0 = {t0.x + t2.x, t0.y + t2.y}, b2 = {t0.x - t2.x, t0.y - t2.y}, b1 = {t1.x + t3.y, t1.y - t3.x}, b3 = {t1.x - t3.y, t1.y + t3.x};
;   float2 w1 = twid(r), w2 = cmul(w1, w1), w3 = cmul(w2, w1);
;   o0 = b0; o1 = cmul(b1, w1); o2 = cmul(b2, w2); o3 = cmul(b3, w3);
; }
;   const int Q = 1 << lq; const float invM = 1.f / (float)(4 << lq);
;   for (int bb = tid; bb < NBT * (N / 4); bb += NTHR) { const int b = bb & (N / 4 - 1); float2* z = z0 + (bb / (N / 4)) * N; int j = b & (Q - 1), base = ((b >> lq) << (lq + 2)) + j; float2 o0, o1, o2, o3;
;     bfly_fwd(z[base], z[base + Q], z[base + 2 * Q], z[base + 3 * Q], (float)j * invM, o0, o1, o2, o3);
;     z[base] = o0; z[base + Q] = o1; z[base + 2 * Q] = o2; z[base + 3 * Q] = o3; }
;   __syncthreads();
; }
.LBB0_1527:
	v_ashrrev_i32_e32 v13, 31, v12
	v_lshrrev_b32_e32 v13, 20, v13
	v_add_lshl_u32 v13, v12, v13, 5
	v_and_b32_e32 v14, 0x3ffc, v11
	v_and_b32_e32 v13, 0xfffe0000, v13
	v_lshlrev_b32_e32 v14, 3, v14
	v_add3_u32 v13, 16, v13, v14
	ds_read_b128 v[14:17], v13
	ds_read_b128 v[18:21], v13 offset:16
	s_waitcnt lgkmcnt(0)
	v_pk_add_f32 v[22:23], v[14:15], v[18:19]
	v_pk_add_f32 v[26:27], v[16:17], v[20:21]
	v_pk_add_f32 v[24:25], v[14:15], v[18:19] neg_lo:[0,1] neg_hi:[0,1]
	v_pk_add_f32 v[28:29], v[16:17], v[20:21] neg_lo:[0,1] neg_hi:[0,1]
	v_pk_add_f32 v[14:15], v[22:23], v[26:27]
	v_pk_add_f32 v[18:19], v[22:23], v[26:27] neg_lo:[0,1] neg_hi:[0,1]
	v_pk_add_f32 v[16:17], v[24:25], v[28:29] op_sel:[0,1] op_sel_hi:[1,0] neg_hi:[0,1]
	v_pk_add_f32 v[20:21], v[24:25], v[28:29] op_sel:[0,1] op_sel_hi:[1,0] neg_lo:[0,1]
	s_nop 0
	ds_write_b128 v13, v[14:17]
	ds_write_b128 v13, v[18:21] offset:16
	ds_read_b128 v[14:17], v13 offset:16384
	ds_read_b128 v[18:21], v13 offset:16400
	s_waitcnt lgkmcnt(0)
	v_pk_add_f32 v[22:23], v[14:15], v[18:19]
	v_pk_add_f32 v[26:27], v[16:17], v[20:21]
	v_pk_add_f32 v[24:25], v[14:15], v[18:19] neg_lo:[0,1] neg_hi:[0,1]
	v_pk_add_f32 v[28:29], v[16:17], v[20:21] neg_lo:[0,1] neg_hi:[0,1]
	v_pk_add_f32 v[14:15], v[22:23], v[26:27]
	v_pk_add_f32 v[18:19], v[22:23], v[26:27] neg_lo:[0,1] neg_hi:[0,1]
	v_pk_add_f32 v[16:17], v[24:25], v[28:29] op_sel:[0,1] op_sel_hi:[1,0] neg_hi:[0,1]
	v_pk_add_f32 v[20:21], v[24:25], v[28:29] op_sel:[0,1] op_sel_hi:[1,0] neg_lo:[0,1]
	s_nop 0
	ds_write_b128 v13, v[14:17] offset:16384
	ds_write_b128 v13, v[18:21] offset:16400
	ds_read_b128 v[14:17], v13 offset:32768
	ds_read_b128 v[18:21], v13 offset:32784
	s_waitcnt lgkmcnt(0)
	v_pk_add_f32 v[22:23], v[14:15], v[18:19]
	v_pk_add_f32 v[26:27], v[16:17], v[20:21]
	v_pk_add_f32 v[24:25], v[14:15], v[18:19] neg_lo:[0,1] neg_hi:[0,1]
	v_pk_add_f32 v[28:29], v[16:17], v[20:21] neg_lo:[0,1] neg_hi:[0,1]
	v_pk_add_f32 v[14:15], v[22:23], v[26:27]
	v_pk_add_f32 v[18:19], v[22:23], v[26:27] neg_lo:[0,1] neg_hi:[0,1]
	v_pk_add_f32 v[16:17], v[24:25], v[28:29] op_sel:[0,1] op_sel_hi:[1,0] neg_hi:[0,1]
	v_pk_add_f32 v[20:21], v[24:25], v[28:29] op_sel:[0,1] op_sel_hi:[1,0] neg_lo:[0,1]
	s_nop 0
	ds_write_b128 v13, v[14:17] offset:32768
	ds_write_b128 v13, v[18:21] offset:32784
	ds_read_b128 v[14:17], v13 offset:49152
	ds_read_b128 v[18:21], v13 offset:49168
	s_waitcnt lgkmcnt(0)
	v_pk_add_f32 v[22:23], v[14:15], v[18:19]
	v_pk_add_f32 v[26:27], v[16:17], v[20:21]
	v_pk_add_f32 v[24:25], v[14:15], v[18:19] neg_lo:[0,1] neg_hi:[0,1]
	v_pk_add_f32 v[28:29], v[16:17], v[20:21] neg_lo:[0,1] neg_hi:[0,1]
	v_pk_add_f32 v[14:15], v[22:23], v[26:27]
	v_pk_add_f32 v[18:19], v[22:23], v[26:27] neg_lo:[0,1] neg_hi:[0,1]
	v_pk_add_f32 v[16:17], v[24:25], v[28:29] op_sel:[0,1] op_sel_hi:[1,0] neg_hi:[0,1]
	v_pk_add_f32 v[20:21], v[24:25], v[28:29] op_sel:[0,1] op_sel_hi:[1,0] neg_lo:[0,1]
	s_nop 0
	ds_write_b128 v13, v[14:17] offset:49152
	ds_write_b128 v13, v[18:21] offset:49168
	v_add_u32_e32 v13, 0x10000, v13
	ds_read_b128 v[14:17], v13
	ds_read_b128 v[18:21], v13 offset:16
	s_waitcnt lgkmcnt(0)
	v_pk_add_f32 v[22:23], v[14:15], v[18:19]
	v_pk_add_f32 v[26:27], v[16:17], v[20:21]
	v_pk_add_f32 v[24:25], v[14:15], v[18:19] neg_lo:[0,1] neg_hi:[0,1]
	v_pk_add_f32 v[28:29], v[16:17], v[20:21] neg_lo:[0,1] neg_hi:[0,1]
	v_pk_add_f32 v[14:15], v[22:23], v[26:27]
	v_pk_add_f32 v[18:19], v[22:23], v[26:27] neg_lo:[0,1] neg_hi:[0,1]
	v_pk_add_f32 v[16:17], v[24:25], v[28:29] op_sel:[0,1] op_sel_hi:[1,0] neg_hi:[0,1]
	v_pk_add_f32 v[20:21], v[24:25], v[28:29] op_sel:[0,1] op_sel_hi:[1,0] neg_lo:[0,1]
	s_nop 0
	ds_write_b128 v13, v[14:17]
	ds_write_b128 v13, v[18:21] offset:16
	ds_read_b128 v[14:17], v13 offset:16384
	ds_read_b128 v[18:21], v13 offset:16400
	s_waitcnt lgkmcnt(0)
	v_pk_add_f32 v[22:23], v[14:15], v[18:19]
	v_pk_add_f32 v[26:27], v[16:17], v[20:21]
	v_pk_add_f32 v[24:25], v[14:15], v[18:19] neg_lo:[0,1] neg_hi:[0,1]
	v_pk_add_f32 v[28:29], v[16:17], v[20:21] neg_lo:[0,1] neg_hi:[0,1]
	v_pk_add_f32 v[14:15], v[22:23], v[26:27]
	v_pk_add_f32 v[18:19], v[22:23], v[26:27] neg_lo:[0,1] neg_hi:[0,1]
	v_pk_add_f32 v[16:17], v[24:25], v[28:29] op_sel:[0,1] op_sel_hi:[1,0] neg_hi:[0,1]
	v_pk_add_f32 v[20:21], v[24:25], v[28:29] op_sel:[0,1] op_sel_hi:[1,0] neg_lo:[0,1]
	s_nop 0
	ds_write_b128 v13, v[14:17] offset:16384
	ds_write_b128 v13, v[18:21] offset:16400
	ds_read_b128 v[14:17], v13 offset:32768
	ds_read_b128 v[18:21], v13 offset:32784
	s_waitcnt lgkmcnt(0)
	v_pk_add_f32 v[22:23], v[14:15], v[18:19]
	v_pk_add_f32 v[26:27], v[16:17], v[20:21]
	v_pk_add_f32 v[24:25], v[14:15], v[18:19] neg_lo:[0,1] neg_hi:[0,1]
	v_pk_add_f32 v[28:29], v[16:17], v[20:21] neg_lo:[0,1] neg_hi:[0,1]
	v_pk_add_f32 v[14:15], v[22:23], v[26:27]
	v_pk_add_f32 v[18:19], v[22:23], v[26:27] neg_lo:[0,1] neg_hi:[0,1]
	v_pk_add_f32 v[16:17], v[24:25], v[28:29] op_sel:[0,1] op_sel_hi:[1,0] neg_hi:[0,1]
	v_pk_add_f32 v[20:21], v[24:25], v[28:29] op_sel:[0,1] op_sel_hi:[1,0] neg_lo:[0,1]
	s_nop 0
	ds_write_b128 v13, v[14:17] offset:32768
	ds_write_b128 v13, v[18:21] offset:32784
	ds_read_b128 v[14:17], v13 offset:49152
	ds_read_b128 v[18:21], v13 offset:49168
	s_waitcnt lgkmcnt(0)
	v_pk_add_f32 v[22:23], v[14:15], v[18:19]
	v_pk_add_f32 v[26:27], v[16:17], v[20:21]
	v_pk_add_f32 v[24:25], v[14:15], v[18:19] neg_lo:[0,1] neg_hi:[0,1]
	v_pk_add_f32 v[28:29], v[16:17], v[20:21] neg_lo:[0,1] neg_hi:[0,1]
	v_pk_add_f32 v[14:15], v[22:23], v[26:27]
	v_pk_add_f32 v[18:19], v[22:23], v[26:27] neg_lo:[0,1] neg_hi:[0,1]
	v_pk_add_f32 v[16:17], v[24:25], v[28:29] op_sel:[0,1] op_sel_hi:[1,0] neg_hi:[0,1]
	v_pk_add_f32 v[20:21], v[24:25], v[28:29] op_sel:[0,1] op_sel_hi:[1,0] neg_lo:[0,1]
	s_nop 0
	ds_write_b128 v13, v[14:17] offset:49152
	ds_write_b128 v13, v[18:21] offset:49168
	v_add_u32_e32 v11, 0x4000, v11
	v_add_u32_e32 v13, 0x1000, v12
	v_mov_b32_e32 v12, v13
	s_mov_b64 s[8:9], exec

; DI float2 twid(float r) { return float2{__builtin_amdgcn_cosf(r), -__builtin_amdgcn_sinf(r)}; }
; DI void bfly_fwd(float2 a0, float2 a1, float2 a2, float2 a3, float r, float2& o0, float2& o1, float2& o2, float2& o3) {
;   float2 t0 = {a0.x + a2.x, a0.y + a2.y}, t1 = {a0.x - a2.x, a0.y - a2.y}, t2 = {a1.x + a3.x, a1.y + a3.y}, t3 = {a1.x - a3.x, a1.y - a3.y};
;   float2 b0 = {t0.x + t2.x, t0.y + t2.y}, b2 = {t0.x - t2.x, t0.y - t2.y}, b1 = {t1.x + t3.y, t1.y - t3.x}, b3 = {t1.x - t3.y, t1.y + t3.x};
;   float2 w1 = twid(r), w2 = cmul(w1, w1), w3 = cmul(w2, w1);
;   o0 = b0; o1 = cmul(b1, w1); o2 = cmul(b2, w2); o3 = cmul(b3, w3);
; }
;   const int Q = 1 << lq; const float invM = 1.f / (float)(4 << lq);
;   for (int bb = tid; bb < NBT * (N / 4); bb += NTHR) { const int b = bb & (N / 4 - 1); float2* z = z0 + (bb / (N / 4)) * N; int j = b & (Q - 1), base = ((b >> lq) << (lq + 2)) + j; float2 o0, o1, o2, o3;
;     bfly_fwd(z[base], z[base + Q], z[base + 2 * Q], z[base + 3 * Q], (float)j * invM, o0, o1, o2, o3);
;     z[base] = o0; z[base + Q] = o1; z[base + 2 * Q] = o2; z[base + 3 * Q] = o3; }
;   __syncthreads();
; }
.LBB0_1606:
	v_ashrrev_i32_e32 v19, 31, v18
	v_lshrrev_b32_e32 v19, 21, v19
	v_add_lshl_u32 v19, v18, v19, 5
	v_and_b32_e32 v19, 0xffff0000, v19
	v_and_b32_e32 v20, 0x1ff0, v17
	v_add_u32_e32 v19, 16, v19
	v_lshlrev_b32_e32 v20, 3, v20
	v_lshlrev_b32_e32 v21, 3, v14
	v_add3_u32 v19, v19, v20, v21
	v_add_u32_e32 v241, v19, v236
	v_add_u32_e32 v242, v19, v237
	v_add_u32_e32 v243, v19, v238
	v_add_u32_e32 v244, v19, v239
	ds_read_b64 v[20:21], v241
	ds_read_b64 v[22:23], v242
	ds_read_b64 v[24:25], v243
	ds_read_b64 v[26:27], v244
	s_waitcnt lgkmcnt(0)
	v_pk_mul_f32 v[218:219], v[22:23], v[222:223] op_sel:[1,1] op_sel_hi:[1,0]
	v_pk_mul_f32 v[220:221], v[24:25], v[224:225] op_sel:[1,1] op_sel_hi:[1,0]
	v_pk_mul_f32 v[28:29], v[26:27], v[226:227] op_sel:[1,1] op_sel_hi:[1,0]
	v_pk_fma_f32 v[22:23], v[22:23], v[222:223], v[218:219] op_sel_hi:[0,1,1] neg_lo:[0,0,1]
	v_pk_fma_f32 v[24:25], v[24:25], v[224:225], v[220:221] op_sel_hi:[0,1,1] neg_lo:[0,0,1]
	v_pk_fma_f32 v[26:27], v[26:27], v[226:227], v[28:29] op_sel_hi:[0,1,1] neg_lo:[0,0,1]
	v_pk_add_f32 v[28:29], v[20:21], v[24:25]
	v_pk_add_f32 v[30:31], v[20:21], v[24:25] neg_lo:[0,1] neg_hi:[0,1]
	v_pk_add_f32 v[32:33], v[22:23], v[26:27]
	v_pk_add_f32 v[34:35], v[22:23], v[26:27] neg_lo:[0,1] neg_hi:[0,1]
	v_pk_add_f32 v[20:21], v[28:29], v[32:33]
	v_pk_add_f32 v[24:25], v[28:29], v[32:33] neg_lo:[0,1] neg_hi:[0,1]
	v_pk_add_f32 v[22:23], v[30:31], v[34:35] op_sel:[0,1] op_sel_hi:[1,0] neg_hi:[0,1]
	v_pk_add_f32 v[26:27], v[30:31], v[34:35] op_sel:[0,1] op_sel_hi:[1,0] neg_lo:[0,1]
	v_pk_mul_f32 v[218:219], v[20:21], v[228:229] op_sel:[1,1] op_sel_hi:[1,0]
	v_pk_mul_f32 v[220:221], v[24:25], v[232:233] op_sel:[1,1] op_sel_hi:[1,0]
	v_pk_mul_f32 v[28:29], v[22:23], v[230:231] op_sel:[1,1] op_sel_hi:[1,0]
	v_pk_mul_f32 v[32:33], v[26:27], v[234:235] op_sel:[1,1] op_sel_hi:[1,0]
	v_pk_fma_f32 v[20:21], v[20:21], v[228:229], v[218:219] op_sel_hi:[0,1,1] neg_lo:[0,0,1]
	v_pk_fma_f32 v[24:25], v[24:25], v[232:233], v[220:221] op_sel_hi:[0,1,1] neg_lo:[0,0,1]
	v_pk_fma_f32 v[22:23], v[22:23], v[230:231], v[28:29] op_sel_hi:[0,1,1] neg_lo:[0,0,1]
	v_pk_fma_f32 v[26:27], v[26:27], v[234:235], v[32:33] op_sel_hi:[0,1,1] neg_lo:[0,0,1]
	s_nop 0
	ds_write_b64 v241, v[20:21]
	ds_write_b64 v243, v[24:25]
	ds_write_b64 v242, v[22:23]
	ds_write_b64 v244, v[26:27]
	ds_read_b64 v[20:21], v241 offset:16384
	ds_read_b64 v[22:23], v242 offset:16384
	ds_read_b64 v[24:25], v243 offset:16384
	ds_read_b64 v[26:27], v244 offset:16384
	s_waitcnt lgkmcnt(0)
	v_pk_mul_f32 v[218:219], v[22:23], v[222:223] op_sel:[1,1] op_sel_hi:[1,0]
	v_pk_mul_f32 v[220:221], v[24:25], v[224:225] op_sel:[1,1] op_sel_hi:[1,0]
	v_pk_mul_f32 v[28:29], v[26:27], v[226:227] op_sel:[1,1] op_sel_hi:[1,0]
	v_pk_fma_f32 v[22:23], v[22:23], v[222:223], v[218:219] op_sel_hi:[0,1,1] neg_lo:[0,0,1]
	v_pk_fma_f32 v[24:25], v[24:25], v[224:225], v[220:221] op_sel_hi:[0,1,1] neg_lo:[0,0,1]
	v_pk_fma_f32 v[26:27], v[26:27], v[226:227], v[28:29] op_sel_hi:[0,1,1] neg_lo:[0,0,1]
	v_pk_add_f32 v[28:29], v[20:21], v[24:25]
	v_pk_add_f32 v[30:31], v[20:21], v[24:25] neg_lo:[0,1] neg_hi:[0,1]
	v_pk_add_f32 v[32:33], v[22:23], v[26:27]
	v_pk_add_f32 v[34:35], v[22:23], v[26:27] neg_lo:[0,1] neg_hi:[0,1]
	v_pk_add_f32 v[20:21], v[28:29], v[32:33]
	v_pk_add_f32 v[24:25], v[28:29], v[32:33] neg_lo:[0,1] neg_hi:[0,1]
	v_pk_add_f32 v[22:23], v[30:31], v[34:35] op_sel:[0,1] op_sel_hi:[1,0] neg_hi:[0,1]
	v_pk_add_f32 v[26:27], v[30:31], v[34:35] op_sel:[0,1] op_sel_hi:[1,0] neg_lo:[0,1]
	v_pk_mul_f32 v[218:219], v[20:21], v[228:229] op_sel:[1,1] op_sel_hi:[1,0]
	v_pk_mul_f32 v[220:221], v[24:25], v[232:233] op_sel:[1,1] op_sel_hi:[1,0]
	v_pk_mul_f32 v[28:29], v[22:23], v[230:231] op_sel:[1,1] op_sel_hi:[1,0]
	v_pk_mul_f32 v[32:33], v[26:27], v[234:235] op_sel:[1,1] op_sel_hi:[1,0]
	v_pk_fma_f32 v[20:21], v[20:21], v[228:229], v[218:219] op_sel_hi:[0,1,1] neg_lo:[0,0,1]
	v_pk_fma_f32 v[24:25], v[24:25], v[232:233], v[220:221] op_sel_hi:[0,1,1] neg_lo:[0,0,1]
	v_pk_fma_f32 v[22:23], v[22:23], v[230:231], v[28:29] op_sel_hi:[0,1,1] neg_lo:[0,0,1]
	v_pk_fma_f32 v[26:27], v[26:27], v[234:235], v[32:33] op_sel_hi:[0,1,1] neg_lo:[0,0,1]
	s_nop 0
	ds_write_b64 v241, v[20:21] offset:16384
	ds_write_b64 v243, v[24:25] offset:16384
	ds_write_b64 v242, v[22:23] offset:16384
	ds_write_b64 v244, v[26:27] offset:16384
	ds_read_b64 v[20:21], v241 offset:32768
	ds_read_b64 v[22:23], v242 offset:32768
	ds_read_b64 v[24:25], v243 offset:32768
	ds_read_b64 v[26:27], v244 offset:32768
	s_waitcnt lgkmcnt(0)
	v_pk_mul_f32 v[218:219], v[22:23], v[222:223] op_sel:[1,1] op_sel_hi:[1,0]
	v_pk_mul_f32 v[220:221], v[24:25], v[224:225] op_sel:[1,1] op_sel_hi:[1,0]
	v_pk_mul_f32 v[28:29], v[26:27], v[226:227] op_sel:[1,1] op_sel_hi:[1,0]
	v_pk_fma_f32 v[22:23], v[22:23], v[222:223], v[218:219] op_sel_hi:[0,1,1] neg_lo:[0,0,1]
	v_pk_fma_f32 v[24:25], v[24:25], v[224:225], v[220:221] op_sel_hi:[0,1,1] neg_lo:[0,0,1]
	v_pk_fma_f32 v[26:27], v[26:27], v[226:227], v[28:29] op_sel_hi:[0,1,1] neg_lo:[0,0,1]
	v_pk_add_f32 v[28:29], v[20:21], v[24:25]
	v_pk_add_f32 v[30:31], v[20:21], v[24:25] neg_lo:[0,1] neg_hi:[0,1]
	v_pk_add_f32 v[32:33], v[22:23], v[26:27]
	v_pk_add_f32 v[34:35], v[22:23], v[26:27] neg_lo:[0,1] neg_hi:[0,1]
	v_pk_add_f32 v[20:21], v[28:29], v[32:33]
	v_pk_add_f32 v[24:25], v[28:29], v[32:33] neg_lo:[0,1] neg_hi:[0,1]
	v_pk_add_f32 v[22:23], v[30:31], v[34:35] op_sel:[0,1] op_sel_hi:[1,0] neg_hi:[0,1]
	v_pk_add_f32 v[26:27], v[30:31], v[34:35] op_sel:[0,1] op_sel_hi:[1,0] neg_lo:[0,1]
	v_pk_mul_f32 v[218:219], v[20:21], v[228:229] op_sel:[1,1] op_sel_hi:[1,0]
	v_pk_mul_f32 v[220:221], v[24:25], v[232:233] op_sel:[1,1] op_sel_hi:[1,0]
	v_pk_mul_f32 v[28:29], v[22:23], v[230:231] op_sel:[1,1] op_sel_hi:[1,0]
	v_pk_mul_f32 v[32:33], v[26:27], v[234:235] op_sel:[1,1] op_sel_hi:[1,0]
	v_pk_fma_f32 v[20:21], v[20:21], v[228:229], v[218:219] op_sel_hi:[0,1,1] neg_lo:[0,0,1]
	v_pk_fma_f32 v[24:25], v[24:25], v[232:233], v[220:221] op_sel_hi:[0,1,1] neg_lo:[0,0,1]
	v_pk_fma_f32 v[22:23], v[22:23], v[230:231], v[28:29] op_sel_hi:[0,1,1] neg_lo:[0,0,1]
	v_pk_fma_f32 v[26:27], v[26:27], v[234:235], v[32:33] op_sel_hi:[0,1,1] neg_lo:[0,0,1]
	s_nop 0
	ds_write_b64 v241, v[20:21] offset:32768
	ds_write_b64 v243, v[24:25] offset:32768
	ds_write_b64 v242, v[22:23] offset:32768
	ds_write_b64 v244, v[26:27] offset:32768
	ds_read_b64 v[20:21], v241 offset:49152
	ds_read_b64 v[22:23], v242 offset:49152
	ds_read_b64 v[24:25], v243 offset:49152
	ds_read_b64 v[26:27], v244 offset:49152
	s_waitcnt lgkmcnt(0)
; DI float2 twid(float r) { return float2{__builtin_amdgcn_cosf(r), -__builtin_amdgcn_sinf(r)}; }
; DI void bfly_fwd(float2 a0, float2 a1, float2 a2, float2 a3, float r, float2& o0, float2& o1, float2& o2, float2& o3) {
;   float2 t0 = {a0.x + a2.x, a0.y + a2.y}, t1 = {a0.x - a2.x, a0.y - a2.y}, t2 = {a1.x + a3.x, a1.y + a3.y}, t3 = {a1.x - a3.x, a1.y - a3.y};
;   float2 b0 = {t0.x + t2.x, t0.y + t2.y}, b2 = {t0.x - t2.x, t0.y - t2.y}, b1 = {t1.x + t3.y, t1.y - t3.x}, b3 = {t1.x - t3.y, t1.y + t3.x};
;   float2 w1 = twid(r), w2 = cmul(w1, w1), w3 = cmul(w2, w1);
;   o0 = b0; o1 = cmul(b1, w1); o2 = cmul(b2, w2); o3 = cmul(b3, w3);
; }
;   const int Q = 1 << lq; const float invM = 1.f / (float)(4 << lq);
;   for (int bb = tid; bb < NBT * (N / 4); bb += NTHR) { const int b = bb & (N / 4 - 1); float2* z = z0 + (bb / (N / 4)) * N; int j = b & (Q - 1), base = ((b >> lq) << (lq + 2)) + j; float2 o0, o1, o2, o3;
;     bfly_fwd(z[base], z[base + Q], z[base + 2 * Q], z[base + 3 * Q], (float)j * invM, o0, o1, o2, o3);
;     z[base] = o0; z[base + Q] = o1; z[base + 2 * Q] = o2; z[base + 3 * Q] = o3; }
;   __syncthreads();
; }
	v_pk_mul_f32 v[218:219], v[22:23], v[222:223] op_sel:[1,1] op_sel_hi:[1,0]
	v_pk_mul_f32 v[220:221], v[24:25], v[224:225] op_sel:[1,1] op_sel_hi:[1,0]
	v_pk_mul_f32 v[28:29], v[26:27], v[226:227] op_sel:[1,1] op_sel_hi:[1,0]
	v_pk_fma_f32 v[22:23], v[22:23], v[222:223], v[218:219] op_sel_hi:[0,1,1] neg_lo:[0,0,1]
	v_pk_fma_f32 v[24:25], v[24:25], v[224:225], v[220:221] op_sel_hi:[0,1,1] neg_lo:[0,0,1]
	v_pk_fma_f32 v[26:27], v[26:27], v[226:227], v[28:29] op_sel_hi:[0,1,1] neg_lo:[0,0,1]
	v_pk_add_f32 v[28:29], v[20:21], v[24:25]
	v_pk_add_f32 v[30:31], v[20:21], v[24:25] neg_lo:[0,1] neg_hi:[0,1]
	v_pk_add_f32 v[32:33], v[22:23], v[26:27]
	v_pk_add_f32 v[34:35], v[22:23], v[26:27] neg_lo:[0,1] neg_hi:[0,1]
	v_pk_add_f32 v[20:21], v[28:29], v[32:33]
	v_pk_add_f32 v[24:25], v[28:29], v[32:33] neg_lo:[0,1] neg_hi:[0,1]
	v_pk_add_f32 v[22:23], v[30:31], v[34:35] op_sel:[0,1] op_sel_hi:[1,0] neg_hi:[0,1]
	v_pk_add_f32 v[26:27], v[30:31], v[34:35] op_sel:[0,1] op_sel_hi:[1,0] neg_lo:[0,1]
	v_pk_mul_f32 v[218:219], v[20:21], v[228:229] op_sel:[1,1] op_sel_hi:[1,0]
	v_pk_mul_f32 v[220:221], v[24:25], v[232:233] op_sel:[1,1] op_sel_hi:[1,0]
	v_pk_mul_f32 v[28:29], v[22:23], v[230:231] op_sel:[1,1] op_sel_hi:[1,0]
	v_pk_mul_f32 v[32:33], v[26:27], v[234:235] op_sel:[1,1] op_sel_hi:[1,0]
	v_pk_fma_f32 v[20:21], v[20:21], v[228:229], v[218:219] op_sel_hi:[0,1,1] neg_lo:[0,0,1]
	v_pk_fma_f32 v[24:25], v[24:25], v[232:233], v[220:221] op_sel_hi:[0,1,1] neg_lo:[0,0,1]
	v_pk_fma_f32 v[22:23], v[22:23], v[230:231], v[28:29] op_sel_hi:[0,1,1] neg_lo:[0,0,1]
	v_pk_fma_f32 v[26:27], v[26:27], v[234:235], v[32:33] op_sel_hi:[0,1,1] neg_lo:[0,0,1]
	s_nop 0
	ds_write_b64 v241, v[20:21] offset:49152
	ds_write_b64 v243, v[24:25] offset:49152
	ds_write_b64 v242, v[22:23] offset:49152
	ds_write_b64 v244, v[26:27] offset:49152
	v_add_u32_e32 v241, 0x10000, v241
	v_add_u32_e32 v242, 0x10000, v242
	v_add_u32_e32 v243, 0x10000, v243
	v_add_u32_e32 v244, 0x10000, v244
	ds_read_b64 v[20:21], v241
	ds_read_b64 v[22:23], v242
	ds_read_b64 v[24:25], v243
	ds_read_b64 v[26:27], v244
	s_waitcnt lgkmcnt(0)
	v_pk_mul_f32 v[218:219], v[22:23], v[222:223] op_sel:[1,1] op_sel_hi:[1,0]
	v_pk_mul_f32 v[220:221], v[24:25], v[224:225] op_sel:[1,1] op_sel_hi:[1,0]
	v_pk_mul_f32 v[28:29], v[26:27], v[226:227] op_sel:[1,1] op_sel_hi:[1,0]
	v_pk_fma_f32 v[22:23], v[22:23], v[222:223], v[218:219] op_sel_hi:[0,1,1] neg_lo:[0,0,1]
	v_pk_fma_f32 v[24:25], v[24:25], v[224:225], v[220:221] op_sel_hi:[0,1,1] neg_lo:[0,0,1]
	v_pk_fma_f32 v[26:27], v[26:27], v[226:227], v[28:29] op_sel_hi:[0,1,1] neg_lo:[0,0,1]
	v_pk_add_f32 v[28:29], v[20:21], v[24:25]
	v_pk_add_f32 v[30:31], v[20:21], v[24:25] neg_lo:[0,1] neg_hi:[0,1]
	v_pk_add_f32 v[32:33], v[22:23], v[26:27]
	v_pk_add_f32 v[34:35], v[22:23], v[26:27] neg_lo:[0,1] neg_hi:[0,1]
	v_pk_add_f32 v[20:21], v[28:29], v[32:33]
	v_pk_add_f32 v[24:25], v[28:29], v[32:33] neg_lo:[0,1] neg_hi:[0,1]
	v_pk_add_f32 v[22:23], v[30:31], v[34:35] op_sel:[0,1] op_sel_hi:[1,0] neg_hi:[0,1]
	v_pk_add_f32 v[26:27], v[30:31], v[34:35] op_sel:[0,1] op_sel_hi:[1,0] neg_lo:[0,1]
	v_pk_mul_f32 v[218:219], v[20:21], v[228:229] op_sel:[1,1] op_sel_hi:[1,0]
	v_pk_mul_f32 v[220:221], v[24:25], v[232:233] op_sel:[1,1] op_sel_hi:[1,0]
	v_pk_mul_f32 v[28:29], v[22:23], v[230:231] op_sel:[1,1] op_sel_hi:[1,0]
	v_pk_mul_f32 v[32:33], v[26:27], v[234:235] op_sel:[1,1] op_sel_hi:[1,0]
	v_pk_fma_f32 v[20:21], v[20:21], v[228:229], v[218:219] op_sel_hi:[0,1,1] neg_lo:[0,0,1]
	v_pk_fma_f32 v[24:25], v[24:25], v[232:233], v[220:221] op_sel_hi:[0,1,1] neg_lo:[0,0,1]
	v_pk_fma_f32 v[22:23], v[22:23], v[230:231], v[28:29] op_sel_hi:[0,1,1] neg_lo:[0,0,1]
	v_pk_fma_f32 v[26:27], v[26:27], v[234:235], v[32:33] op_sel_hi:[0,1,1] neg_lo:[0,0,1]
	s_nop 0
	ds_write_b64 v241, v[20:21]
	ds_write_b64 v243, v[24:25]
	ds_write_b64 v242, v[22:23]
	ds_write_b64 v244, v[26:27]
	ds_read_b64 v[20:21], v241 offset:16384
	ds_read_b64 v[22:23], v242 offset:16384
	ds_read_b64 v[24:25], v243 offset:16384
	ds_read_b64 v[26:27], v244 offset:16384
	s_waitcnt lgkmcnt(0)
; DI float2 twid(float r) { return float2{__builtin_amdgcn_cosf(r), -__builtin_amdgcn_sinf(r)}; }
; DI void bfly_fwd(float2 a0, float2 a1, float2 a2, float2 a3, float r, float2& o0, float2& o1, float2& o2, float2& o3) {
;   float2 t0 = {a0.x + a2.x, a0.y + a2.y}, t1 = {a0.x - a2.x, a0.y - a2.y}, t2 = {a1.x + a3.x, a1.y + a3.y}, t3 = {a1.x - a3.x, a1.y - a3.y};
;   float2 b0 = {t0.x + t2.x, t0.y + t2.y}, b2 = {t0.x - t2.x, t0.y - t2.y}, b1 = {t1.x + t3.y, t1.y - t3.x}, b3 = {t1.x - t3.y, t1.y + t3.x};
;   float2 w1 = twid(r), w2 = cmul(w1, w1), w3 = cmul(w2, w1);
;   o0 = b0; o1 = cmul(b1, w1); o2 = cmul(b2, w2); o3 = cmul(b3, w3);
; }
;   const int Q = 1 << lq; const float invM = 1.f / (float)(4 << lq);
;   for (int bb = tid; bb < NBT * (N / 4); bb += NTHR) { const int b = bb & (N / 4 - 1); float2* z = z0 + (bb / (N / 4)) * N; int j = b & (Q - 1), base = ((b >> lq) << (lq + 2)) + j; float2 o0, o1, o2, o3;
;     bfly_fwd(z[base], z[base + Q], z[base + 2 * Q], z[base + 3 * Q], (float)j * invM, o0, o1, o2, o3);
;     z[base] = o0; z[base + Q] = o1; z[base + 2 * Q] = o2; z[base + 3 * Q] = o3; }
;   __syncthreads();
; }
	v_pk_mul_f32 v[218:219], v[22:23], v[222:223] op_sel:[1,1] op_sel_hi:[1,0]
	v_pk_mul_f32 v[220:221], v[24:25], v[224:225] op_sel:[1,1] op_sel_hi:[1,0]
	v_pk_mul_f32 v[28:29], v[26:27], v[226:227] op_sel:[1,1] op_sel_hi:[1,0]
	v_pk_fma_f32 v[22:23], v[22:23], v[222:223], v[218:219] op_sel_hi:[0,1,1] neg_lo:[0,0,1]
	v_pk_fma_f32 v[24:25], v[24:25], v[224:225], v[220:221] op_sel_hi:[0,1,1] neg_lo:[0,0,1]
	v_pk_fma_f32 v[26:27], v[26:27], v[226:227], v[28:29] op_sel_hi:[0,1,1] neg_lo:[0,0,1]
	v_pk_add_f32 v[28:29], v[20:21], v[24:25]
	v_pk_add_f32 v[30:31], v[20:21], v[24:25] neg_lo:[0,1] neg_hi:[0,1]
	v_pk_add_f32 v[32:33], v[22:23], v[26:27]
	v_pk_add_f32 v[34:35], v[22:23], v[26:27] neg_lo:[0,1] neg_hi:[0,1]
	v_pk_add_f32 v[20:21], v[28:29], v[32:33]
	v_pk_add_f32 v[24:25], v[28:29], v[32:33] neg_lo:[0,1] neg_hi:[0,1]
	v_pk_add_f32 v[22:23], v[30:31], v[34:35] op_sel:[0,1] op_sel_hi:[1,0] neg_hi:[0,1]
	v_pk_add_f32 v[26:27], v[30:31], v[34:35] op_sel:[0,1] op_sel_hi:[1,0] neg_lo:[0,1]
	v_pk_mul_f32 v[218:219], v[20:21], v[228:229] op_sel:[1,1] op_sel_hi:[1,0]
	v_pk_mul_f32 v[220:221], v[24:25], v[232:233] op_sel:[1,1] op_sel_hi:[1,0]
	v_pk_mul_f32 v[28:29], v[22:23], v[230:231] op_sel:[1,1] op_sel_hi:[1,0]
	v_pk_mul_f32 v[32:33], v[26:27], v[234:235] op_sel:[1,1] op_sel_hi:[1,0]
	v_pk_fma_f32 v[20:21], v[20:21], v[228:229], v[218:219] op_sel_hi:[0,1,1] neg_lo:[0,0,1]
	v_pk_fma_f32 v[24:25], v[24:25], v[232:233], v[220:221] op_sel_hi:[0,1,1] neg_lo:[0,0,1]
	v_pk_fma_f32 v[22:23], v[22:23], v[230:231], v[28:29] op_sel_hi:[0,1,1] neg_lo:[0,0,1]
	v_pk_fma_f32 v[26:27], v[26:27], v[234:235], v[32:33] op_sel_hi:[0,1,1] neg_lo:[0,0,1]
	s_nop 0
	ds_write_b64 v241, v[20:21] offset:16384
	ds_write_b64 v243, v[24:25] offset:16384
	ds_write_b64 v242, v[22:23] offset:16384
	ds_write_b64 v244, v[26:27] offset:16384
	ds_read_b64 v[20:21], v241 offset:32768
	ds_read_b64 v[22:23], v242 offset:32768
	ds_read_b64 v[24:25], v243 offset:32768
	ds_read_b64 v[26:27], v244 offset:32768
	s_waitcnt lgkmcnt(0)
	v_pk_mul_f32 v[218:219], v[22:23], v[222:223] op_sel:[1,1] op_sel_hi:[1,0]
	v_pk_mul_f32 v[220:221], v[24:25], v[224:225] op_sel:[1,1] op_sel_hi:[1,0]
	v_pk_mul_f32 v[28:29], v[26:27], v[226:227] op_sel:[1,1] op_sel_hi:[1,0]
	v_pk_fma_f32 v[22:23], v[22:23], v[222:223], v[218:219] op_sel_hi:[0,1,1] neg_lo:[0,0,1]
	v_pk_fma_f32 v[24:25], v[24:25], v[224:225], v[220:221] op_sel_hi:[0,1,1] neg_lo:[0,0,1]
	v_pk_fma_f32 v[26:27], v[26:27], v[226:227], v[28:29] op_sel_hi:[0,1,1] neg_lo:[0,0,1]
	v_pk_add_f32 v[28:29], v[20:21], v[24:25]
	v_pk_add_f32 v[30:31], v[20:21], v[24:25] neg_lo:[0,1] neg_hi:[0,1]
	v_pk_add_f32 v[32:33], v[22:23], v[26:27]
	v_pk_add_f32 v[34:35], v[22:23], v[26:27] neg_lo:[0,1] neg_hi:[0,1]
	v_pk_add_f32 v[20:21], v[28:29], v[32:33]
	v_pk_add_f32 v[24:25], v[28:29], v[32:33] neg_lo:[0,1] neg_hi:[0,1]
	v_pk_add_f32 v[22:23], v[30:31], v[34:35] op_sel:[0,1] op_sel_hi:[1,0] neg_hi:[0,1]
	v_pk_add_f32 v[26:27], v[30:31], v[34:35] op_sel:[0,1] op_sel_hi:[1,0] neg_lo:[0,1]
	v_pk_mul_f32 v[218:219], v[20:21], v[228:229] op_sel:[1,1] op_sel_hi:[1,0]
	v_pk_mul_f32 v[220:221], v[24:25], v[232:233] op_sel:[1,1] op_sel_hi:[1,0]
	v_pk_mul_f32 v[28:29], v[22:23], v[230:231] op_sel:[1,1] op_sel_hi:[1,0]
	v_pk_mul_f32 v[32:33], v[26:27], v[234:235] op_sel:[1,1] op_sel_hi:[1,0]
	v_pk_fma_f32 v[20:21], v[20:21], v[228:229], v[218:219] op_sel_hi:[0,1,1] neg_lo:[0,0,1]
	v_pk_fma_f32 v[24:25], v[24:25], v[232:233], v[220:221] op_sel_hi:[0,1,1] neg_lo:[0,0,1]
	v_pk_fma_f32 v[22:23], v[22:23], v[230:231], v[28:29] op_sel_hi:[0,1,1] neg_lo:[0,0,1]
	v_pk_fma_f32 v[26:27], v[26:27], v[234:235], v[32:33] op_sel_hi:[0,1,1] neg_lo:[0,0,1]
	s_nop 0
	ds_write_b64 v241, v[20:21] offset:32768
	ds_write_b64 v243, v[24:25] offset:32768
	ds_write_b64 v242, v[22:23] offset:32768
	ds_write_b64 v244, v[26:27] offset:32768
	ds_read_b64 v[20:21], v241 offset:49152
	ds_read_b64 v[22:23], v242 offset:49152
	ds_read_b64 v[24:25], v243 offset:49152
	ds_read_b64 v[26:27], v244 offset:49152
	s_waitcnt lgkmcnt(0)
	v_pk_mul_f32 v[218:219], v[22:23], v[222:223] op_sel:[1,1] op_sel_hi:[1,0]
	v_pk_mul_f32 v[220:221], v[24:25], v[224:225] op_sel:[1,1] op_sel_hi:[1,0]
	v_pk_mul_f32 v[28:29], v[26:27], v[226:227] op_sel:[1,1] op_sel_hi:[1,0]
	v_pk_fma_f32 v[22:23], v[22:23], v[222:223], v[218:219] op_sel_hi:[0,1,1] neg_lo:[0,0,1]
	v_pk_fma_f32 v[24:25], v[24:25], v[224:225], v[220:221] op_sel_hi:[0,1,1] neg_lo:[0,0,1]
	v_pk_fma_f32 v[26:27], v[26:27], v[226:227], v[28:29] op_sel_hi:[0,1,1] neg_lo:[0,0,1]
	v_pk_add_f32 v[28:29], v[20:21], v[24:25]
	v_pk_add_f32 v[30:31], v[20:21], v[24:25] neg_lo:[0,1] neg_hi:[0,1]
	v_pk_add_f32 v[32:33], v[22:23], v[26:27]
	v_pk_add_f32 v[34:35], v[22:23], v[26:27] neg_lo:[0,1] neg_hi:[0,1]
	v_pk_add_f32 v[20:21], v[28:29], v[32:33]
	v_pk_add_f32 v[24:25], v[28:29], v[32:33] neg_lo:[0,1] neg_hi:[0,1]
	v_pk_add_f32 v[22:23], v[30:31], v[34:35] op_sel:[0,1] op_sel_hi:[1,0] neg_hi:[0,1]
	v_pk_add_f32 v[26:27], v[30:31], v[34:35] op_sel:[0,1] op_sel_hi:[1,0] neg_lo:[0,1]
	v_pk_mul_f32 v[218:219], v[20:21], v[228:229] op_sel:[1,1] op_sel_hi:[1,0]
	v_pk_mul_f32 v[220:221], v[24:25], v[232:233] op_sel:[1,1] op_sel_hi:[1,0]
	v_pk_mul_f32 v[28:29], v[22:23], v[230:231] op_sel:[1,1] op_sel_hi:[1,0]
	v_pk_mul_f32 v[32:33], v[26:27], v[234:235] op_sel:[1,1] op_sel_hi:[1,0]
	v_pk_fma_f32 v[20:21], v[20:21], v[228:229], v[218:219] op_sel_hi:[0,1,1] neg_lo:[0,0,1]
	v_pk_fma_f32 v[24:25], v[24:25], v[232:233], v[220:221] op_sel_hi:[0,1,1] neg_lo:[0,0,1]
	v_pk_fma_f32 v[22:23], v[22:23], v[230:231], v[28:29] op_sel_hi:[0,1,1] neg_lo:[0,0,1]
	v_pk_fma_f32 v[26:27], v[26:27], v[234:235], v[32:33] op_sel_hi:[0,1,1] neg_lo:[0,0,1]
	s_nop 0
	ds_write_b64 v241, v[20:21] offset:49152
	ds_write_b64 v243, v[24:25] offset:49152
	ds_write_b64 v242, v[22:23] offset:49152
	ds_write_b64 v244, v[26:27] offset:49152
	v_add_u32_e32 v17, 0x4000, v17
	v_add_u32_e32 v19, 0x1000, v18
	v_mov_b32_e32 v18, v19
	s_mov_b64 s[80:81], exec

; DI float2 twid(float r) { return float2{__builtin_amdgcn_cosf(r), -__builtin_amdgcn_sinf(r)}; }
; DI void bfly_fwd(float2 a0, float2 a1, float2 a2, float2 a3, float r, float2& o0, float2& o1, float2& o2, float2& o3) {
;   float2 t0 = {a0.x + a2.x, a0.y + a2.y}, t1 = {a0.x - a2.x, a0.y - a2.y}, t2 = {a1.x + a3.x, a1.y + a3.y}, t3 = {a1.x - a3.x, a1.y - a3.y};
;   float2 b0 = {t0.x + t2.x, t0.y + t2.y}, b2 = {t0.x - t2.x, t0.y - t2.y}, b1 = {t1.x + t3.y, t1.y - t3.x}, b3 = {t1.x - t3.y, t1.y + t3.x};
;   float2 w1 = twid(r), w2 = cmul(w1, w1), w3 = cmul(w2, w1);
;   o0 = b0; o1 = cmul(b1, w1); o2 = cmul(b2, w2); o3 = cmul(b3, w3);
; }
;   const int Q = 1 << lq; const float invM = 1.f / (float)(4 << lq);
;   for (int bb = tid; bb < NBT * (N / 4); bb += NTHR) { const int b = bb & (N / 4 - 1); float2* z = z0 + (bb / (N / 4)) * N; int j = b & (Q - 1), base = ((b >> lq) << (lq + 2)) + j; float2 o0, o1, o2, o3;
;     bfly_fwd(z[base], z[base + Q], z[base + 2 * Q], z[base + 3 * Q], (float)j * invM, o0, o1, o2, o3);
;     z[base] = o0; z[base + Q] = o1; z[base + 2 * Q] = o2; z[base + 3 * Q] = o3; }
;   __syncthreads();
; }
.LBB0_1609:
	v_ashrrev_i32_e32 v4, 31, v3
	v_lshrrev_b32_e32 v4, 21, v4
	v_add_lshl_u32 v4, v3, v4, 5
	v_and_b32_e32 v5, 0x1ffc, v2
	v_and_b32_e32 v4, 0xffff0000, v4
	v_lshlrev_b32_e32 v5, 3, v5
	v_add3_u32 v17, 16, v4, v5
	ds_read_b128 v[4:7], v17
	ds_read_b128 v[8:11], v17 offset:16
	s_waitcnt lgkmcnt(0)
	v_pk_add_f32 v[12:13], v[4:5], v[8:9]
	v_pk_add_f32 v[20:21], v[6:7], v[10:11]
	v_pk_add_f32 v[18:19], v[4:5], v[8:9] neg_lo:[0,1] neg_hi:[0,1]
	v_pk_add_f32 v[22:23], v[6:7], v[10:11] neg_lo:[0,1] neg_hi:[0,1]
	v_pk_add_f32 v[4:5], v[12:13], v[20:21]
	v_pk_add_f32 v[8:9], v[12:13], v[20:21] neg_lo:[0,1] neg_hi:[0,1]
	v_pk_add_f32 v[6:7], v[18:19], v[22:23] op_sel:[0,1] op_sel_hi:[1,0] neg_hi:[0,1]
	v_pk_add_f32 v[10:11], v[18:19], v[22:23] op_sel:[0,1] op_sel_hi:[1,0] neg_lo:[0,1]
	s_nop 0
	ds_write_b128 v17, v[4:7]
	ds_write_b128 v17, v[8:11] offset:16
	ds_read_b128 v[4:7], v17 offset:16384
	ds_read_b128 v[8:11], v17 offset:16400
	s_waitcnt lgkmcnt(0)
	v_pk_add_f32 v[12:13], v[4:5], v[8:9]
	v_pk_add_f32 v[20:21], v[6:7], v[10:11]
	v_pk_add_f32 v[18:19], v[4:5], v[8:9] neg_lo:[0,1] neg_hi:[0,1]
	v_pk_add_f32 v[22:23], v[6:7], v[10:11] neg_lo:[0,1] neg_hi:[0,1]
	v_pk_add_f32 v[4:5], v[12:13], v[20:21]
	v_pk_add_f32 v[8:9], v[12:13], v[20:21] neg_lo:[0,1] neg_hi:[0,1]
	v_pk_add_f32 v[6:7], v[18:19], v[22:23] op_sel:[0,1] op_sel_hi:[1,0] neg_hi:[0,1]
	v_pk_add_f32 v[10:11], v[18:19], v[22:23] op_sel:[0,1] op_sel_hi:[1,0] neg_lo:[0,1]
	s_nop 0
	ds_write_b128 v17, v[4:7] offset:16384
	ds_write_b128 v17, v[8:11] offset:16400
	ds_read_b128 v[4:7], v17 offset:32768
	ds_read_b128 v[8:11], v17 offset:32784
	s_waitcnt lgkmcnt(0)
	v_pk_add_f32 v[12:13], v[4:5], v[8:9]
	v_pk_add_f32 v[20:21], v[6:7], v[10:11]
	v_pk_add_f32 v[18:19], v[4:5], v[8:9] neg_lo:[0,1] neg_hi:[0,1]
	v_pk_add_f32 v[22:23], v[6:7], v[10:11] neg_lo:[0,1] neg_hi:[0,1]
	v_pk_add_f32 v[4:5], v[12:13], v[20:21]
	v_pk_add_f32 v[8:9], v[12:13], v[20:21] neg_lo:[0,1] neg_hi:[0,1]
	v_pk_add_f32 v[6:7], v[18:19], v[22:23] op_sel:[0,1] op_sel_hi:[1,0] neg_hi:[0,1]
	v_pk_add_f32 v[10:11], v[18:19], v[22:23] op_sel:[0,1] op_sel_hi:[1,0] neg_lo:[0,1]
	s_nop 0
	ds_write_b128 v17, v[4:7] offset:32768
	ds_write_b128 v17, v[8:11] offset:32784
	ds_read_b128 v[4:7], v17 offset:49152
	ds_read_b128 v[8:11], v17 offset:49168
	s_waitcnt lgkmcnt(0)
	v_pk_add_f32 v[12:13], v[4:5], v[8:9]
	v_pk_add_f32 v[20:21], v[6:7], v[10:11]
	v_pk_add_f32 v[18:19], v[4:5], v[8:9] neg_lo:[0,1] neg_hi:[0,1]
	v_pk_add_f32 v[22:23], v[6:7], v[10:11] neg_lo:[0,1] neg_hi:[0,1]
	v_pk_add_f32 v[4:5], v[12:13], v[20:21]
	v_pk_add_f32 v[8:9], v[12:13], v[20:21] neg_lo:[0,1] neg_hi:[0,1]
	v_pk_add_f32 v[6:7], v[18:19], v[22:23] op_sel:[0,1] op_sel_hi:[1,0] neg_hi:[0,1]
	v_pk_add_f32 v[10:11], v[18:19], v[22:23] op_sel:[0,1] op_sel_hi:[1,0] neg_lo:[0,1]
	s_nop 0
	ds_write_b128 v17, v[4:7] offset:49152
	ds_write_b128 v17, v[8:11] offset:49168
	v_add_u32_e32 v17, 0x10000, v17
	ds_read_b128 v[4:7], v17
	ds_read_b128 v[8:11], v17 offset:16
	s_waitcnt lgkmcnt(0)
	v_pk_add_f32 v[12:13], v[4:5], v[8:9]
	v_pk_add_f32 v[20:21], v[6:7], v[10:11]
	v_pk_add_f32 v[18:19], v[4:5], v[8:9] neg_lo:[0,1] neg_hi:[0,1]
	v_pk_add_f32 v[22:23], v[6:7], v[10:11] neg_lo:[0,1] neg_hi:[0,1]
	v_pk_add_f32 v[4:5], v[12:13], v[20:21]
	v_pk_add_f32 v[8:9], v[12:13], v[20:21] neg_lo:[0,1] neg_hi:[0,1]
	v_pk_add_f32 v[6:7], v[18:19], v[22:23] op_sel:[0,1] op_sel_hi:[1,0] neg_hi:[0,1]
	v_pk_add_f32 v[10:11], v[18:19], v[22:23] op_sel:[0,1] op_sel_hi:[1,0] neg_lo:[0,1]
	s_nop 0
	ds_write_b128 v17, v[4:7]
	ds_write_b128 v17, v[8:11] offset:16
	ds_read_b128 v[4:7], v17 offset:16384
	ds_read_b128 v[8:11], v17 offset:16400
	s_waitcnt lgkmcnt(0)
	v_pk_add_f32 v[12:13], v[4:5], v[8:9]
	v_pk_add_f32 v[20:21], v[6:7], v[10:11]
	v_pk_add_f32 v[18:19], v[4:5], v[8:9] neg_lo:[0,1] neg_hi:[0,1]
	v_pk_add_f32 v[22:23], v[6:7], v[10:11] neg_lo:[0,1] neg_hi:[0,1]
	v_pk_add_f32 v[4:5], v[12:13], v[20:21]
	v_pk_add_f32 v[8:9], v[12:13], v[20:21] neg_lo:[0,1] neg_hi:[0,1]
	v_pk_add_f32 v[6:7], v[18:19], v[22:23] op_sel:[0,1] op_sel_hi:[1,0] neg_hi:[0,1]
	v_pk_add_f32 v[10:11], v[18:19], v[22:23] op_sel:[0,1] op_sel_hi:[1,0] neg_lo:[0,1]
	s_nop 0
	ds_write_b128 v17, v[4:7] offset:16384
	ds_write_b128 v17, v[8:11] offset:16400
	ds_read_b128 v[4:7], v17 offset:32768
	ds_read_b128 v[8:11], v17 offset:32784
	s_waitcnt lgkmcnt(0)
	v_pk_add_f32 v[12:13], v[4:5], v[8:9]
	v_pk_add_f32 v[20:21], v[6:7], v[10:11]
	v_pk_add_f32 v[18:19], v[4:5], v[8:9] neg_lo:[0,1] neg_hi:[0,1]
	v_pk_add_f32 v[22:23], v[6:7], v[10:11] neg_lo:[0,1] neg_hi:[0,1]
	v_pk_add_f32 v[4:5], v[12:13], v[20:21]
	v_pk_add_f32 v[8:9], v[12:13], v[20:21] neg_lo:[0,1] neg_hi:[0,1]
	v_pk_add_f32 v[6:7], v[18:19], v[22:23] op_sel:[0,1] op_sel_hi:[1,0] neg_hi:[0,1]
	v_pk_add_f32 v[10:11], v[18:19], v[22:23] op_sel:[0,1] op_sel_hi:[1,0] neg_lo:[0,1]
	s_nop 0
	ds_write_b128 v17, v[4:7] offset:32768
	ds_write_b128 v17, v[8:11] offset:32784
	ds_read_b128 v[4:7], v17 offset:49152
	ds_read_b128 v[8:11], v17 offset:49168
	s_waitcnt lgkmcnt(0)
	v_pk_add_f32 v[12:13], v[4:5], v[8:9]
	v_pk_add_f32 v[20:21], v[6:7], v[10:11]
	v_pk_add_f32 v[18:19], v[4:5], v[8:9] neg_lo:[0,1] neg_hi:[0,1]
	v_pk_add_f32 v[22:23], v[6:7], v[10:11] neg_lo:[0,1] neg_hi:[0,1]
	v_pk_add_f32 v[4:5], v[12:13], v[20:21]
	v_pk_add_f32 v[8:9], v[12:13], v[20:21] neg_lo:[0,1] neg_hi:[0,1]
	v_pk_add_f32 v[6:7], v[18:19], v[22:23] op_sel:[0,1] op_sel_hi:[1,0] neg_hi:[0,1]
	v_pk_add_f32 v[10:11], v[18:19], v[22:23] op_sel:[0,1] op_sel_hi:[1,0] neg_lo:[0,1]
	s_nop 0
	ds_write_b128 v17, v[4:7] offset:49152
	ds_write_b128 v17, v[8:11] offset:49168
	v_add_u32_e32 v2, 0x4000, v2
	v_add_u32_e32 v4, 0x1000, v3
	v_mov_b32_e32 v3, v4
	s_mov_b64 s[80:81], exec

; DI float2 twid(float r) { return float2{__builtin_amdgcn_cosf(r), -__builtin_amdgcn_sinf(r)}; }
; DI void bfly_fwd(float2 a0, float2 a1, float2 a2, float2 a3, float r, float2& o0, float2& o1, float2& o2, float2& o3) {
;   float2 t0 = {a0.x + a2.x, a0.y + a2.y}, t1 = {a0.x - a2.x, a0.y - a2.y}, t2 = {a1.x + a3.x, a1.y + a3.y}, t3 = {a1.x - a3.x, a1.y - a3.y};
;   float2 b0 = {t0.x + t2.x, t0.y + t2.y}, b2 = {t0.x - t2.x, t0.y - t2.y}, b1 = {t1.x + t3.y, t1.y - t3.x}, b3 = {t1.x - t3.y, t1.y + t3.x};
;   float2 w1 = twid(r), w2 = cmul(w1, w1), w3 = cmul(w2, w1);
;   o0 = b0; o1 = cmul(b1, w1); o2 = cmul(b2, w2); o3 = cmul(b3, w3);
; }
;   const int Q = 1 << lq; const float invM = 1.f / (float)(4 << lq);
;   for (int bb = tid; bb < NBT * (N / 4); bb += NTHR) { const int b = bb & (N / 4 - 1); float2* z = z0 + (bb / (N / 4)) * N; int j = b & (Q - 1), base = ((b >> lq) << (lq + 2)) + j; float2 o0, o1, o2, o3;
;     bfly_fwd(z[base], z[base + Q], z[base + 2 * Q], z[base + 3 * Q], (float)j * invM, o0, o1, o2, o3);
;     z[base] = o0; z[base + Q] = o1; z[base + 2 * Q] = o2; z[base + 3 * Q] = o3; }
;   __syncthreads();
; }
.LBB0_1615:
	v_ashrrev_i32_e32 v17, 31, v16
	v_lshrrev_b32_e32 v17, 21, v17
	v_add_lshl_u32 v17, v16, v17, 5
	v_and_b32_e32 v17, 0xffff0000, v17
	v_and_b32_e32 v18, 0x1ff0, v15
	v_add_u32_e32 v17, 16, v17
	v_lshlrev_b32_e32 v18, 3, v18
	v_lshlrev_b32_e32 v19, 3, v14
	v_add3_u32 v17, v17, v18, v19
	v_add_u32_e32 v245, v17, v241
	v_add_u32_e32 v246, v17, v242
	v_add_u32_e32 v247, v17, v243
	v_add_u32_e32 v248, v17, v244
	ds_read_b64 v[18:19], v245
	ds_read_b64 v[20:21], v246
	ds_read_b64 v[22:23], v247
	ds_read_b64 v[24:25], v248
	s_waitcnt lgkmcnt(0)
	v_pk_mul_f32 v[220:221], v[18:19], v[224:225] op_sel:[1,1] op_sel_hi:[1,0]
	v_pk_mul_f32 v[222:223], v[20:21], v[226:227] op_sel:[1,1] op_sel_hi:[1,0]
	v_pk_mul_f32 v[26:27], v[22:23], v[228:229] op_sel:[1,1] op_sel_hi:[1,0]
	v_pk_mul_f32 v[28:29], v[24:25], v[230:231] op_sel:[1,1] op_sel_hi:[1,0]
	v_pk_fma_f32 v[18:19], v[18:19], v[224:225], v[220:221] op_sel_hi:[0,1,1] neg_lo:[0,0,1]
	v_pk_fma_f32 v[20:21], v[20:21], v[226:227], v[222:223] op_sel_hi:[0,1,1] neg_lo:[0,0,1]
	v_pk_fma_f32 v[22:23], v[22:23], v[228:229], v[26:27] op_sel_hi:[0,1,1] neg_lo:[0,0,1]
	v_pk_fma_f32 v[24:25], v[24:25], v[230:231], v[28:29] op_sel_hi:[0,1,1] neg_lo:[0,0,1]
	v_pk_add_f32 v[26:27], v[18:19], v[22:23]
	v_pk_add_f32 v[28:29], v[18:19], v[22:23] neg_lo:[0,1] neg_hi:[0,1]
	v_pk_add_f32 v[30:31], v[20:21], v[24:25]
	v_pk_add_f32 v[218:219], v[20:21], v[24:25] neg_lo:[0,1] neg_hi:[0,1]
	v_pk_add_f32 v[18:19], v[26:27], v[30:31]
	v_pk_add_f32 v[22:23], v[26:27], v[30:31] neg_lo:[0,1] neg_hi:[0,1]
	v_pk_add_f32 v[20:21], v[28:29], v[218:219] op_sel:[0,1] op_sel_hi:[1,0] neg_lo:[0,1]
	v_pk_add_f32 v[24:25], v[28:29], v[218:219] op_sel:[0,1] op_sel_hi:[1,0] neg_hi:[0,1]
	v_pk_mul_f32 v[220:221], v[18:19], v[232:233] op_sel:[1,1] op_sel_hi:[1,0]
	v_pk_mul_f32 v[222:223], v[22:23], v[236:237] op_sel:[1,1] op_sel_hi:[1,0]
	v_pk_mul_f32 v[26:27], v[20:21], v[234:235] op_sel:[1,1] op_sel_hi:[1,0]
	v_pk_mul_f32 v[30:31], v[24:25], v[238:239] op_sel:[1,1] op_sel_hi:[1,0]
	v_pk_fma_f32 v[18:19], v[18:19], v[232:233], v[220:221] op_sel_hi:[0,1,1] neg_lo:[0,0,1]
	v_pk_fma_f32 v[22:23], v[22:23], v[236:237], v[222:223] op_sel_hi:[0,1,1] neg_lo:[0,0,1]
	v_pk_fma_f32 v[20:21], v[20:21], v[234:235], v[26:27] op_sel_hi:[0,1,1] neg_lo:[0,0,1]
	v_pk_fma_f32 v[24:25], v[24:25], v[238:239], v[30:31] op_sel_hi:[0,1,1] neg_lo:[0,0,1]
	s_nop 0
	ds_write_b64 v245, v[18:19]
	ds_write_b64 v247, v[22:23]
	ds_write_b64 v246, v[20:21]
	ds_write_b64 v248, v[24:25]
	ds_read_b64 v[18:19], v245 offset:16384
	ds_read_b64 v[20:21], v246 offset:16384
	ds_read_b64 v[22:23], v247 offset:16384
	ds_read_b64 v[24:25], v248 offset:16384
	s_waitcnt lgkmcnt(0)
	v_pk_mul_f32 v[220:221], v[18:19], v[224:225] op_sel:[1,1] op_sel_hi:[1,0]
	v_pk_mul_f32 v[222:223], v[20:21], v[226:227] op_sel:[1,1] op_sel_hi:[1,0]
	v_pk_mul_f32 v[26:27], v[22:23], v[228:229] op_sel:[1,1] op_sel_hi:[1,0]
	v_pk_mul_f32 v[28:29], v[24:25], v[230:231] op_sel:[1,1] op_sel_hi:[1,0]
	v_pk_fma_f32 v[18:19], v[18:19], v[224:225], v[220:221] op_sel_hi:[0,1,1] neg_lo:[0,0,1]
	v_pk_fma_f32 v[20:21], v[20:21], v[226:227], v[222:223] op_sel_hi:[0,1,1] neg_lo:[0,0,1]
	v_pk_fma_f32 v[22:23], v[22:23], v[228:229], v[26:27] op_sel_hi:[0,1,1] neg_lo:[0,0,1]
	v_pk_fma_f32 v[24:25], v[24:25], v[230:231], v[28:29] op_sel_hi:[0,1,1] neg_lo:[0,0,1]
	v_pk_add_f32 v[26:27], v[18:19], v[22:23]
	v_pk_add_f32 v[28:29], v[18:19], v[22:23] neg_lo:[0,1] neg_hi:[0,1]
	v_pk_add_f32 v[30:31], v[20:21], v[24:25]
	v_pk_add_f32 v[218:219], v[20:21], v[24:25] neg_lo:[0,1] neg_hi:[0,1]
	v_pk_add_f32 v[18:19], v[26:27], v[30:31]
	v_pk_add_f32 v[22:23], v[26:27], v[30:31] neg_lo:[0,1] neg_hi:[0,1]
	v_pk_add_f32 v[20:21], v[28:29], v[218:219] op_sel:[0,1] op_sel_hi:[1,0] neg_lo:[0,1]
	v_pk_add_f32 v[24:25], v[28:29], v[218:219] op_sel:[0,1] op_sel_hi:[1,0] neg_hi:[0,1]
	v_pk_mul_f32 v[220:221], v[18:19], v[232:233] op_sel:[1,1] op_sel_hi:[1,0]
	v_pk_mul_f32 v[222:223], v[22:23], v[236:237] op_sel:[1,1] op_sel_hi:[1,0]
	v_pk_mul_f32 v[26:27], v[20:21], v[234:235] op_sel:[1,1] op_sel_hi:[1,0]
	v_pk_mul_f32 v[30:31], v[24:25], v[238:239] op_sel:[1,1] op_sel_hi:[1,0]
	v_pk_fma_f32 v[18:19], v[18:19], v[232:233], v[220:221] op_sel_hi:[0,1,1] neg_lo:[0,0,1]
	v_pk_fma_f32 v[22:23], v[22:23], v[236:237], v[222:223] op_sel_hi:[0,1,1] neg_lo:[0,0,1]
	v_pk_fma_f32 v[20:21], v[20:21], v[234:235], v[26:27] op_sel_hi:[0,1,1] neg_lo:[0,0,1]
	v_pk_fma_f32 v[24:25], v[24:25], v[238:239], v[30:31] op_sel_hi:[0,1,1] neg_lo:[0,0,1]
	s_nop 0
	ds_write_b64 v245, v[18:19] offset:16384
	ds_write_b64 v247, v[22:23] offset:16384
	ds_write_b64 v246, v[20:21] offset:16384
	ds_write_b64 v248, v[24:25] offset:16384
	ds_read_b64 v[18:19], v245 offset:32768
	ds_read_b64 v[20:21], v246 offset:32768
	ds_read_b64 v[22:23], v247 offset:32768
	ds_read_b64 v[24:25], v248 offset:32768
	s_waitcnt lgkmcnt(0)
; DI float2 twid(float r) { return float2{__builtin_amdgcn_cosf(r), -__builtin_amdgcn_sinf(r)}; }
; DI void bfly_fwd(float2 a0, float2 a1, float2 a2, float2 a3, float r, float2& o0, float2& o1, float2& o2, float2& o3) {
;   float2 t0 = {a0.x + a2.x, a0.y + a2.y}, t1 = {a0.x - a2.x, a0.y - a2.y}, t2 = {a1.x + a3.x, a1.y + a3.y}, t3 = {a1.x - a3.x, a1.y - a3.y};
;   float2 b0 = {t0.x + t2.x, t0.y + t2.y}, b2 = {t0.x - t2.x, t0.y - t2.y}, b1 = {t1.x + t3.y, t1.y - t3.x}, b3 = {t1.x - t3.y, t1.y + t3.x};
;   float2 w1 = twid(r), w2 = cmul(w1, w1), w3 = cmul(w2, w1);
;   o0 = b0; o1 = cmul(b1, w1); o2 = cmul(b2, w2); o3 = cmul(b3, w3);
; }
;   const int Q = 1 << lq; const float invM = 1.f / (float)(4 << lq);
;   for (int bb = tid; bb < NBT * (N / 4); bb += NTHR) { const int b = bb & (N / 4 - 1); float2* z = z0 + (bb / (N / 4)) * N; int j = b & (Q - 1), base = ((b >> lq) << (lq + 2)) + j; float2 o0, o1, o2, o3;
;     bfly_fwd(z[base], z[base + Q], z[base + 2 * Q], z[base + 3 * Q], (float)j * invM, o0, o1, o2, o3);
;     z[base] = o0; z[base + Q] = o1; z[base + 2 * Q] = o2; z[base + 3 * Q] = o3; }
;   __syncthreads();
; }
	v_pk_mul_f32 v[220:221], v[18:19], v[224:225] op_sel:[1,1] op_sel_hi:[1,0]
	v_pk_mul_f32 v[222:223], v[20:21], v[226:227] op_sel:[1,1] op_sel_hi:[1,0]
	v_pk_mul_f32 v[26:27], v[22:23], v[228:229] op_sel:[1,1] op_sel_hi:[1,0]
	v_pk_mul_f32 v[28:29], v[24:25], v[230:231] op_sel:[1,1] op_sel_hi:[1,0]
	v_pk_fma_f32 v[18:19], v[18:19], v[224:225], v[220:221] op_sel_hi:[0,1,1] neg_lo:[0,0,1]
	v_pk_fma_f32 v[20:21], v[20:21], v[226:227], v[222:223] op_sel_hi:[0,1,1] neg_lo:[0,0,1]
	v_pk_fma_f32 v[22:23], v[22:23], v[228:229], v[26:27] op_sel_hi:[0,1,1] neg_lo:[0,0,1]
	v_pk_fma_f32 v[24:25], v[24:25], v[230:231], v[28:29] op_sel_hi:[0,1,1] neg_lo:[0,0,1]
	v_pk_add_f32 v[26:27], v[18:19], v[22:23]
	v_pk_add_f32 v[28:29], v[18:19], v[22:23] neg_lo:[0,1] neg_hi:[0,1]
	v_pk_add_f32 v[30:31], v[20:21], v[24:25]
	v_pk_add_f32 v[218:219], v[20:21], v[24:25] neg_lo:[0,1] neg_hi:[0,1]
	v_pk_add_f32 v[18:19], v[26:27], v[30:31]
	v_pk_add_f32 v[22:23], v[26:27], v[30:31] neg_lo:[0,1] neg_hi:[0,1]
	v_pk_add_f32 v[20:21], v[28:29], v[218:219] op_sel:[0,1] op_sel_hi:[1,0] neg_lo:[0,1]
	v_pk_add_f32 v[24:25], v[28:29], v[218:219] op_sel:[0,1] op_sel_hi:[1,0] neg_hi:[0,1]
	v_pk_mul_f32 v[220:221], v[18:19], v[232:233] op_sel:[1,1] op_sel_hi:[1,0]
	v_pk_mul_f32 v[222:223], v[22:23], v[236:237] op_sel:[1,1] op_sel_hi:[1,0]
	v_pk_mul_f32 v[26:27], v[20:21], v[234:235] op_sel:[1,1] op_sel_hi:[1,0]
	v_pk_mul_f32 v[30:31], v[24:25], v[238:239] op_sel:[1,1] op_sel_hi:[1,0]
	v_pk_fma_f32 v[18:19], v[18:19], v[232:233], v[220:221] op_sel_hi:[0,1,1] neg_lo:[0,0,1]
	v_pk_fma_f32 v[22:23], v[22:23], v[236:237], v[222:223] op_sel_hi:[0,1,1] neg_lo:[0,0,1]
	v_pk_fma_f32 v[20:21], v[20:21], v[234:235], v[26:27] op_sel_hi:[0,1,1] neg_lo:[0,0,1]
	v_pk_fma_f32 v[24:25], v[24:25], v[238:239], v[30:31] op_sel_hi:[0,1,1] neg_lo:[0,0,1]
	s_nop 0
	ds_write_b64 v245, v[18:19] offset:32768
	ds_write_b64 v247, v[22:23] offset:32768
	ds_write_b64 v246, v[20:21] offset:32768
	ds_write_b64 v248, v[24:25] offset:32768
	ds_read_b64 v[18:19], v245 offset:49152
	ds_read_b64 v[20:21], v246 offset:49152
	ds_read_b64 v[22:23], v247 offset:49152
	ds_read_b64 v[24:25], v248 offset:49152
	s_waitcnt lgkmcnt(0)
	v_pk_mul_f32 v[220:221], v[18:19], v[224:225] op_sel:[1,1] op_sel_hi:[1,0]
	v_pk_mul_f32 v[222:223], v[20:21], v[226:227] op_sel:[1,1] op_sel_hi:[1,0]
	v_pk_mul_f32 v[26:27], v[22:23], v[228:229] op_sel:[1,1] op_sel_hi:[1,0]
	v_pk_mul_f32 v[28:29], v[24:25], v[230:231] op_sel:[1,1] op_sel_hi:[1,0]
	v_pk_fma_f32 v[18:19], v[18:19], v[224:225], v[220:221] op_sel_hi:[0,1,1] neg_lo:[0,0,1]
	v_pk_fma_f32 v[20:21], v[20:21], v[226:227], v[222:223] op_sel_hi:[0,1,1] neg_lo:[0,0,1]
	v_pk_fma_f32 v[22:23], v[22:23], v[228:229], v[26:27] op_sel_hi:[0,1,1] neg_lo:[0,0,1]
	v_pk_fma_f32 v[24:25], v[24:25], v[230:231], v[28:29] op_sel_hi:[0,1,1] neg_lo:[0,0,1]
	v_pk_add_f32 v[26:27], v[18:19], v[22:23]
	v_pk_add_f32 v[28:29], v[18:19], v[22:23] neg_lo:[0,1] neg_hi:[0,1]
	v_pk_add_f32 v[30:31], v[20:21], v[24:25]
	v_pk_add_f32 v[218:219], v[20:21], v[24:25] neg_lo:[0,1] neg_hi:[0,1]
	v_pk_add_f32 v[18:19], v[26:27], v[30:31]
	v_pk_add_f32 v[22:23], v[26:27], v[30:31] neg_lo:[0,1] neg_hi:[0,1]
	v_pk_add_f32 v[20:21], v[28:29], v[218:219] op_sel:[0,1] op_sel_hi:[1,0] neg_lo:[0,1]
	v_pk_add_f32 v[24:25], v[28:29], v[218:219] op_sel:[0,1] op_sel_hi:[1,0] neg_hi:[0,1]
	v_pk_mul_f32 v[220:221], v[18:19], v[232:233] op_sel:[1,1] op_sel_hi:[1,0]
	v_pk_mul_f32 v[222:223], v[22:23], v[236:237] op_sel:[1,1] op_sel_hi:[1,0]
	v_pk_mul_f32 v[26:27], v[20:21], v[234:235] op_sel:[1,1] op_sel_hi:[1,0]
	v_pk_mul_f32 v[30:31], v[24:25], v[238:239] op_sel:[1,1] op_sel_hi:[1,0]
	v_pk_fma_f32 v[18:19], v[18:19], v[232:233], v[220:221] op_sel_hi:[0,1,1] neg_lo:[0,0,1]
	v_pk_fma_f32 v[22:23], v[22:23], v[236:237], v[222:223] op_sel_hi:[0,1,1] neg_lo:[0,0,1]
	v_pk_fma_f32 v[20:21], v[20:21], v[234:235], v[26:27] op_sel_hi:[0,1,1] neg_lo:[0,0,1]
	v_pk_fma_f32 v[24:25], v[24:25], v[238:239], v[30:31] op_sel_hi:[0,1,1] neg_lo:[0,0,1]
	s_nop 0
	ds_write_b64 v245, v[18:19] offset:49152
	ds_write_b64 v247, v[22:23] offset:49152
	ds_write_b64 v246, v[20:21] offset:49152
	ds_write_b64 v248, v[24:25] offset:49152
	v_add_u32_e32 v245, 0x10000, v245
	v_add_u32_e32 v246, 0x10000, v246
	v_add_u32_e32 v247, 0x10000, v247
	v_add_u32_e32 v248, 0x10000, v248
	ds_read_b64 v[18:19], v245
	ds_read_b64 v[20:21], v246
	ds_read_b64 v[22:23], v247
	ds_read_b64 v[24:25], v248
	s_waitcnt lgkmcnt(0)
	v_pk_mul_f32 v[220:221], v[18:19], v[224:225] op_sel:[1,1] op_sel_hi:[1,0]
	v_pk_mul_f32 v[222:223], v[20:21], v[226:227] op_sel:[1,1] op_sel_hi:[1,0]
	v_pk_mul_f32 v[26:27], v[22:23], v[228:229] op_sel:[1,1] op_sel_hi:[1,0]
	v_pk_mul_f32 v[28:29], v[24:25], v[230:231] op_sel:[1,1] op_sel_hi:[1,0]
	v_pk_fma_f32 v[18:19], v[18:19], v[224:225], v[220:221] op_sel_hi:[0,1,1] neg_lo:[0,0,1]
	v_pk_fma_f32 v[20:21], v[20:21], v[226:227], v[222:223] op_sel_hi:[0,1,1] neg_lo:[0,0,1]
	v_pk_fma_f32 v[22:23], v[22:23], v[228:229], v[26:27] op_sel_hi:[0,1,1] neg_lo:[0,0,1]
	v_pk_fma_f32 v[24:25], v[24:25], v[230:231], v[28:29] op_sel_hi:[0,1,1] neg_lo:[0,0,1]
	v_pk_add_f32 v[26:27], v[18:19], v[22:23]
	v_pk_add_f32 v[28:29], v[18:19], v[22:23] neg_lo:[0,1] neg_hi:[0,1]
	v_pk_add_f32 v[30:31], v[20:21], v[24:25]
	v_pk_add_f32 v[218:219], v[20:21], v[24:25] neg_lo:[0,1] neg_hi:[0,1]
	v_pk_add_f32 v[18:19], v[26:27], v[30:31]
	v_pk_add_f32 v[22:23], v[26:27], v[30:31] neg_lo:[0,1] neg_hi:[0,1]
	v_pk_add_f32 v[20:21], v[28:29], v[218:219] op_sel:[0,1] op_sel_hi:[1,0] neg_lo:[0,1]
	v_pk_add_f32 v[24:25], v[28:29], v[218:219] op_sel:[0,1] op_sel_hi:[1,0] neg_hi:[0,1]
	v_pk_mul_f32 v[220:221], v[18:19], v[232:233] op_sel:[1,1] op_sel_hi:[1,0]
	v_pk_mul_f32 v[222:223], v[22:23], v[236:237] op_sel:[1,1] op_sel_hi:[1,0]
	v_pk_mul_f32 v[26:27], v[20:21], v[234:235] op_sel:[1,1] op_sel_hi:[1,0]
	v_pk_mul_f32 v[30:31], v[24:25], v[238:239] op_sel:[1,1] op_sel_hi:[1,0]
	v_pk_fma_f32 v[18:19], v[18:19], v[232:233], v[220:221] op_sel_hi:[0,1,1] neg_lo:[0,0,1]
	v_pk_fma_f32 v[22:23], v[22:23], v[236:237], v[222:223] op_sel_hi:[0,1,1] neg_lo:[0,0,1]
	v_pk_fma_f32 v[20:21], v[20:21], v[234:235], v[26:27] op_sel_hi:[0,1,1] neg_lo:[0,0,1]
	v_pk_fma_f32 v[24:25], v[24:25], v[238:239], v[30:31] op_sel_hi:[0,1,1] neg_lo:[0,0,1]
	s_nop 0
	ds_write_b64 v245, v[18:19]
	ds_write_b64 v247, v[22:23]
	ds_write_b64 v246, v[20:21]
	ds_write_b64 v248, v[24:25]
	ds_read_b64 v[18:19], v245 offset:16384
	ds_read_b64 v[20:21], v246 offset:16384
	ds_read_b64 v[22:23], v247 offset:16384
	ds_read_b64 v[24:25], v248 offset:16384
	s_waitcnt lgkmcnt(0)
; DI float2 twid(float r) { return float2{__builtin_amdgcn_cosf(r), -__builtin_amdgcn_sinf(r)}; }
; DI void bfly_fwd(float2 a0, float2 a1, float2 a2, float2 a3, float r, float2& o0, float2& o1, float2& o2, float2& o3) {
;   float2 t0 = {a0.x + a2.x, a0.y + a2.y}, t1 = {a0.x - a2.x, a0.y - a2.y}, t2 = {a1.x + a3.x, a1.y + a3.y}, t3 = {a1.x - a3.x, a1.y - a3.y};
;   float2 b0 = {t0.x + t2.x, t0.y + t2.y}, b2 = {t0.x - t2.x, t0.y - t2.y}, b1 = {t1.x + t3.y, t1.y - t3.x}, b3 = {t1.x - t3.y, t1.y + t3.x};
;   float2 w1 = twid(r), w2 = cmul(w1, w1), w3 = cmul(w2, w1);
;   o0 = b0; o1 = cmul(b1, w1); o2 = cmul(b2, w2); o3 = cmul(b3, w3);
; }
;   const int Q = 1 << lq; const float invM = 1.f / (float)(4 << lq);
;   for (int bb = tid; bb < NBT * (N / 4); bb += NTHR) { const int b = bb & (N / 4 - 1); float2* z = z0 + (bb / (N / 4)) * N; int j = b & (Q - 1), base = ((b >> lq) << (lq + 2)) + j; float2 o0, o1, o2, o3;
;     bfly_fwd(z[base], z[base + Q], z[base + 2 * Q], z[base + 3 * Q], (float)j * invM, o0, o1, o2, o3);
;     z[base] = o0; z[base + Q] = o1; z[base + 2 * Q] = o2; z[base + 3 * Q] = o3; }
;   __syncthreads();
; }
	v_pk_mul_f32 v[220:221], v[18:19], v[224:225] op_sel:[1,1] op_sel_hi:[1,0]
	v_pk_mul_f32 v[222:223], v[20:21], v[226:227] op_sel:[1,1] op_sel_hi:[1,0]
	v_pk_mul_f32 v[26:27], v[22:23], v[228:229] op_sel:[1,1] op_sel_hi:[1,0]
	v_pk_mul_f32 v[28:29], v[24:25], v[230:231] op_sel:[1,1] op_sel_hi:[1,0]
	v_pk_fma_f32 v[18:19], v[18:19], v[224:225], v[220:221] op_sel_hi:[0,1,1] neg_lo:[0,0,1]
	v_pk_fma_f32 v[20:21], v[20:21], v[226:227], v[222:223] op_sel_hi:[0,1,1] neg_lo:[0,0,1]
	v_pk_fma_f32 v[22:23], v[22:23], v[228:229], v[26:27] op_sel_hi:[0,1,1] neg_lo:[0,0,1]
	v_pk_fma_f32 v[24:25], v[24:25], v[230:231], v[28:29] op_sel_hi:[0,1,1] neg_lo:[0,0,1]
	v_pk_add_f32 v[26:27], v[18:19], v[22:23]
	v_pk_add_f32 v[28:29], v[18:19], v[22:23] neg_lo:[0,1] neg_hi:[0,1]
	v_pk_add_f32 v[30:31], v[20:21], v[24:25]
	v_pk_add_f32 v[218:219], v[20:21], v[24:25] neg_lo:[0,1] neg_hi:[0,1]
	v_pk_add_f32 v[18:19], v[26:27], v[30:31]
	v_pk_add_f32 v[22:23], v[26:27], v[30:31] neg_lo:[0,1] neg_hi:[0,1]
	v_pk_add_f32 v[20:21], v[28:29], v[218:219] op_sel:[0,1] op_sel_hi:[1,0] neg_lo:[0,1]
	v_pk_add_f32 v[24:25], v[28:29], v[218:219] op_sel:[0,1] op_sel_hi:[1,0] neg_hi:[0,1]
	v_pk_mul_f32 v[220:221], v[18:19], v[232:233] op_sel:[1,1] op_sel_hi:[1,0]
	v_pk_mul_f32 v[222:223], v[22:23], v[236:237] op_sel:[1,1] op_sel_hi:[1,0]
	v_pk_mul_f32 v[26:27], v[20:21], v[234:235] op_sel:[1,1] op_sel_hi:[1,0]
	v_pk_mul_f32 v[30:31], v[24:25], v[238:239] op_sel:[1,1] op_sel_hi:[1,0]
	v_pk_fma_f32 v[18:19], v[18:19], v[232:233], v[220:221] op_sel_hi:[0,1,1] neg_lo:[0,0,1]
	v_pk_fma_f32 v[22:23], v[22:23], v[236:237], v[222:223] op_sel_hi:[0,1,1] neg_lo:[0,0,1]
	v_pk_fma_f32 v[20:21], v[20:21], v[234:235], v[26:27] op_sel_hi:[0,1,1] neg_lo:[0,0,1]
	v_pk_fma_f32 v[24:25], v[24:25], v[238:239], v[30:31] op_sel_hi:[0,1,1] neg_lo:[0,0,1]
	s_nop 0
	ds_write_b64 v245, v[18:19] offset:16384
	ds_write_b64 v247, v[22:23] offset:16384
	ds_write_b64 v246, v[20:21] offset:16384
	ds_write_b64 v248, v[24:25] offset:16384
	ds_read_b64 v[18:19], v245 offset:32768
	ds_read_b64 v[20:21], v246 offset:32768
	ds_read_b64 v[22:23], v247 offset:32768
	ds_read_b64 v[24:25], v248 offset:32768
	s_waitcnt lgkmcnt(0)
	v_pk_mul_f32 v[220:221], v[18:19], v[224:225] op_sel:[1,1] op_sel_hi:[1,0]
	v_pk_mul_f32 v[222:223], v[20:21], v[226:227] op_sel:[1,1] op_sel_hi:[1,0]
	v_pk_mul_f32 v[26:27], v[22:23], v[228:229] op_sel:[1,1] op_sel_hi:[1,0]
	v_pk_mul_f32 v[28:29], v[24:25], v[230:231] op_sel:[1,1] op_sel_hi:[1,0]
	v_pk_fma_f32 v[18:19], v[18:19], v[224:225], v[220:221] op_sel_hi:[0,1,1] neg_lo:[0,0,1]
	v_pk_fma_f32 v[20:21], v[20:21], v[226:227], v[222:223] op_sel_hi:[0,1,1] neg_lo:[0,0,1]
	v_pk_fma_f32 v[22:23], v[22:23], v[228:229], v[26:27] op_sel_hi:[0,1,1] neg_lo:[0,0,1]
	v_pk_fma_f32 v[24:25], v[24:25], v[230:231], v[28:29] op_sel_hi:[0,1,1] neg_lo:[0,0,1]
	v_pk_add_f32 v[26:27], v[18:19], v[22:23]
	v_pk_add_f32 v[28:29], v[18:19], v[22:23] neg_lo:[0,1] neg_hi:[0,1]
	v_pk_add_f32 v[30:31], v[20:21], v[24:25]
	v_pk_add_f32 v[218:219], v[20:21], v[24:25] neg_lo:[0,1] neg_hi:[0,1]
	v_pk_add_f32 v[18:19], v[26:27], v[30:31]
	v_pk_add_f32 v[22:23], v[26:27], v[30:31] neg_lo:[0,1] neg_hi:[0,1]
	v_pk_add_f32 v[20:21], v[28:29], v[218:219] op_sel:[0,1] op_sel_hi:[1,0] neg_lo:[0,1]
	v_pk_add_f32 v[24:25], v[28:29], v[218:219] op_sel:[0,1] op_sel_hi:[1,0] neg_hi:[0,1]
	v_pk_mul_f32 v[220:221], v[18:19], v[232:233] op_sel:[1,1] op_sel_hi:[1,0]
	v_pk_mul_f32 v[222:223], v[22:23], v[236:237] op_sel:[1,1] op_sel_hi:[1,0]
	v_pk_mul_f32 v[26:27], v[20:21], v[234:235] op_sel:[1,1] op_sel_hi:[1,0]
	v_pk_mul_f32 v[30:31], v[24:25], v[238:239] op_sel:[1,1] op_sel_hi:[1,0]
	v_pk_fma_f32 v[18:19], v[18:19], v[232:233], v[220:221] op_sel_hi:[0,1,1] neg_lo:[0,0,1]
	v_pk_fma_f32 v[22:23], v[22:23], v[236:237], v[222:223] op_sel_hi:[0,1,1] neg_lo:[0,0,1]
	v_pk_fma_f32 v[20:21], v[20:21], v[234:235], v[26:27] op_sel_hi:[0,1,1] neg_lo:[0,0,1]
	v_pk_fma_f32 v[24:25], v[24:25], v[238:239], v[30:31] op_sel_hi:[0,1,1] neg_lo:[0,0,1]
	s_nop 0
	ds_write_b64 v245, v[18:19] offset:32768
	ds_write_b64 v247, v[22:23] offset:32768
	ds_write_b64 v246, v[20:21] offset:32768
	ds_write_b64 v248, v[24:25] offset:32768
	ds_read_b64 v[18:19], v245 offset:49152
	ds_read_b64 v[20:21], v246 offset:49152
	ds_read_b64 v[22:23], v247 offset:49152
	ds_read_b64 v[24:25], v248 offset:49152
	s_waitcnt lgkmcnt(0)
	v_pk_mul_f32 v[220:221], v[18:19], v[224:225] op_sel:[1,1] op_sel_hi:[1,0]
	v_pk_mul_f32 v[222:223], v[20:21], v[226:227] op_sel:[1,1] op_sel_hi:[1,0]
	v_pk_mul_f32 v[26:27], v[22:23], v[228:229] op_sel:[1,1] op_sel_hi:[1,0]
	v_pk_mul_f32 v[28:29], v[24:25], v[230:231] op_sel:[1,1] op_sel_hi:[1,0]
	v_pk_fma_f32 v[18:19], v[18:19], v[224:225], v[220:221] op_sel_hi:[0,1,1] neg_lo:[0,0,1]
	v_pk_fma_f32 v[20:21], v[20:21], v[226:227], v[222:223] op_sel_hi:[0,1,1] neg_lo:[0,0,1]
	v_pk_fma_f32 v[22:23], v[22:23], v[228:229], v[26:27] op_sel_hi:[0,1,1] neg_lo:[0,0,1]
	v_pk_fma_f32 v[24:25], v[24:25], v[230:231], v[28:29] op_sel_hi:[0,1,1] neg_lo:[0,0,1]
	v_pk_add_f32 v[26:27], v[18:19], v[22:23]
	v_pk_add_f32 v[28:29], v[18:19], v[22:23] neg_lo:[0,1] neg_hi:[0,1]
	v_pk_add_f32 v[30:31], v[20:21], v[24:25]
	v_pk_add_f32 v[218:219], v[20:21], v[24:25] neg_lo:[0,1] neg_hi:[0,1]
	v_pk_add_f32 v[18:19], v[26:27], v[30:31]
	v_pk_add_f32 v[22:23], v[26:27], v[30:31] neg_lo:[0,1] neg_hi:[0,1]
	v_pk_add_f32 v[20:21], v[28:29], v[218:219] op_sel:[0,1] op_sel_hi:[1,0] neg_lo:[0,1]
	v_pk_add_f32 v[24:25], v[28:29], v[218:219] op_sel:[0,1] op_sel_hi:[1,0] neg_hi:[0,1]
	v_pk_mul_f32 v[220:221], v[18:19], v[232:233] op_sel:[1,1] op_sel_hi:[1,0]
	v_pk_mul_f32 v[222:223], v[22:23], v[236:237] op_sel:[1,1] op_sel_hi:[1,0]
	v_pk_mul_f32 v[26:27], v[20:21], v[234:235] op_sel:[1,1] op_sel_hi:[1,0]
	v_pk_mul_f32 v[30:31], v[24:25], v[238:239] op_sel:[1,1] op_sel_hi:[1,0]
	v_pk_fma_f32 v[18:19], v[18:19], v[232:233], v[220:221] op_sel_hi:[0,1,1] neg_lo:[0,0,1]
	v_pk_fma_f32 v[22:23], v[22:23], v[236:237], v[222:223] op_sel_hi:[0,1,1] neg_lo:[0,0,1]
	v_pk_fma_f32 v[20:21], v[20:21], v[234:235], v[26:27] op_sel_hi:[0,1,1] neg_lo:[0,0,1]
	v_pk_fma_f32 v[24:25], v[24:25], v[238:239], v[30:31] op_sel_hi:[0,1,1] neg_lo:[0,0,1]
	s_nop 0
	ds_write_b64 v245, v[18:19] offset:49152
	ds_write_b64 v247, v[22:23] offset:49152
	ds_write_b64 v246, v[20:21] offset:49152
	ds_write_b64 v248, v[24:25] offset:49152
	v_add_u32_e32 v15, 0x4000, v15
	v_add_u32_e32 v17, 0x1000, v16
	v_mov_b32_e32 v16, v17
	s_mov_b64 s[80:81], exec

; DI float2 twid(float r) { return float2{__builtin_amdgcn_cosf(r), -__builtin_amdgcn_sinf(r)}; }
; DI void bfly_inv(float2 s0, float2 s1, float2 s2, float2 s3, float r, float2& o0, float2& o1, float2& o2, float2& o3) {
;   float2 w1 = twid(r), w2 = cmul(w1, w1), w3 = cmul(w2, w1);
;   float2 c0 = s0, c1 = cmulc(s1, w1), c2 = cmulc(s2, w2), c3 = cmulc(s3, w3);
;   float2 t0 = {c0.x + c2.x, c0.y + c2.y}, t1 = {c0.x - c2.x, c0.y - c2.y}, t2 = {c1.x + c3.x, c1.y + c3.y}, t3 = {c1.x - c3.x, c1.y - c3.y};
;   o0 = float2{t0.x + t2.x, t0.y + t2.y}; o2 = float2{t0.x - t2.x, t0.y - t2.y}; o1 = float2{t1.x - t3.y, t1.y + t3.x}; o3 = float2{t1.x + t3.y, t1.y - t3.x};
; }
;   const int Q = 1 << lq; const float invM = 1.f / (float)(4 << lq);
;   for (int bb = tid; bb < NBT * (N / 4); bb += NTHR) { const int b = bb & (N / 4 - 1); float2* z = z0 + (bb / (N / 4)) * N; int j = b & (Q - 1), base = ((b >> lq) << (lq + 2)) + j; float2 o0, o1, o2, o3;
;     bfly_inv(z[base], z[base + Q], z[base + 2 * Q], z[base + 3 * Q], (float)j * invM, o0, o1, o2, o3);
;     z[base] = o0; z[base + Q] = o1; z[base + 2 * Q] = o2; z[base + 3 * Q] = o3; }
;   __syncthreads();
; }
.LBB0_1638:
	v_ashrrev_i32_e32 v21, 31, v20
	v_lshrrev_b32_e32 v21, 20, v21
	v_add_lshl_u32 v21, v20, v21, 5
	v_and_b32_e32 v21, 0xfffe0000, v21
	v_and_b32_e32 v22, 0x3ff0, v19
	v_add_u32_e32 v21, 16, v21
	v_lshlrev_b32_e32 v22, 3, v22
	v_lshlrev_b32_e32 v23, 3, v16
	v_add3_u32 v21, v21, v22, v23
	v_add_u32_e32 v241, v21, v236
	v_add_u32_e32 v242, v21, v237
	v_add_u32_e32 v243, v21, v238
	v_add_u32_e32 v244, v21, v239
	ds_read_b64 v[22:23], v241
	ds_read_b64 v[24:25], v242
	ds_read_b64 v[26:27], v243
	ds_read_b64 v[28:29], v244
	s_waitcnt lgkmcnt(0)
	v_pk_mul_f32 v[218:219], v[24:25], v[222:223] op_sel:[1,1] op_sel_hi:[1,0]
	v_pk_mul_f32 v[220:221], v[26:27], v[224:225] op_sel:[1,1] op_sel_hi:[1,0]
	v_pk_mul_f32 v[30:31], v[28:29], v[226:227] op_sel:[1,1] op_sel_hi:[1,0]
	v_pk_fma_f32 v[24:25], v[24:25], v[222:223], v[218:219] op_sel_hi:[0,1,1] neg_lo:[0,0,1]
	v_pk_fma_f32 v[26:27], v[26:27], v[224:225], v[220:221] op_sel_hi:[0,1,1] neg_lo:[0,0,1]
	v_pk_fma_f32 v[28:29], v[28:29], v[226:227], v[30:31] op_sel_hi:[0,1,1] neg_lo:[0,0,1]
	v_pk_add_f32 v[30:31], v[22:23], v[26:27]
	v_pk_add_f32 v[32:33], v[22:23], v[26:27] neg_lo:[0,1] neg_hi:[0,1]
	v_pk_add_f32 v[34:35], v[24:25], v[28:29]
	v_pk_add_f32 v[36:37], v[24:25], v[28:29] neg_lo:[0,1] neg_hi:[0,1]
	v_pk_add_f32 v[22:23], v[30:31], v[34:35]
	v_pk_add_f32 v[26:27], v[30:31], v[34:35] neg_lo:[0,1] neg_hi:[0,1]
	v_pk_add_f32 v[24:25], v[32:33], v[36:37] op_sel:[0,1] op_sel_hi:[1,0] neg_hi:[0,1]
	v_pk_add_f32 v[28:29], v[32:33], v[36:37] op_sel:[0,1] op_sel_hi:[1,0] neg_lo:[0,1]
	v_pk_mul_f32 v[218:219], v[22:23], v[228:229] op_sel:[1,1] op_sel_hi:[1,0]
	v_pk_mul_f32 v[220:221], v[26:27], v[232:233] op_sel:[1,1] op_sel_hi:[1,0]
	v_pk_mul_f32 v[30:31], v[24:25], v[230:231] op_sel:[1,1] op_sel_hi:[1,0]
	v_pk_mul_f32 v[34:35], v[28:29], v[234:235] op_sel:[1,1] op_sel_hi:[1,0]
	v_pk_fma_f32 v[22:23], v[22:23], v[228:229], v[218:219] op_sel_hi:[0,1,1] neg_lo:[0,0,1]
	v_pk_fma_f32 v[26:27], v[26:27], v[232:233], v[220:221] op_sel_hi:[0,1,1] neg_lo:[0,0,1]
	v_pk_fma_f32 v[24:25], v[24:25], v[230:231], v[30:31] op_sel_hi:[0,1,1] neg_lo:[0,0,1]
	v_pk_fma_f32 v[28:29], v[28:29], v[234:235], v[34:35] op_sel_hi:[0,1,1] neg_lo:[0,0,1]
	s_nop 0
	ds_write_b64 v241, v[22:23]
	ds_write_b64 v243, v[26:27]
	ds_write_b64 v242, v[24:25]
	ds_write_b64 v244, v[28:29]
	ds_read_b64 v[22:23], v241 offset:16384
	ds_read_b64 v[24:25], v242 offset:16384
	ds_read_b64 v[26:27], v243 offset:16384
	ds_read_b64 v[28:29], v244 offset:16384
	s_waitcnt lgkmcnt(0)
	v_pk_mul_f32 v[218:219], v[24:25], v[222:223] op_sel:[1,1] op_sel_hi:[1,0]
	v_pk_mul_f32 v[220:221], v[26:27], v[224:225] op_sel:[1,1] op_sel_hi:[1,0]
	v_pk_mul_f32 v[30:31], v[28:29], v[226:227] op_sel:[1,1] op_sel_hi:[1,0]
	v_pk_fma_f32 v[24:25], v[24:25], v[222:223], v[218:219] op_sel_hi:[0,1,1] neg_lo:[0,0,1]
	v_pk_fma_f32 v[26:27], v[26:27], v[224:225], v[220:221] op_sel_hi:[0,1,1] neg_lo:[0,0,1]
	v_pk_fma_f32 v[28:29], v[28:29], v[226:227], v[30:31] op_sel_hi:[0,1,1] neg_lo:[0,0,1]
	v_pk_add_f32 v[30:31], v[22:23], v[26:27]
	v_pk_add_f32 v[32:33], v[22:23], v[26:27] neg_lo:[0,1] neg_hi:[0,1]
	v_pk_add_f32 v[34:35], v[24:25], v[28:29]
	v_pk_add_f32 v[36:37], v[24:25], v[28:29] neg_lo:[0,1] neg_hi:[0,1]
	v_pk_add_f32 v[22:23], v[30:31], v[34:35]
	v_pk_add_f32 v[26:27], v[30:31], v[34:35] neg_lo:[0,1] neg_hi:[0,1]
	v_pk_add_f32 v[24:25], v[32:33], v[36:37] op_sel:[0,1] op_sel_hi:[1,0] neg_hi:[0,1]
	v_pk_add_f32 v[28:29], v[32:33], v[36:37] op_sel:[0,1] op_sel_hi:[1,0] neg_lo:[0,1]
	v_pk_mul_f32 v[218:219], v[22:23], v[228:229] op_sel:[1,1] op_sel_hi:[1,0]
	v_pk_mul_f32 v[220:221], v[26:27], v[232:233] op_sel:[1,1] op_sel_hi:[1,0]
	v_pk_mul_f32 v[30:31], v[24:25], v[230:231] op_sel:[1,1] op_sel_hi:[1,0]
	v_pk_mul_f32 v[34:35], v[28:29], v[234:235] op_sel:[1,1] op_sel_hi:[1,0]
	v_pk_fma_f32 v[22:23], v[22:23], v[228:229], v[218:219] op_sel_hi:[0,1,1] neg_lo:[0,0,1]
	v_pk_fma_f32 v[26:27], v[26:27], v[232:233], v[220:221] op_sel_hi:[0,1,1] neg_lo:[0,0,1]
	v_pk_fma_f32 v[24:25], v[24:25], v[230:231], v[30:31] op_sel_hi:[0,1,1] neg_lo:[0,0,1]
	v_pk_fma_f32 v[28:29], v[28:29], v[234:235], v[34:35] op_sel_hi:[0,1,1] neg_lo:[0,0,1]
	s_nop 0
	ds_write_b64 v241, v[22:23] offset:16384
	ds_write_b64 v243, v[26:27] offset:16384
	ds_write_b64 v242, v[24:25] offset:16384
	ds_write_b64 v244, v[28:29] offset:16384
	ds_read_b64 v[22:23], v241 offset:32768
	ds_read_b64 v[24:25], v242 offset:32768
	ds_read_b64 v[26:27], v243 offset:32768
	ds_read_b64 v[28:29], v244 offset:32768
	s_waitcnt lgkmcnt(0)
	v_pk_mul_f32 v[218:219], v[24:25], v[222:223] op_sel:[1,1] op_sel_hi:[1,0]
	v_pk_mul_f32 v[220:221], v[26:27], v[224:225] op_sel:[1,1] op_sel_hi:[1,0]
	v_pk_mul_f32 v[30:31], v[28:29], v[226:227] op_sel:[1,1] op_sel_hi:[1,0]
	v_pk_fma_f32 v[24:25], v[24:25], v[222:223], v[218:219] op_sel_hi:[0,1,1] neg_lo:[0,0,1]
	v_pk_fma_f32 v[26:27], v[26:27], v[224:225], v[220:221] op_sel_hi:[0,1,1] neg_lo:[0,0,1]
	v_pk_fma_f32 v[28:29], v[28:29], v[226:227], v[30:31] op_sel_hi:[0,1,1] neg_lo:[0,0,1]
	v_pk_add_f32 v[30:31], v[22:23], v[26:27]
	v_pk_add_f32 v[32:33], v[22:23], v[26:27] neg_lo:[0,1] neg_hi:[0,1]
	v_pk_add_f32 v[34:35], v[24:25], v[28:29]
	v_pk_add_f32 v[36:37], v[24:25], v[28:29] neg_lo:[0,1] neg_hi:[0,1]
	v_pk_add_f32 v[22:23], v[30:31], v[34:35]
	v_pk_add_f32 v[26:27], v[30:31], v[34:35] neg_lo:[0,1] neg_hi:[0,1]
	v_pk_add_f32 v[24:25], v[32:33], v[36:37] op_sel:[0,1] op_sel_hi:[1,0] neg_hi:[0,1]
	v_pk_add_f32 v[28:29], v[32:33], v[36:37] op_sel:[0,1] op_sel_hi:[1,0] neg_lo:[0,1]
	v_pk_mul_f32 v[218:219], v[22:23], v[228:229] op_sel:[1,1] op_sel_hi:[1,0]
	v_pk_mul_f32 v[220:221], v[26:27], v[232:233] op_sel:[1,1] op_sel_hi:[1,0]
	v_pk_mul_f32 v[30:31], v[24:25], v[230:231] op_sel:[1,1] op_sel_hi:[1,0]
	v_pk_mul_f32 v[34:35], v[28:29], v[234:235] op_sel:[1,1] op_sel_hi:[1,0]
	v_pk_fma_f32 v[22:23], v[22:23], v[228:229], v[218:219] op_sel_hi:[0,1,1] neg_lo:[0,0,1]
	v_pk_fma_f32 v[26:27], v[26:27], v[232:233], v[220:221] op_sel_hi:[0,1,1] neg_lo:[0,0,1]
	v_pk_fma_f32 v[24:25], v[24:25], v[230:231], v[30:31] op_sel_hi:[0,1,1] neg_lo:[0,0,1]
	v_pk_fma_f32 v[28:29], v[28:29], v[234:235], v[34:35] op_sel_hi:[0,1,1] neg_lo:[0,0,1]
	s_nop 0
	ds_write_b64 v241, v[22:23] offset:32768
	ds_write_b64 v243, v[26:27] offset:32768
	ds_write_b64 v242, v[24:25] offset:32768
	ds_write_b64 v244, v[28:29] offset:32768
	ds_read_b64 v[22:23], v241 offset:49152
	ds_read_b64 v[24:25], v242 offset:49152
	ds_read_b64 v[26:27], v243 offset:49152
	ds_read_b64 v[28:29], v244 offset:49152
	s_waitcnt lgkmcnt(0)
; DI float2 twid(float r) { return float2{__builtin_amdgcn_cosf(r), -__builtin_amdgcn_sinf(r)}; }
; DI void bfly_inv(float2 s0, float2 s1, float2 s2, float2 s3, float r, float2& o0, float2& o1, float2& o2, float2& o3) {
;   float2 w1 = twid(r), w2 = cmul(w1, w1), w3 = cmul(w2, w1);
;   float2 c0 = s0, c1 = cmulc(s1, w1), c2 = cmulc(s2, w2), c3 = cmulc(s3, w3);
;   float2 t0 = {c0.x + c2.x, c0.y + c2.y}, t1 = {c0.x - c2.x, c0.y - c2.y}, t2 = {c1.x + c3.x, c1.y + c3.y}, t3 = {c1.x - c3.x, c1.y - c3.y};
;   o0 = float2{t0.x + t2.x, t0.y + t2.y}; o2 = float2{t0.x - t2.x, t0.y - t2.y}; o1 = float2{t1.x - t3.y, t1.y + t3.x}; o3 = float2{t1.x + t3.y, t1.y - t3.x};
; }
;   const int Q = 1 << lq; const float invM = 1.f / (float)(4 << lq);
;   for (int bb = tid; bb < NBT * (N / 4); bb += NTHR) { const int b = bb & (N / 4 - 1); float2* z = z0 + (bb / (N / 4)) * N; int j = b & (Q - 1), base = ((b >> lq) << (lq + 2)) + j; float2 o0, o1, o2, o3;
;     bfly_inv(z[base], z[base + Q], z[base + 2 * Q], z[base + 3 * Q], (float)j * invM, o0, o1, o2, o3);
;     z[base] = o0; z[base + Q] = o1; z[base + 2 * Q] = o2; z[base + 3 * Q] = o3; }
;   __syncthreads();
; }
	v_pk_mul_f32 v[218:219], v[24:25], v[222:223] op_sel:[1,1] op_sel_hi:[1,0]
	v_pk_mul_f32 v[220:221], v[26:27], v[224:225] op_sel:[1,1] op_sel_hi:[1,0]
	v_pk_mul_f32 v[30:31], v[28:29], v[226:227] op_sel:[1,1] op_sel_hi:[1,0]
	v_pk_fma_f32 v[24:25], v[24:25], v[222:223], v[218:219] op_sel_hi:[0,1,1] neg_lo:[0,0,1]
	v_pk_fma_f32 v[26:27], v[26:27], v[224:225], v[220:221] op_sel_hi:[0,1,1] neg_lo:[0,0,1]
	v_pk_fma_f32 v[28:29], v[28:29], v[226:227], v[30:31] op_sel_hi:[0,1,1] neg_lo:[0,0,1]
	v_pk_add_f32 v[30:31], v[22:23], v[26:27]
	v_pk_add_f32 v[32:33], v[22:23], v[26:27] neg_lo:[0,1] neg_hi:[0,1]
	v_pk_add_f32 v[34:35], v[24:25], v[28:29]
	v_pk_add_f32 v[36:37], v[24:25], v[28:29] neg_lo:[0,1] neg_hi:[0,1]
	v_pk_add_f32 v[22:23], v[30:31], v[34:35]
	v_pk_add_f32 v[26:27], v[30:31], v[34:35] neg_lo:[0,1] neg_hi:[0,1]
	v_pk_add_f32 v[24:25], v[32:33], v[36:37] op_sel:[0,1] op_sel_hi:[1,0] neg_hi:[0,1]
	v_pk_add_f32 v[28:29], v[32:33], v[36:37] op_sel:[0,1] op_sel_hi:[1,0] neg_lo:[0,1]
	v_pk_mul_f32 v[218:219], v[22:23], v[228:229] op_sel:[1,1] op_sel_hi:[1,0]
	v_pk_mul_f32 v[220:221], v[26:27], v[232:233] op_sel:[1,1] op_sel_hi:[1,0]
	v_pk_mul_f32 v[30:31], v[24:25], v[230:231] op_sel:[1,1] op_sel_hi:[1,0]
	v_pk_mul_f32 v[34:35], v[28:29], v[234:235] op_sel:[1,1] op_sel_hi:[1,0]
	v_pk_fma_f32 v[22:23], v[22:23], v[228:229], v[218:219] op_sel_hi:[0,1,1] neg_lo:[0,0,1]
	v_pk_fma_f32 v[26:27], v[26:27], v[232:233], v[220:221] op_sel_hi:[0,1,1] neg_lo:[0,0,1]
	v_pk_fma_f32 v[24:25], v[24:25], v[230:231], v[30:31] op_sel_hi:[0,1,1] neg_lo:[0,0,1]
	v_pk_fma_f32 v[28:29], v[28:29], v[234:235], v[34:35] op_sel_hi:[0,1,1] neg_lo:[0,0,1]
	s_nop 0
	ds_write_b64 v241, v[22:23] offset:49152
	ds_write_b64 v243, v[26:27] offset:49152
	ds_write_b64 v242, v[24:25] offset:49152
	ds_write_b64 v244, v[28:29] offset:49152
	v_add_u32_e32 v241, 0x10000, v241
	v_add_u32_e32 v242, 0x10000, v242
	v_add_u32_e32 v243, 0x10000, v243
	v_add_u32_e32 v244, 0x10000, v244
	ds_read_b64 v[22:23], v241
	ds_read_b64 v[24:25], v242
	ds_read_b64 v[26:27], v243
	ds_read_b64 v[28:29], v244
	s_waitcnt lgkmcnt(0)
	v_pk_mul_f32 v[218:219], v[24:25], v[222:223] op_sel:[1,1] op_sel_hi:[1,0]
	v_pk_mul_f32 v[220:221], v[26:27], v[224:225] op_sel:[1,1] op_sel_hi:[1,0]
	v_pk_mul_f32 v[30:31], v[28:29], v[226:227] op_sel:[1,1] op_sel_hi:[1,0]
	v_pk_fma_f32 v[24:25], v[24:25], v[222:223], v[218:219] op_sel_hi:[0,1,1] neg_lo:[0,0,1]
	v_pk_fma_f32 v[26:27], v[26:27], v[224:225], v[220:221] op_sel_hi:[0,1,1] neg_lo:[0,0,1]
	v_pk_fma_f32 v[28:29], v[28:29], v[226:227], v[30:31] op_sel_hi:[0,1,1] neg_lo:[0,0,1]
	v_pk_add_f32 v[30:31], v[22:23], v[26:27]
	v_pk_add_f32 v[32:33], v[22:23], v[26:27] neg_lo:[0,1] neg_hi:[0,1]
	v_pk_add_f32 v[34:35], v[24:25], v[28:29]
	v_pk_add_f32 v[36:37], v[24:25], v[28:29] neg_lo:[0,1] neg_hi:[0,1]
	v_pk_add_f32 v[22:23], v[30:31], v[34:35]
	v_pk_add_f32 v[26:27], v[30:31], v[34:35] neg_lo:[0,1] neg_hi:[0,1]
	v_pk_add_f32 v[24:25], v[32:33], v[36:37] op_sel:[0,1] op_sel_hi:[1,0] neg_hi:[0,1]
	v_pk_add_f32 v[28:29], v[32:33], v[36:37] op_sel:[0,1] op_sel_hi:[1,0] neg_lo:[0,1]
	v_pk_mul_f32 v[218:219], v[22:23], v[228:229] op_sel:[1,1] op_sel_hi:[1,0]
	v_pk_mul_f32 v[220:221], v[26:27], v[232:233] op_sel:[1,1] op_sel_hi:[1,0]
	v_pk_mul_f32 v[30:31], v[24:25], v[230:231] op_sel:[1,1] op_sel_hi:[1,0]
	v_pk_mul_f32 v[34:35], v[28:29], v[234:235] op_sel:[1,1] op_sel_hi:[1,0]
	v_pk_fma_f32 v[22:23], v[22:23], v[228:229], v[218:219] op_sel_hi:[0,1,1] neg_lo:[0,0,1]
	v_pk_fma_f32 v[26:27], v[26:27], v[232:233], v[220:221] op_sel_hi:[0,1,1] neg_lo:[0,0,1]
	v_pk_fma_f32 v[24:25], v[24:25], v[230:231], v[30:31] op_sel_hi:[0,1,1] neg_lo:[0,0,1]
	v_pk_fma_f32 v[28:29], v[28:29], v[234:235], v[34:35] op_sel_hi:[0,1,1] neg_lo:[0,0,1]
	s_nop 0
	ds_write_b64 v241, v[22:23]
	ds_write_b64 v243, v[26:27]
	ds_write_b64 v242, v[24:25]
	ds_write_b64 v244, v[28:29]
	ds_read_b64 v[22:23], v241 offset:16384
	ds_read_b64 v[24:25], v242 offset:16384
	ds_read_b64 v[26:27], v243 offset:16384
	ds_read_b64 v[28:29], v244 offset:16384
	s_waitcnt lgkmcnt(0)
; DI float2 twid(float r) { return float2{__builtin_amdgcn_cosf(r), -__builtin_amdgcn_sinf(r)}; }
; DI void bfly_inv(float2 s0, float2 s1, float2 s2, float2 s3, float r, float2& o0, float2& o1, float2& o2, float2& o3) {
;   float2 w1 = twid(r), w2 = cmul(w1, w1), w3 = cmul(w2, w1);
;   float2 c0 = s0, c1 = cmulc(s1, w1), c2 = cmulc(s2, w2), c3 = cmulc(s3, w3);
;   float2 t0 = {c0.x + c2.x, c0.y + c2.y}, t1 = {c0.x - c2.x, c0.y - c2.y}, t2 = {c1.x + c3.x, c1.y + c3.y}, t3 = {c1.x - c3.x, c1.y - c3.y};
;   o0 = float2{t0.x + t2.x, t0.y + t2.y}; o2 = float2{t0.x - t2.x, t0.y - t2.y}; o1 = float2{t1.x - t3.y, t1.y + t3.x}; o3 = float2{t1.x + t3.y, t1.y - t3.x};
; }
;   const int Q = 1 << lq; const float invM = 1.f / (float)(4 << lq);
;   for (int bb = tid; bb < NBT * (N / 4); bb += NTHR) { const int b = bb & (N / 4 - 1); float2* z = z0 + (bb / (N / 4)) * N; int j = b & (Q - 1), base = ((b >> lq) << (lq + 2)) + j; float2 o0, o1, o2, o3;
;     bfly_inv(z[base], z[base + Q], z[base + 2 * Q], z[base + 3 * Q], (float)j * invM, o0, o1, o2, o3);
;     z[base] = o0; z[base + Q] = o1; z[base + 2 * Q] = o2; z[base + 3 * Q] = o3; }
;   __syncthreads();
; }
	v_pk_mul_f32 v[218:219], v[24:25], v[222:223] op_sel:[1,1] op_sel_hi:[1,0]
	v_pk_mul_f32 v[220:221], v[26:27], v[224:225] op_sel:[1,1] op_sel_hi:[1,0]
	v_pk_mul_f32 v[30:31], v[28:29], v[226:227] op_sel:[1,1] op_sel_hi:[1,0]
	v_pk_fma_f32 v[24:25], v[24:25], v[222:223], v[218:219] op_sel_hi:[0,1,1] neg_lo:[0,0,1]
	v_pk_fma_f32 v[26:27], v[26:27], v[224:225], v[220:221] op_sel_hi:[0,1,1] neg_lo:[0,0,1]
	v_pk_fma_f32 v[28:29], v[28:29], v[226:227], v[30:31] op_sel_hi:[0,1,1] neg_lo:[0,0,1]
	v_pk_add_f32 v[30:31], v[22:23], v[26:27]
	v_pk_add_f32 v[32:33], v[22:23], v[26:27] neg_lo:[0,1] neg_hi:[0,1]
	v_pk_add_f32 v[34:35], v[24:25], v[28:29]
	v_pk_add_f32 v[36:37], v[24:25], v[28:29] neg_lo:[0,1] neg_hi:[0,1]
	v_pk_add_f32 v[22:23], v[30:31], v[34:35]
	v_pk_add_f32 v[26:27], v[30:31], v[34:35] neg_lo:[0,1] neg_hi:[0,1]
	v_pk_add_f32 v[24:25], v[32:33], v[36:37] op_sel:[0,1] op_sel_hi:[1,0] neg_hi:[0,1]
	v_pk_add_f32 v[28:29], v[32:33], v[36:37] op_sel:[0,1] op_sel_hi:[1,0] neg_lo:[0,1]
	v_pk_mul_f32 v[218:219], v[22:23], v[228:229] op_sel:[1,1] op_sel_hi:[1,0]
	v_pk_mul_f32 v[220:221], v[26:27], v[232:233] op_sel:[1,1] op_sel_hi:[1,0]
	v_pk_mul_f32 v[30:31], v[24:25], v[230:231] op_sel:[1,1] op_sel_hi:[1,0]
	v_pk_mul_f32 v[34:35], v[28:29], v[234:235] op_sel:[1,1] op_sel_hi:[1,0]
	v_pk_fma_f32 v[22:23], v[22:23], v[228:229], v[218:219] op_sel_hi:[0,1,1] neg_lo:[0,0,1]
	v_pk_fma_f32 v[26:27], v[26:27], v[232:233], v[220:221] op_sel_hi:[0,1,1] neg_lo:[0,0,1]
	v_pk_fma_f32 v[24:25], v[24:25], v[230:231], v[30:31] op_sel_hi:[0,1,1] neg_lo:[0,0,1]
	v_pk_fma_f32 v[28:29], v[28:29], v[234:235], v[34:35] op_sel_hi:[0,1,1] neg_lo:[0,0,1]
	s_nop 0
	ds_write_b64 v241, v[22:23] offset:16384
	ds_write_b64 v243, v[26:27] offset:16384
	ds_write_b64 v242, v[24:25] offset:16384
	ds_write_b64 v244, v[28:29] offset:16384
	ds_read_b64 v[22:23], v241 offset:32768
	ds_read_b64 v[24:25], v242 offset:32768
	ds_read_b64 v[26:27], v243 offset:32768
	ds_read_b64 v[28:29], v244 offset:32768
	s_waitcnt lgkmcnt(0)
	v_pk_mul_f32 v[218:219], v[24:25], v[222:223] op_sel:[1,1] op_sel_hi:[1,0]
	v_pk_mul_f32 v[220:221], v[26:27], v[224:225] op_sel:[1,1] op_sel_hi:[1,0]
	v_pk_mul_f32 v[30:31], v[28:29], v[226:227] op_sel:[1,1] op_sel_hi:[1,0]
	v_pk_fma_f32 v[24:25], v[24:25], v[222:223], v[218:219] op_sel_hi:[0,1,1] neg_lo:[0,0,1]
	v_pk_fma_f32 v[26:27], v[26:27], v[224:225], v[220:221] op_sel_hi:[0,1,1] neg_lo:[0,0,1]
	v_pk_fma_f32 v[28:29], v[28:29], v[226:227], v[30:31] op_sel_hi:[0,1,1] neg_lo:[0,0,1]
	v_pk_add_f32 v[30:31], v[22:23], v[26:27]
	v_pk_add_f32 v[32:33], v[22:23], v[26:27] neg_lo:[0,1] neg_hi:[0,1]
	v_pk_add_f32 v[34:35], v[24:25], v[28:29]
	v_pk_add_f32 v[36:37], v[24:25], v[28:29] neg_lo:[0,1] neg_hi:[0,1]
	v_pk_add_f32 v[22:23], v[30:31], v[34:35]
	v_pk_add_f32 v[26:27], v[30:31], v[34:35] neg_lo:[0,1] neg_hi:[0,1]
	v_pk_add_f32 v[24:25], v[32:33], v[36:37] op_sel:[0,1] op_sel_hi:[1,0] neg_hi:[0,1]
	v_pk_add_f32 v[28:29], v[32:33], v[36:37] op_sel:[0,1] op_sel_hi:[1,0] neg_lo:[0,1]
	v_pk_mul_f32 v[218:219], v[22:23], v[228:229] op_sel:[1,1] op_sel_hi:[1,0]
	v_pk_mul_f32 v[220:221], v[26:27], v[232:233] op_sel:[1,1] op_sel_hi:[1,0]
	v_pk_mul_f32 v[30:31], v[24:25], v[230:231] op_sel:[1,1] op_sel_hi:[1,0]
	v_pk_mul_f32 v[34:35], v[28:29], v[234:235] op_sel:[1,1] op_sel_hi:[1,0]
	v_pk_fma_f32 v[22:23], v[22:23], v[228:229], v[218:219] op_sel_hi:[0,1,1] neg_lo:[0,0,1]
	v_pk_fma_f32 v[26:27], v[26:27], v[232:233], v[220:221] op_sel_hi:[0,1,1] neg_lo:[0,0,1]
	v_pk_fma_f32 v[24:25], v[24:25], v[230:231], v[30:31] op_sel_hi:[0,1,1] neg_lo:[0,0,1]
	v_pk_fma_f32 v[28:29], v[28:29], v[234:235], v[34:35] op_sel_hi:[0,1,1] neg_lo:[0,0,1]
	s_nop 0
	ds_write_b64 v241, v[22:23] offset:32768
	ds_write_b64 v243, v[26:27] offset:32768
	ds_write_b64 v242, v[24:25] offset:32768
	ds_write_b64 v244, v[28:29] offset:32768
	ds_read_b64 v[22:23], v241 offset:49152
	ds_read_b64 v[24:25], v242 offset:49152
	ds_read_b64 v[26:27], v243 offset:49152
	ds_read_b64 v[28:29], v244 offset:49152
	s_waitcnt lgkmcnt(0)
	v_pk_mul_f32 v[218:219], v[24:25], v[222:223] op_sel:[1,1] op_sel_hi:[1,0]
	v_pk_mul_f32 v[220:221], v[26:27], v[224:225] op_sel:[1,1] op_sel_hi:[1,0]
	v_pk_mul_f32 v[30:31], v[28:29], v[226:227] op_sel:[1,1] op_sel_hi:[1,0]
	v_pk_fma_f32 v[24:25], v[24:25], v[222:223], v[218:219] op_sel_hi:[0,1,1] neg_lo:[0,0,1]
	v_pk_fma_f32 v[26:27], v[26:27], v[224:225], v[220:221] op_sel_hi:[0,1,1] neg_lo:[0,0,1]
	v_pk_fma_f32 v[28:29], v[28:29], v[226:227], v[30:31] op_sel_hi:[0,1,1] neg_lo:[0,0,1]
	v_pk_add_f32 v[30:31], v[22:23], v[26:27]
	v_pk_add_f32 v[32:33], v[22:23], v[26:27] neg_lo:[0,1] neg_hi:[0,1]
	v_pk_add_f32 v[34:35], v[24:25], v[28:29]
	v_pk_add_f32 v[36:37], v[24:25], v[28:29] neg_lo:[0,1] neg_hi:[0,1]
	v_pk_add_f32 v[22:23], v[30:31], v[34:35]
	v_pk_add_f32 v[26:27], v[30:31], v[34:35] neg_lo:[0,1] neg_hi:[0,1]
	v_pk_add_f32 v[24:25], v[32:33], v[36:37] op_sel:[0,1] op_sel_hi:[1,0] neg_hi:[0,1]
	v_pk_add_f32 v[28:29], v[32:33], v[36:37] op_sel:[0,1] op_sel_hi:[1,0] neg_lo:[0,1]
	v_pk_mul_f32 v[218:219], v[22:23], v[228:229] op_sel:[1,1] op_sel_hi:[1,0]
	v_pk_mul_f32 v[220:221], v[26:27], v[232:233] op_sel:[1,1] op_sel_hi:[1,0]
	v_pk_mul_f32 v[30:31], v[24:25], v[230:231] op_sel:[1,1] op_sel_hi:[1,0]
	v_pk_mul_f32 v[34:35], v[28:29], v[234:235] op_sel:[1,1] op_sel_hi:[1,0]
	v_pk_fma_f32 v[22:23], v[22:23], v[228:229], v[218:219] op_sel_hi:[0,1,1] neg_lo:[0,0,1]
	v_pk_fma_f32 v[26:27], v[26:27], v[232:233], v[220:221] op_sel_hi:[0,1,1] neg_lo:[0,0,1]
	v_pk_fma_f32 v[24:25], v[24:25], v[230:231], v[30:31] op_sel_hi:[0,1,1] neg_lo:[0,0,1]
	v_pk_fma_f32 v[28:29], v[28:29], v[234:235], v[34:35] op_sel_hi:[0,1,1] neg_lo:[0,0,1]
	s_nop 0
	ds_write_b64 v241, v[22:23] offset:49152
	ds_write_b64 v243, v[26:27] offset:49152
	ds_write_b64 v242, v[24:25] offset:49152
	ds_write_b64 v244, v[28:29] offset:49152
	v_add_u32_e32 v19, 0x4000, v19
	v_add_u32_e32 v21, 0x1000, v20
	v_mov_b32_e32 v20, v21
	s_mov_b64 s[80:81], exec

; DI void bfly_fwd(float2 a0, float2 a1, float2 a2, float2 a3, float r, float2& o0, float2& o1, float2& o2, float2& o3) {
;   float2 t0 = {a0.x + a2.x, a0.y + a2.y}, t1 = {a0.x - a2.x, a0.y - a2.y}, t2 = {a1.x + a3.x, a1.y + a3.y}, t3 = {a1.x - a3.x, a1.y - a3.y};
;   float2 b0 = {t0.x + t2.x, t0.y + t2.y}, b2 = {t0.x - t2.x, t0.y - t2.y}, b1 = {t1.x + t3.y, t1.y - t3.x}, b3 = {t1.x - t3.y, t1.y + t3.x};
;   const int Q = 1 << lq; const float invM = 1.f / (float)(4 << lq);
;   for (int bb = tid; bb < NBT * (N / 4); bb += NTHR) { const int b = bb & (N / 4 - 1); float2* z = z0 + (bb / (N / 4)) * N; int j = b & (Q - 1), base = ((b >> lq) << (lq + 2)) + j; float2 o0, o1, o2, o3;
;     bfly_fwd(z[base], z[base + Q], z[base + 2 * Q], z[base + 3 * Q], (float)j * invM, o0, o1, o2, o3);
;     z[base] = o0; z[base + Q] = o1; z[base + 2 * Q] = o2; z[base + 3 * Q] = o3; }
;   __syncthreads();
; }
.LBB0_1641:
	v_ashrrev_i32_e32 v6, 31, v5
	v_lshrrev_b32_e32 v6, 20, v6
	v_add_lshl_u32 v6, v5, v6, 5
	v_and_b32_e32 v7, 0x3ffc, v4
	v_and_b32_e32 v6, 0xfffe0000, v6
	v_lshlrev_b32_e32 v7, 3, v7
	v_add3_u32 v19, 16, v6, v7
	ds_read_b128 v[6:9], v19
	ds_read_b128 v[10:13], v19 offset:16
	s_waitcnt lgkmcnt(0)
	v_pk_add_f32 v[14:15], v[6:7], v[10:11]
	v_pk_add_f32 v[22:23], v[8:9], v[12:13]
	v_pk_add_f32 v[20:21], v[6:7], v[10:11] neg_lo:[0,1] neg_hi:[0,1]
	v_pk_add_f32 v[24:25], v[8:9], v[12:13] neg_lo:[0,1] neg_hi:[0,1]
	v_pk_add_f32 v[6:7], v[14:15], v[22:23]
	v_pk_add_f32 v[10:11], v[14:15], v[22:23] neg_lo:[0,1] neg_hi:[0,1]
	v_pk_add_f32 v[8:9], v[20:21], v[24:25] op_sel:[0,1] op_sel_hi:[1,0] neg_hi:[0,1]
	v_pk_add_f32 v[12:13], v[20:21], v[24:25] op_sel:[0,1] op_sel_hi:[1,0] neg_lo:[0,1]
	s_nop 0
	ds_write_b128 v19, v[6:9]
	ds_write_b128 v19, v[10:13] offset:16
	ds_read_b128 v[6:9], v19 offset:16384
	ds_read_b128 v[10:13], v19 offset:16400
	s_waitcnt lgkmcnt(0)
	v_pk_add_f32 v[14:15], v[6:7], v[10:11]
	v_pk_add_f32 v[22:23], v[8:9], v[12:13]
	v_pk_add_f32 v[20:21], v[6:7], v[10:11] neg_lo:[0,1] neg_hi:[0,1]
	v_pk_add_f32 v[24:25], v[8:9], v[12:13] neg_lo:[0,1] neg_hi:[0,1]
	v_pk_add_f32 v[6:7], v[14:15], v[22:23]
	v_pk_add_f32 v[10:11], v[14:15], v[22:23] neg_lo:[0,1] neg_hi:[0,1]
	v_pk_add_f32 v[8:9], v[20:21], v[24:25] op_sel:[0,1] op_sel_hi:[1,0] neg_hi:[0,1]
	v_pk_add_f32 v[12:13], v[20:21], v[24:25] op_sel:[0,1] op_sel_hi:[1,0] neg_lo:[0,1]
	s_nop 0
	ds_write_b128 v19, v[6:9] offset:16384
	ds_write_b128 v19, v[10:13] offset:16400
	ds_read_b128 v[6:9], v19 offset:32768
	ds_read_b128 v[10:13], v19 offset:32784
	s_waitcnt lgkmcnt(0)
	v_pk_add_f32 v[14:15], v[6:7], v[10:11]
	v_pk_add_f32 v[22:23], v[8:9], v[12:13]
	v_pk_add_f32 v[20:21], v[6:7], v[10:11] neg_lo:[0,1] neg_hi:[0,1]
	v_pk_add_f32 v[24:25], v[8:9], v[12:13] neg_lo:[0,1] neg_hi:[0,1]
	v_pk_add_f32 v[6:7], v[14:15], v[22:23]
	v_pk_add_f32 v[10:11], v[14:15], v[22:23] neg_lo:[0,1] neg_hi:[0,1]
	v_pk_add_f32 v[8:9], v[20:21], v[24:25] op_sel:[0,1] op_sel_hi:[1,0] neg_hi:[0,1]
	v_pk_add_f32 v[12:13], v[20:21], v[24:25] op_sel:[0,1] op_sel_hi:[1,0] neg_lo:[0,1]
	s_nop 0
	ds_write_b128 v19, v[6:9] offset:32768
	ds_write_b128 v19, v[10:13] offset:32784
	ds_read_b128 v[6:9], v19 offset:49152
	ds_read_b128 v[10:13], v19 offset:49168
	s_waitcnt lgkmcnt(0)
	v_pk_add_f32 v[14:15], v[6:7], v[10:11]
	v_pk_add_f32 v[22:23], v[8:9], v[12:13]
	v_pk_add_f32 v[20:21], v[6:7], v[10:11] neg_lo:[0,1] neg_hi:[0,1]
	v_pk_add_f32 v[24:25], v[8:9], v[12:13] neg_lo:[0,1] neg_hi:[0,1]
	v_pk_add_f32 v[6:7], v[14:15], v[22:23]
	v_pk_add_f32 v[10:11], v[14:15], v[22:23] neg_lo:[0,1] neg_hi:[0,1]
	v_pk_add_f32 v[8:9], v[20:21], v[24:25] op_sel:[0,1] op_sel_hi:[1,0] neg_hi:[0,1]
	v_pk_add_f32 v[12:13], v[20:21], v[24:25] op_sel:[0,1] op_sel_hi:[1,0] neg_lo:[0,1]
	s_nop 0
	ds_write_b128 v19, v[6:9] offset:49152
	ds_write_b128 v19, v[10:13] offset:49168
	v_add_u32_e32 v19, 0x10000, v19
	ds_read_b128 v[6:9], v19
	ds_read_b128 v[10:13], v19 offset:16
	s_waitcnt lgkmcnt(0)
	v_pk_add_f32 v[14:15], v[6:7], v[10:11]
	v_pk_add_f32 v[22:23], v[8:9], v[12:13]
	v_pk_add_f32 v[20:21], v[6:7], v[10:11] neg_lo:[0,1] neg_hi:[0,1]
	v_pk_add_f32 v[24:25], v[8:9], v[12:13] neg_lo:[0,1] neg_hi:[0,1]
	v_pk_add_f32 v[6:7], v[14:15], v[22:23]
	v_pk_add_f32 v[10:11], v[14:15], v[22:23] neg_lo:[0,1] neg_hi:[0,1]
	v_pk_add_f32 v[8:9], v[20:21], v[24:25] op_sel:[0,1] op_sel_hi:[1,0] neg_hi:[0,1]
	v_pk_add_f32 v[12:13], v[20:21], v[24:25] op_sel:[0,1] op_sel_hi:[1,0] neg_lo:[0,1]
	s_nop 0
	ds_write_b128 v19, v[6:9]
	ds_write_b128 v19, v[10:13] offset:16
	ds_read_b128 v[6:9], v19 offset:16384
	ds_read_b128 v[10:13], v19 offset:16400
	s_waitcnt lgkmcnt(0)
	v_pk_add_f32 v[14:15], v[6:7], v[10:11]
	v_pk_add_f32 v[22:23], v[8:9], v[12:13]
	v_pk_add_f32 v[20:21], v[6:7], v[10:11] neg_lo:[0,1] neg_hi:[0,1]
	v_pk_add_f32 v[24:25], v[8:9], v[12:13] neg_lo:[0,1] neg_hi:[0,1]
	v_pk_add_f32 v[6:7], v[14:15], v[22:23]
	v_pk_add_f32 v[10:11], v[14:15], v[22:23] neg_lo:[0,1] neg_hi:[0,1]
	v_pk_add_f32 v[8:9], v[20:21], v[24:25] op_sel:[0,1] op_sel_hi:[1,0] neg_hi:[0,1]
	v_pk_add_f32 v[12:13], v[20:21], v[24:25] op_sel:[0,1] op_sel_hi:[1,0] neg_lo:[0,1]
	s_nop 0
	ds_write_b128 v19, v[6:9] offset:16384
	ds_write_b128 v19, v[10:13] offset:16400
	ds_read_b128 v[6:9], v19 offset:32768
	ds_read_b128 v[10:13], v19 offset:32784
	s_waitcnt lgkmcnt(0)
	v_pk_add_f32 v[14:15], v[6:7], v[10:11]
	v_pk_add_f32 v[22:23], v[8:9], v[12:13]
	v_pk_add_f32 v[20:21], v[6:7], v[10:11] neg_lo:[0,1] neg_hi:[0,1]
	v_pk_add_f32 v[24:25], v[8:9], v[12:13] neg_lo:[0,1] neg_hi:[0,1]
	v_pk_add_f32 v[6:7], v[14:15], v[22:23]
	v_pk_add_f32 v[10:11], v[14:15], v[22:23] neg_lo:[0,1] neg_hi:[0,1]
	v_pk_add_f32 v[8:9], v[20:21], v[24:25] op_sel:[0,1] op_sel_hi:[1,0] neg_hi:[0,1]
	v_pk_add_f32 v[12:13], v[20:21], v[24:25] op_sel:[0,1] op_sel_hi:[1,0] neg_lo:[0,1]
	s_nop 0
	ds_write_b128 v19, v[6:9] offset:32768
	ds_write_b128 v19, v[10:13] offset:32784
	ds_read_b128 v[6:9], v19 offset:49152
	ds_read_b128 v[10:13], v19 offset:49168
	s_waitcnt lgkmcnt(0)
	v_pk_add_f32 v[14:15], v[6:7], v[10:11]
	v_pk_add_f32 v[22:23], v[8:9], v[12:13]
	v_pk_add_f32 v[20:21], v[6:7], v[10:11] neg_lo:[0,1] neg_hi:[0,1]
	v_pk_add_f32 v[24:25], v[8:9], v[12:13] neg_lo:[0,1] neg_hi:[0,1]
	v_pk_add_f32 v[6:7], v[14:15], v[22:23]
	v_pk_add_f32 v[10:11], v[14:15], v[22:23] neg_lo:[0,1] neg_hi:[0,1]
	v_pk_add_f32 v[8:9], v[20:21], v[24:25] op_sel:[0,1] op_sel_hi:[1,0] neg_hi:[0,1]
	v_pk_add_f32 v[12:13], v[20:21], v[24:25] op_sel:[0,1] op_sel_hi:[1,0] neg_lo:[0,1]
	s_nop 0
	ds_write_b128 v19, v[6:9] offset:49152
	ds_write_b128 v19, v[10:13] offset:49168
	v_add_u32_e32 v4, 0x4000, v4
	v_add_u32_e32 v6, 0x1000, v5
	v_mov_b32_e32 v5, v6
	s_mov_b64 s[80:81], exec

; DI float2 twid(float r) { return float2{__builtin_amdgcn_cosf(r), -__builtin_amdgcn_sinf(r)}; }
; DI void bfly_fwd(float2 a0, float2 a1, float2 a2, float2 a3, float r, float2& o0, float2& o1, float2& o2, float2& o3) {
;   float2 t0 = {a0.x + a2.x, a0.y + a2.y}, t1 = {a0.x - a2.x, a0.y - a2.y}, t2 = {a1.x + a3.x, a1.y + a3.y}, t3 = {a1.x - a3.x, a1.y - a3.y};
;   float2 b0 = {t0.x + t2.x, t0.y + t2.y}, b2 = {t0.x - t2.x, t0.y - t2.y}, b1 = {t1.x + t3.y, t1.y - t3.x}, b3 = {t1.x - t3.y, t1.y + t3.x};
;   float2 w1 = twid(r), w2 = cmul(w1, w1), w3 = cmul(w2, w1);
;   o0 = b0; o1 = cmul(b1, w1); o2 = cmul(b2, w2); o3 = cmul(b3, w3);
; }
;   const int Q = 1 << lq; const float invM = 1.f / (float)(4 << lq);
;   for (int bb = tid; bb < NBT * (N / 4); bb += NTHR) { const int b = bb & (N / 4 - 1); float2* z = z0 + (bb / (N / 4)) * N; int j = b & (Q - 1), base = ((b >> lq) << (lq + 2)) + j; float2 o0, o1, o2, o3;
;     bfly_fwd(z[base], z[base + Q], z[base + 2 * Q], z[base + 3 * Q], (float)j * invM, o0, o1, o2, o3);
;     z[base] = o0; z[base + Q] = o1; z[base + 2 * Q] = o2; z[base + 3 * Q] = o3; }
;   __syncthreads();
; }
.LBB0_1647:
	v_ashrrev_i32_e32 v19, 31, v18
	v_lshrrev_b32_e32 v19, 20, v19
	v_add_lshl_u32 v19, v18, v19, 5
	v_and_b32_e32 v19, 0xfffe0000, v19
	v_and_b32_e32 v20, 0x3ff0, v17
	v_add_u32_e32 v19, 16, v19
	v_lshlrev_b32_e32 v20, 3, v20
	v_lshlrev_b32_e32 v21, 3, v16
	v_add3_u32 v19, v19, v20, v21
	v_add_u32_e32 v245, v19, v241
	v_add_u32_e32 v246, v19, v242
	v_add_u32_e32 v247, v19, v243
	v_add_u32_e32 v248, v19, v244
	ds_read_b64 v[20:21], v245
	ds_read_b64 v[22:23], v246
	ds_read_b64 v[24:25], v247
	ds_read_b64 v[26:27], v248
	s_waitcnt lgkmcnt(0)
	v_pk_mul_f32 v[220:221], v[20:21], v[224:225] op_sel:[1,1] op_sel_hi:[1,0]
	v_pk_mul_f32 v[222:223], v[22:23], v[226:227] op_sel:[1,1] op_sel_hi:[1,0]
	v_pk_mul_f32 v[28:29], v[24:25], v[228:229] op_sel:[1,1] op_sel_hi:[1,0]
	v_pk_mul_f32 v[30:31], v[26:27], v[230:231] op_sel:[1,1] op_sel_hi:[1,0]
	v_pk_fma_f32 v[20:21], v[20:21], v[224:225], v[220:221] op_sel_hi:[0,1,1] neg_lo:[0,0,1]
	v_pk_fma_f32 v[22:23], v[22:23], v[226:227], v[222:223] op_sel_hi:[0,1,1] neg_lo:[0,0,1]
	v_pk_fma_f32 v[24:25], v[24:25], v[228:229], v[28:29] op_sel_hi:[0,1,1] neg_lo:[0,0,1]
	v_pk_fma_f32 v[26:27], v[26:27], v[230:231], v[30:31] op_sel_hi:[0,1,1] neg_lo:[0,0,1]
	v_pk_add_f32 v[28:29], v[20:21], v[24:25]
	v_pk_add_f32 v[30:31], v[20:21], v[24:25] neg_lo:[0,1] neg_hi:[0,1]
	v_pk_add_f32 v[32:33], v[22:23], v[26:27]
	v_pk_add_f32 v[218:219], v[22:23], v[26:27] neg_lo:[0,1] neg_hi:[0,1]
	v_pk_add_f32 v[20:21], v[28:29], v[32:33]
	v_pk_add_f32 v[24:25], v[28:29], v[32:33] neg_lo:[0,1] neg_hi:[0,1]
	v_pk_add_f32 v[22:23], v[30:31], v[218:219] op_sel:[0,1] op_sel_hi:[1,0] neg_lo:[0,1]
	v_pk_add_f32 v[26:27], v[30:31], v[218:219] op_sel:[0,1] op_sel_hi:[1,0] neg_hi:[0,1]
	v_pk_mul_f32 v[220:221], v[20:21], v[232:233] op_sel:[1,1] op_sel_hi:[1,0]
	v_pk_mul_f32 v[222:223], v[24:25], v[236:237] op_sel:[1,1] op_sel_hi:[1,0]
	v_pk_mul_f32 v[28:29], v[22:23], v[234:235] op_sel:[1,1] op_sel_hi:[1,0]
	v_pk_mul_f32 v[32:33], v[26:27], v[238:239] op_sel:[1,1] op_sel_hi:[1,0]
	v_pk_fma_f32 v[20:21], v[20:21], v[232:233], v[220:221] op_sel_hi:[0,1,1] neg_lo:[0,0,1]
	v_pk_fma_f32 v[24:25], v[24:25], v[236:237], v[222:223] op_sel_hi:[0,1,1] neg_lo:[0,0,1]
	v_pk_fma_f32 v[22:23], v[22:23], v[234:235], v[28:29] op_sel_hi:[0,1,1] neg_lo:[0,0,1]
	v_pk_fma_f32 v[26:27], v[26:27], v[238:239], v[32:33] op_sel_hi:[0,1,1] neg_lo:[0,0,1]
	s_nop 0
	ds_write_b64 v245, v[20:21]
	ds_write_b64 v247, v[24:25]
	ds_write_b64 v246, v[22:23]
	ds_write_b64 v248, v[26:27]
	ds_read_b64 v[20:21], v245 offset:16384
	ds_read_b64 v[22:23], v246 offset:16384
	ds_read_b64 v[24:25], v247 offset:16384
	ds_read_b64 v[26:27], v248 offset:16384
	s_waitcnt lgkmcnt(0)
	v_pk_mul_f32 v[220:221], v[20:21], v[224:225] op_sel:[1,1] op_sel_hi:[1,0]
	v_pk_mul_f32 v[222:223], v[22:23], v[226:227] op_sel:[1,1] op_sel_hi:[1,0]
	v_pk_mul_f32 v[28:29], v[24:25], v[228:229] op_sel:[1,1] op_sel_hi:[1,0]
	v_pk_mul_f32 v[30:31], v[26:27], v[230:231] op_sel:[1,1] op_sel_hi:[1,0]
	v_pk_fma_f32 v[20:21], v[20:21], v[224:225], v[220:221] op_sel_hi:[0,1,1] neg_lo:[0,0,1]
	v_pk_fma_f32 v[22:23], v[22:23], v[226:227], v[222:223] op_sel_hi:[0,1,1] neg_lo:[0,0,1]
	v_pk_fma_f32 v[24:25], v[24:25], v[228:229], v[28:29] op_sel_hi:[0,1,1] neg_lo:[0,0,1]
	v_pk_fma_f32 v[26:27], v[26:27], v[230:231], v[30:31] op_sel_hi:[0,1,1] neg_lo:[0,0,1]
	v_pk_add_f32 v[28:29], v[20:21], v[24:25]
	v_pk_add_f32 v[30:31], v[20:21], v[24:25] neg_lo:[0,1] neg_hi:[0,1]
	v_pk_add_f32 v[32:33], v[22:23], v[26:27]
	v_pk_add_f32 v[218:219], v[22:23], v[26:27] neg_lo:[0,1] neg_hi:[0,1]
	v_pk_add_f32 v[20:21], v[28:29], v[32:33]
	v_pk_add_f32 v[24:25], v[28:29], v[32:33] neg_lo:[0,1] neg_hi:[0,1]
	v_pk_add_f32 v[22:23], v[30:31], v[218:219] op_sel:[0,1] op_sel_hi:[1,0] neg_lo:[0,1]
	v_pk_add_f32 v[26:27], v[30:31], v[218:219] op_sel:[0,1] op_sel_hi:[1,0] neg_hi:[0,1]
	v_pk_mul_f32 v[220:221], v[20:21], v[232:233] op_sel:[1,1] op_sel_hi:[1,0]
	v_pk_mul_f32 v[222:223], v[24:25], v[236:237] op_sel:[1,1] op_sel_hi:[1,0]
	v_pk_mul_f32 v[28:29], v[22:23], v[234:235] op_sel:[1,1] op_sel_hi:[1,0]
	v_pk_mul_f32 v[32:33], v[26:27], v[238:239] op_sel:[1,1] op_sel_hi:[1,0]
	v_pk_fma_f32 v[20:21], v[20:21], v[232:233], v[220:221] op_sel_hi:[0,1,1] neg_lo:[0,0,1]
	v_pk_fma_f32 v[24:25], v[24:25], v[236:237], v[222:223] op_sel_hi:[0,1,1] neg_lo:[0,0,1]
	v_pk_fma_f32 v[22:23], v[22:23], v[234:235], v[28:29] op_sel_hi:[0,1,1] neg_lo:[0,0,1]
	v_pk_fma_f32 v[26:27], v[26:27], v[238:239], v[32:33] op_sel_hi:[0,1,1] neg_lo:[0,0,1]
	s_nop 0
	ds_write_b64 v245, v[20:21] offset:16384
	ds_write_b64 v247, v[24:25] offset:16384
	ds_write_b64 v246, v[22:23] offset:16384
	ds_write_b64 v248, v[26:27] offset:16384
	ds_read_b64 v[20:21], v245 offset:32768
	ds_read_b64 v[22:23], v246 offset:32768
	ds_read_b64 v[24:25], v247 offset:32768
	ds_read_b64 v[26:27], v248 offset:32768
	s_waitcnt lgkmcnt(0)
; DI float2 twid(float r) { return float2{__builtin_amdgcn_cosf(r), -__builtin_amdgcn_sinf(r)}; }
; DI void bfly_fwd(float2 a0, float2 a1, float2 a2, float2 a3, float r, float2& o0, float2& o1, float2& o2, float2& o3) {
;   float2 t0 = {a0.x + a2.x, a0.y + a2.y}, t1 = {a0.x - a2.x, a0.y - a2.y}, t2 = {a1.x + a3.x, a1.y + a3.y}, t3 = {a1.x - a3.x, a1.y - a3.y};
;   float2 b0 = {t0.x + t2.x, t0.y + t2.y}, b2 = {t0.x - t2.x, t0.y - t2.y}, b1 = {t1.x + t3.y, t1.y - t3.x}, b3 = {t1.x - t3.y, t1.y + t3.x};
;   float2 w1 = twid(r), w2 = cmul(w1, w1), w3 = cmul(w2, w1);
;   o0 = b0; o1 = cmul(b1, w1); o2 = cmul(b2, w2); o3 = cmul(b3, w3);
; }
;   const int Q = 1 << lq; const float invM = 1.f / (float)(4 << lq);
;   for (int bb = tid; bb < NBT * (N / 4); bb += NTHR) { const int b = bb & (N / 4 - 1); float2* z = z0 + (bb / (N / 4)) * N; int j = b & (Q - 1), base = ((b >> lq) << (lq + 2)) + j; float2 o0, o1, o2, o3;
;     bfly_fwd(z[base], z[base + Q], z[base + 2 * Q], z[base + 3 * Q], (float)j * invM, o0, o1, o2, o3);
;     z[base] = o0; z[base + Q] = o1; z[base + 2 * Q] = o2; z[base + 3 * Q] = o3; }
;   __syncthreads();
; }
	v_pk_mul_f32 v[220:221], v[20:21], v[224:225] op_sel:[1,1] op_sel_hi:[1,0]
	v_pk_mul_f32 v[222:223], v[22:23], v[226:227] op_sel:[1,1] op_sel_hi:[1,0]
	v_pk_mul_f32 v[28:29], v[24:25], v[228:229] op_sel:[1,1] op_sel_hi:[1,0]
	v_pk_mul_f32 v[30:31], v[26:27], v[230:231] op_sel:[1,1] op_sel_hi:[1,0]
	v_pk_fma_f32 v[20:21], v[20:21], v[224:225], v[220:221] op_sel_hi:[0,1,1] neg_lo:[0,0,1]
	v_pk_fma_f32 v[22:23], v[22:23], v[226:227], v[222:223] op_sel_hi:[0,1,1] neg_lo:[0,0,1]
	v_pk_fma_f32 v[24:25], v[24:25], v[228:229], v[28:29] op_sel_hi:[0,1,1] neg_lo:[0,0,1]
	v_pk_fma_f32 v[26:27], v[26:27], v[230:231], v[30:31] op_sel_hi:[0,1,1] neg_lo:[0,0,1]
	v_pk_add_f32 v[28:29], v[20:21], v[24:25]
	v_pk_add_f32 v[30:31], v[20:21], v[24:25] neg_lo:[0,1] neg_hi:[0,1]
	v_pk_add_f32 v[32:33], v[22:23], v[26:27]
	v_pk_add_f32 v[218:219], v[22:23], v[26:27] neg_lo:[0,1] neg_hi:[0,1]
	v_pk_add_f32 v[20:21], v[28:29], v[32:33]
	v_pk_add_f32 v[24:25], v[28:29], v[32:33] neg_lo:[0,1] neg_hi:[0,1]
	v_pk_add_f32 v[22:23], v[30:31], v[218:219] op_sel:[0,1] op_sel_hi:[1,0] neg_lo:[0,1]
	v_pk_add_f32 v[26:27], v[30:31], v[218:219] op_sel:[0,1] op_sel_hi:[1,0] neg_hi:[0,1]
	v_pk_mul_f32 v[220:221], v[20:21], v[232:233] op_sel:[1,1] op_sel_hi:[1,0]
	v_pk_mul_f32 v[222:223], v[24:25], v[236:237] op_sel:[1,1] op_sel_hi:[1,0]
	v_pk_mul_f32 v[28:29], v[22:23], v[234:235] op_sel:[1,1] op_sel_hi:[1,0]
	v_pk_mul_f32 v[32:33], v[26:27], v[238:239] op_sel:[1,1] op_sel_hi:[1,0]
	v_pk_fma_f32 v[20:21], v[20:21], v[232:233], v[220:221] op_sel_hi:[0,1,1] neg_lo:[0,0,1]
	v_pk_fma_f32 v[24:25], v[24:25], v[236:237], v[222:223] op_sel_hi:[0,1,1] neg_lo:[0,0,1]
	v_pk_fma_f32 v[22:23], v[22:23], v[234:235], v[28:29] op_sel_hi:[0,1,1] neg_lo:[0,0,1]
	v_pk_fma_f32 v[26:27], v[26:27], v[238:239], v[32:33] op_sel_hi:[0,1,1] neg_lo:[0,0,1]
	s_nop 0
	ds_write_b64 v245, v[20:21] offset:32768
	ds_write_b64 v247, v[24:25] offset:32768
	ds_write_b64 v246, v[22:23] offset:32768
	ds_write_b64 v248, v[26:27] offset:32768
	ds_read_b64 v[20:21], v245 offset:49152
	ds_read_b64 v[22:23], v246 offset:49152
	ds_read_b64 v[24:25], v247 offset:49152
	ds_read_b64 v[26:27], v248 offset:49152
	s_waitcnt lgkmcnt(0)
	v_pk_mul_f32 v[220:221], v[20:21], v[224:225] op_sel:[1,1] op_sel_hi:[1,0]
	v_pk_mul_f32 v[222:223], v[22:23], v[226:227] op_sel:[1,1] op_sel_hi:[1,0]
	v_pk_mul_f32 v[28:29], v[24:25], v[228:229] op_sel:[1,1] op_sel_hi:[1,0]
	v_pk_mul_f32 v[30:31], v[26:27], v[230:231] op_sel:[1,1] op_sel_hi:[1,0]
	v_pk_fma_f32 v[20:21], v[20:21], v[224:225], v[220:221] op_sel_hi:[0,1,1] neg_lo:[0,0,1]
	v_pk_fma_f32 v[22:23], v[22:23], v[226:227], v[222:223] op_sel_hi:[0,1,1] neg_lo:[0,0,1]
	v_pk_fma_f32 v[24:25], v[24:25], v[228:229], v[28:29] op_sel_hi:[0,1,1] neg_lo:[0,0,1]
	v_pk_fma_f32 v[26:27], v[26:27], v[230:231], v[30:31] op_sel_hi:[0,1,1] neg_lo:[0,0,1]
	v_pk_add_f32 v[28:29], v[20:21], v[24:25]
	v_pk_add_f32 v[30:31], v[20:21], v[24:25] neg_lo:[0,1] neg_hi:[0,1]
	v_pk_add_f32 v[32:33], v[22:23], v[26:27]
	v_pk_add_f32 v[218:219], v[22:23], v[26:27] neg_lo:[0,1] neg_hi:[0,1]
	v_pk_add_f32 v[20:21], v[28:29], v[32:33]
	v_pk_add_f32 v[24:25], v[28:29], v[32:33] neg_lo:[0,1] neg_hi:[0,1]
	v_pk_add_f32 v[22:23], v[30:31], v[218:219] op_sel:[0,1] op_sel_hi:[1,0] neg_lo:[0,1]
	v_pk_add_f32 v[26:27], v[30:31], v[218:219] op_sel:[0,1] op_sel_hi:[1,0] neg_hi:[0,1]
	v_pk_mul_f32 v[220:221], v[20:21], v[232:233] op_sel:[1,1] op_sel_hi:[1,0]
	v_pk_mul_f32 v[222:223], v[24:25], v[236:237] op_sel:[1,1] op_sel_hi:[1,0]
	v_pk_mul_f32 v[28:29], v[22:23], v[234:235] op_sel:[1,1] op_sel_hi:[1,0]
	v_pk_mul_f32 v[32:33], v[26:27], v[238:239] op_sel:[1,1] op_sel_hi:[1,0]
	v_pk_fma_f32 v[20:21], v[20:21], v[232:233], v[220:221] op_sel_hi:[0,1,1] neg_lo:[0,0,1]
	v_pk_fma_f32 v[24:25], v[24:25], v[236:237], v[222:223] op_sel_hi:[0,1,1] neg_lo:[0,0,1]
	v_pk_fma_f32 v[22:23], v[22:23], v[234:235], v[28:29] op_sel_hi:[0,1,1] neg_lo:[0,0,1]
	v_pk_fma_f32 v[26:27], v[26:27], v[238:239], v[32:33] op_sel_hi:[0,1,1] neg_lo:[0,0,1]
	s_nop 0
	ds_write_b64 v245, v[20:21] offset:49152
	ds_write_b64 v247, v[24:25] offset:49152
	ds_write_b64 v246, v[22:23] offset:49152
	ds_write_b64 v248, v[26:27] offset:49152
	v_add_u32_e32 v245, 0x10000, v245
	v_add_u32_e32 v246, 0x10000, v246
	v_add_u32_e32 v247, 0x10000, v247
	v_add_u32_e32 v248, 0x10000, v248
	ds_read_b64 v[20:21], v245
	ds_read_b64 v[22:23], v246
	ds_read_b64 v[24:25], v247
	ds_read_b64 v[26:27], v248
	s_waitcnt lgkmcnt(0)
	v_pk_mul_f32 v[220:221], v[20:21], v[224:225] op_sel:[1,1] op_sel_hi:[1,0]
	v_pk_mul_f32 v[222:223], v[22:23], v[226:227] op_sel:[1,1] op_sel_hi:[1,0]
	v_pk_mul_f32 v[28:29], v[24:25], v[228:229] op_sel:[1,1] op_sel_hi:[1,0]
	v_pk_mul_f32 v[30:31], v[26:27], v[230:231] op_sel:[1,1] op_sel_hi:[1,0]
	v_pk_fma_f32 v[20:21], v[20:21], v[224:225], v[220:221] op_sel_hi:[0,1,1] neg_lo:[0,0,1]
	v_pk_fma_f32 v[22:23], v[22:23], v[226:227], v[222:223] op_sel_hi:[0,1,1] neg_lo:[0,0,1]
	v_pk_fma_f32 v[24:25], v[24:25], v[228:229], v[28:29] op_sel_hi:[0,1,1] neg_lo:[0,0,1]
	v_pk_fma_f32 v[26:27], v[26:27], v[230:231], v[30:31] op_sel_hi:[0,1,1] neg_lo:[0,0,1]
	v_pk_add_f32 v[28:29], v[20:21], v[24:25]
	v_pk_add_f32 v[30:31], v[20:21], v[24:25] neg_lo:[0,1] neg_hi:[0,1]
	v_pk_add_f32 v[32:33], v[22:23], v[26:27]
	v_pk_add_f32 v[218:219], v[22:23], v[26:27] neg_lo:[0,1] neg_hi:[0,1]
	v_pk_add_f32 v[20:21], v[28:29], v[32:33]
	v_pk_add_f32 v[24:25], v[28:29], v[32:33] neg_lo:[0,1] neg_hi:[0,1]
	v_pk_add_f32 v[22:23], v[30:31], v[218:219] op_sel:[0,1] op_sel_hi:[1,0] neg_lo:[0,1]
	v_pk_add_f32 v[26:27], v[30:31], v[218:219] op_sel:[0,1] op_sel_hi:[1,0] neg_hi:[0,1]
	v_pk_mul_f32 v[220:221], v[20:21], v[232:233] op_sel:[1,1] op_sel_hi:[1,0]
	v_pk_mul_f32 v[222:223], v[24:25], v[236:237] op_sel:[1,1] op_sel_hi:[1,0]
	v_pk_mul_f32 v[28:29], v[22:23], v[234:235] op_sel:[1,1] op_sel_hi:[1,0]
	v_pk_mul_f32 v[32:33], v[26:27], v[238:239] op_sel:[1,1] op_sel_hi:[1,0]
	v_pk_fma_f32 v[20:21], v[20:21], v[232:233], v[220:221] op_sel_hi:[0,1,1] neg_lo:[0,0,1]
	v_pk_fma_f32 v[24:25], v[24:25], v[236:237], v[222:223] op_sel_hi:[0,1,1] neg_lo:[0,0,1]
	v_pk_fma_f32 v[22:23], v[22:23], v[234:235], v[28:29] op_sel_hi:[0,1,1] neg_lo:[0,0,1]
	v_pk_fma_f32 v[26:27], v[26:27], v[238:239], v[32:33] op_sel_hi:[0,1,1] neg_lo:[0,0,1]
	s_nop 0
	ds_write_b64 v245, v[20:21]
	ds_write_b64 v247, v[24:25]
	ds_write_b64 v246, v[22:23]
	ds_write_b64 v248, v[26:27]
	ds_read_b64 v[20:21], v245 offset:16384
	ds_read_b64 v[22:23], v246 offset:16384
	ds_read_b64 v[24:25], v247 offset:16384
	ds_read_b64 v[26:27], v248 offset:16384
	s_waitcnt lgkmcnt(0)
; DI float2 twid(float r) { return float2{__builtin_amdgcn_cosf(r), -__builtin_amdgcn_sinf(r)}; }
; DI void bfly_fwd(float2 a0, float2 a1, float2 a2, float2 a3, float r, float2& o0, float2& o1, float2& o2, float2& o3) {
;   float2 t0 = {a0.x + a2.x, a0.y + a2.y}, t1 = {a0.x - a2.x, a0.y - a2.y}, t2 = {a1.x + a3.x, a1.y + a3.y}, t3 = {a1.x - a3.x, a1.y - a3.y};
;   float2 b0 = {t0.x + t2.x, t0.y + t2.y}, b2 = {t0.x - t2.x, t0.y - t2.y}, b1 = {t1.x + t3.y, t1.y - t3.x}, b3 = {t1.x - t3.y, t1.y + t3.x};
;   float2 w1 = twid(r), w2 = cmul(w1, w1), w3 = cmul(w2, w1);
;   o0 = b0; o1 = cmul(b1, w1); o2 = cmul(b2, w2); o3 = cmul(b3, w3);
; }
;   const int Q = 1 << lq; const float invM = 1.f / (float)(4 << lq);
;   for (int bb = tid; bb < NBT * (N / 4); bb += NTHR) { const int b = bb & (N / 4 - 1); float2* z = z0 + (bb / (N / 4)) * N; int j = b & (Q - 1), base = ((b >> lq) << (lq + 2)) + j; float2 o0, o1, o2, o3;
;     bfly_fwd(z[base], z[base + Q], z[base + 2 * Q], z[base + 3 * Q], (float)j * invM, o0, o1, o2, o3);
;     z[base] = o0; z[base + Q] = o1; z[base + 2 * Q] = o2; z[base + 3 * Q] = o3; }
;   __syncthreads();
; }
	v_pk_mul_f32 v[220:221], v[20:21], v[224:225] op_sel:[1,1] op_sel_hi:[1,0]
	v_pk_mul_f32 v[222:223], v[22:23], v[226:227] op_sel:[1,1] op_sel_hi:[1,0]
	v_pk_mul_f32 v[28:29], v[24:25], v[228:229] op_sel:[1,1] op_sel_hi:[1,0]
	v_pk_mul_f32 v[30:31], v[26:27], v[230:231] op_sel:[1,1] op_sel_hi:[1,0]
	v_pk_fma_f32 v[20:21], v[20:21], v[224:225], v[220:221] op_sel_hi:[0,1,1] neg_lo:[0,0,1]
	v_pk_fma_f32 v[22:23], v[22:23], v[226:227], v[222:223] op_sel_hi:[0,1,1] neg_lo:[0,0,1]
	v_pk_fma_f32 v[24:25], v[24:25], v[228:229], v[28:29] op_sel_hi:[0,1,1] neg_lo:[0,0,1]
	v_pk_fma_f32 v[26:27], v[26:27], v[230:231], v[30:31] op_sel_hi:[0,1,1] neg_lo:[0,0,1]
	v_pk_add_f32 v[28:29], v[20:21], v[24:25]
	v_pk_add_f32 v[30:31], v[20:21], v[24:25] neg_lo:[0,1] neg_hi:[0,1]
	v_pk_add_f32 v[32:33], v[22:23], v[26:27]
	v_pk_add_f32 v[218:219], v[22:23], v[26:27] neg_lo:[0,1] neg_hi:[0,1]
	v_pk_add_f32 v[20:21], v[28:29], v[32:33]
	v_pk_add_f32 v[24:25], v[28:29], v[32:33] neg_lo:[0,1] neg_hi:[0,1]
	v_pk_add_f32 v[22:23], v[30:31], v[218:219] op_sel:[0,1] op_sel_hi:[1,0] neg_lo:[0,1]
	v_pk_add_f32 v[26:27], v[30:31], v[218:219] op_sel:[0,1] op_sel_hi:[1,0] neg_hi:[0,1]
	v_pk_mul_f32 v[220:221], v[20:21], v[232:233] op_sel:[1,1] op_sel_hi:[1,0]
	v_pk_mul_f32 v[222:223], v[24:25], v[236:237] op_sel:[1,1] op_sel_hi:[1,0]
	v_pk_mul_f32 v[28:29], v[22:23], v[234:235] op_sel:[1,1] op_sel_hi:[1,0]
	v_pk_mul_f32 v[32:33], v[26:27], v[238:239] op_sel:[1,1] op_sel_hi:[1,0]
	v_pk_fma_f32 v[20:21], v[20:21], v[232:233], v[220:221] op_sel_hi:[0,1,1] neg_lo:[0,0,1]
	v_pk_fma_f32 v[24:25], v[24:25], v[236:237], v[222:223] op_sel_hi:[0,1,1] neg_lo:[0,0,1]
	v_pk_fma_f32 v[22:23], v[22:23], v[234:235], v[28:29] op_sel_hi:[0,1,1] neg_lo:[0,0,1]
	v_pk_fma_f32 v[26:27], v[26:27], v[238:239], v[32:33] op_sel_hi:[0,1,1] neg_lo:[0,0,1]
	s_nop 0
	ds_write_b64 v245, v[20:21] offset:16384
	ds_write_b64 v247, v[24:25] offset:16384
	ds_write_b64 v246, v[22:23] offset:16384
	ds_write_b64 v248, v[26:27] offset:16384
	ds_read_b64 v[20:21], v245 offset:32768
	ds_read_b64 v[22:23], v246 offset:32768
	ds_read_b64 v[24:25], v247 offset:32768
	ds_read_b64 v[26:27], v248 offset:32768
	s_waitcnt lgkmcnt(0)
	v_pk_mul_f32 v[220:221], v[20:21], v[224:225] op_sel:[1,1] op_sel_hi:[1,0]
	v_pk_mul_f32 v[222:223], v[22:23], v[226:227] op_sel:[1,1] op_sel_hi:[1,0]
	v_pk_mul_f32 v[28:29], v[24:25], v[228:229] op_sel:[1,1] op_sel_hi:[1,0]
	v_pk_mul_f32 v[30:31], v[26:27], v[230:231] op_sel:[1,1] op_sel_hi:[1,0]
	v_pk_fma_f32 v[20:21], v[20:21], v[224:225], v[220:221] op_sel_hi:[0,1,1] neg_lo:[0,0,1]
	v_pk_fma_f32 v[22:23], v[22:23], v[226:227], v[222:223] op_sel_hi:[0,1,1] neg_lo:[0,0,1]
	v_pk_fma_f32 v[24:25], v[24:25], v[228:229], v[28:29] op_sel_hi:[0,1,1] neg_lo:[0,0,1]
	v_pk_fma_f32 v[26:27], v[26:27], v[230:231], v[30:31] op_sel_hi:[0,1,1] neg_lo:[0,0,1]
	v_pk_add_f32 v[28:29], v[20:21], v[24:25]
	v_pk_add_f32 v[30:31], v[20:21], v[24:25] neg_lo:[0,1] neg_hi:[0,1]
	v_pk_add_f32 v[32:33], v[22:23], v[26:27]
	v_pk_add_f32 v[218:219], v[22:23], v[26:27] neg_lo:[0,1] neg_hi:[0,1]
	v_pk_add_f32 v[20:21], v[28:29], v[32:33]
	v_pk_add_f32 v[24:25], v[28:29], v[32:33] neg_lo:[0,1] neg_hi:[0,1]
	v_pk_add_f32 v[22:23], v[30:31], v[218:219] op_sel:[0,1] op_sel_hi:[1,0] neg_lo:[0,1]
	v_pk_add_f32 v[26:27], v[30:31], v[218:219] op_sel:[0,1] op_sel_hi:[1,0] neg_hi:[0,1]
	v_pk_mul_f32 v[220:221], v[20:21], v[232:233] op_sel:[1,1] op_sel_hi:[1,0]
	v_pk_mul_f32 v[222:223], v[24:25], v[236:237] op_sel:[1,1] op_sel_hi:[1,0]
	v_pk_mul_f32 v[28:29], v[22:23], v[234:235] op_sel:[1,1] op_sel_hi:[1,0]
	v_pk_mul_f32 v[32:33], v[26:27], v[238:239] op_sel:[1,1] op_sel_hi:[1,0]
	v_pk_fma_f32 v[20:21], v[20:21], v[232:233], v[220:221] op_sel_hi:[0,1,1] neg_lo:[0,0,1]
	v_pk_fma_f32 v[24:25], v[24:25], v[236:237], v[222:223] op_sel_hi:[0,1,1] neg_lo:[0,0,1]
	v_pk_fma_f32 v[22:23], v[22:23], v[234:235], v[28:29] op_sel_hi:[0,1,1] neg_lo:[0,0,1]
	v_pk_fma_f32 v[26:27], v[26:27], v[238:239], v[32:33] op_sel_hi:[0,1,1] neg_lo:[0,0,1]
	s_nop 0
	ds_write_b64 v245, v[20:21] offset:32768
	ds_write_b64 v247, v[24:25] offset:32768
	ds_write_b64 v246, v[22:23] offset:32768
	ds_write_b64 v248, v[26:27] offset:32768
	ds_read_b64 v[20:21], v245 offset:49152
	ds_read_b64 v[22:23], v246 offset:49152
	ds_read_b64 v[24:25], v247 offset:49152
	ds_read_b64 v[26:27], v248 offset:49152
	s_waitcnt lgkmcnt(0)
	v_pk_mul_f32 v[220:221], v[20:21], v[224:225] op_sel:[1,1] op_sel_hi:[1,0]
	v_pk_mul_f32 v[222:223], v[22:23], v[226:227] op_sel:[1,1] op_sel_hi:[1,0]
	v_pk_mul_f32 v[28:29], v[24:25], v[228:229] op_sel:[1,1] op_sel_hi:[1,0]
	v_pk_mul_f32 v[30:31], v[26:27], v[230:231] op_sel:[1,1] op_sel_hi:[1,0]
	v_pk_fma_f32 v[20:21], v[20:21], v[224:225], v[220:221] op_sel_hi:[0,1,1] neg_lo:[0,0,1]
	v_pk_fma_f32 v[22:23], v[22:23], v[226:227], v[222:223] op_sel_hi:[0,1,1] neg_lo:[0,0,1]
	v_pk_fma_f32 v[24:25], v[24:25], v[228:229], v[28:29] op_sel_hi:[0,1,1] neg_lo:[0,0,1]
	v_pk_fma_f32 v[26:27], v[26:27], v[230:231], v[30:31] op_sel_hi:[0,1,1] neg_lo:[0,0,1]
	v_pk_add_f32 v[28:29], v[20:21], v[24:25]
	v_pk_add_f32 v[30:31], v[20:21], v[24:25] neg_lo:[0,1] neg_hi:[0,1]
	v_pk_add_f32 v[32:33], v[22:23], v[26:27]
	v_pk_add_f32 v[218:219], v[22:23], v[26:27] neg_lo:[0,1] neg_hi:[0,1]
	v_pk_add_f32 v[20:21], v[28:29], v[32:33]
	v_pk_add_f32 v[24:25], v[28:29], v[32:33] neg_lo:[0,1] neg_hi:[0,1]
	v_pk_add_f32 v[22:23], v[30:31], v[218:219] op_sel:[0,1] op_sel_hi:[1,0] neg_lo:[0,1]
	v_pk_add_f32 v[26:27], v[30:31], v[218:219] op_sel:[0,1] op_sel_hi:[1,0] neg_hi:[0,1]
	v_pk_mul_f32 v[220:221], v[20:21], v[232:233] op_sel:[1,1] op_sel_hi:[1,0]
	v_pk_mul_f32 v[222:223], v[24:25], v[236:237] op_sel:[1,1] op_sel_hi:[1,0]
	v_pk_mul_f32 v[28:29], v[22:23], v[234:235] op_sel:[1,1] op_sel_hi:[1,0]
	v_pk_mul_f32 v[32:33], v[26:27], v[238:239] op_sel:[1,1] op_sel_hi:[1,0]
	v_pk_fma_f32 v[20:21], v[20:21], v[232:233], v[220:221] op_sel_hi:[0,1,1] neg_lo:[0,0,1]
	v_pk_fma_f32 v[24:25], v[24:25], v[236:237], v[222:223] op_sel_hi:[0,1,1] neg_lo:[0,0,1]
	v_pk_fma_f32 v[22:23], v[22:23], v[234:235], v[28:29] op_sel_hi:[0,1,1] neg_lo:[0,0,1]
	v_pk_fma_f32 v[26:27], v[26:27], v[238:239], v[32:33] op_sel_hi:[0,1,1] neg_lo:[0,0,1]
	s_nop 0
	ds_write_b64 v245, v[20:21] offset:49152
	ds_write_b64 v247, v[24:25] offset:49152
	ds_write_b64 v246, v[22:23] offset:49152
	ds_write_b64 v248, v[26:27] offset:49152
	v_add_u32_e32 v17, 0x4000, v17
	v_add_u32_e32 v19, 0x1000, v18
	v_mov_b32_e32 v18, v19
	s_mov_b64 s[14:15], exec
